# speedup vs baseline: 1.0141x; 1.0092x over previous
; #define STAGE(Pp, BASE, br, kt) do { const u16* _g = (BASE) + ((long)(br) * K + (long)(kt) * BK); \
;     __builtin_amdgcn_global_load_lds((const unsigned*)(_g + voff0), (unsigned*)((char*)(Pp) + tb16), 16, 0, 0); \
;     __builtin_amdgcn_global_load_lds((const unsigned*)(_g + voff1), (unsigned*)((char*)(Pp) + tb16 + 8192), 16, 0, 0); } while (0)
; #define LDA(dst, b, h) _Pragma("unroll") for (int m = 0; m < 4; ++m) _Pragma("unroll") for (int k = 0; k < 2; ++k) \
;     dst[m][k] = *reinterpret_cast<const bf16x8*>((const char*)shm + aB + (((b) * 2 + (h)) * 16384 + (m * 2 + k) * 1024))
; #define LDB(dst, b, h) _Pragma("unroll") for (int n = 0; n < 2; ++n) _Pragma("unroll") for (int k = 0; k < 2; ++k) \
;     dst[n][k] = *reinterpret_cast<const bf16x8*>((const char*)shm + bB + (((b) * 2 + (h)) * 16384 + (n * 2 + k) * 1024))
; #define WAIT_V(n) asm volatile("s_waitcnt vmcnt(" #n ")" ::: "memory")
; #define WAIT_L(n) asm volatile("s_waitcnt lgkmcnt(" #n ")" ::: "memory")
; #define BAR __builtin_amdgcn_s_barrier()
; #define SCHED __builtin_amdgcn_sched_barrier(0)
; template <int MODE> ...
;     ...
;     f32x4 acc[2][2][4][2] = {};
;     bf16x8 At[4][2], B0[2][2], B1[2][2];
;     ...
;     STAGE(SB(0, 0), Bt, bcol, 0); STAGE(SA(0, 0), A, brow, 0); STAGE(SB(0, 1), Bt, bcol + HALF, 0); STAGE(SA(0, 1), A, brow + HALF, 0);
;     STAGE(SB(1, 0), Bt, bcol, 1); STAGE(SA(1, 0), A, brow, 1); STAGE(SB(1, 1), Bt, bcol + HALF, 1);
;     WAIT_V(6);
;     if (wr == 1) BAR;
;     BAR;
;     for (int t = 0; t < nt - 2; t += 2) {
;       LDB(B0, 0, 0); LDB(B1, 0, 1); LDA(At, 0, 0); STAGE(SA(1, 1), A, brow + HALF, t + 1);
;       WAIT_L(0); BAR; MMA2(0, 0, 0, 1); BAR; SCHED;
.LBB0_153:
	s_or_b64 exec, exec, s[78:79]
	v_mov_b32_e32 v0, 0
	v_lshl_add_u64 v[138:139], v[130:131], 0, s[74:75]
	v_lshl_add_u64 v[140:141], v[132:133], 0, s[74:75]
	v_lshl_add_u64 v[142:143], v[130:131], 0, s[76:77]
	v_lshl_add_u64 v[144:145], v[132:133], 0, s[76:77]
	s_mov_b32 s69, -2
	s_mov_b64 s[74:75], s[56:57]
	v_mov_b32_e32 v1, v0
	v_mov_b32_e32 v2, v0
	v_mov_b32_e32 v3, v0
	v_mov_b32_e32 v4, v0
	v_mov_b32_e32 v5, v0
	v_mov_b32_e32 v6, v0
	v_mov_b32_e32 v7, v0
	v_mov_b32_e32 v8, v0
	v_mov_b32_e32 v9, v0
	v_mov_b32_e32 v10, v0
	v_mov_b32_e32 v11, v0
	v_mov_b32_e32 v12, v0
	v_mov_b32_e32 v13, v0
	v_mov_b32_e32 v14, v0
	v_mov_b32_e32 v15, v0
	v_mov_b32_e32 v16, v0
	v_mov_b32_e32 v17, v0
	v_mov_b32_e32 v18, v0
	v_mov_b32_e32 v19, v0
	v_mov_b32_e32 v20, v0
	v_mov_b32_e32 v21, v0
	v_mov_b32_e32 v22, v0
	v_mov_b32_e32 v23, v0
	v_mov_b32_e32 v24, v0
	v_mov_b32_e32 v25, v0
	v_mov_b32_e32 v26, v0
	v_mov_b32_e32 v27, v0
	v_mov_b32_e32 v28, v0
	v_mov_b32_e32 v29, v0
	v_mov_b32_e32 v30, v0
	v_mov_b32_e32 v31, v0
	v_mov_b32_e32 v32, v0
	v_mov_b32_e32 v33, v0
	v_mov_b32_e32 v34, v0
	v_mov_b32_e32 v35, v0
	v_mov_b32_e32 v36, v0
	v_mov_b32_e32 v37, v0
	v_mov_b32_e32 v38, v0
	v_mov_b32_e32 v39, v0
	v_mov_b32_e32 v40, v0
	v_mov_b32_e32 v41, v0
	v_mov_b32_e32 v42, v0
	v_mov_b32_e32 v43, v0
	v_mov_b32_e32 v44, v0
	v_mov_b32_e32 v45, v0
	v_mov_b32_e32 v46, v0
	v_mov_b32_e32 v47, v0
	v_mov_b32_e32 v48, v0
	v_mov_b32_e32 v49, v0
	v_mov_b32_e32 v50, v0
	v_mov_b32_e32 v51, v0
	v_mov_b32_e32 v52, v0
	v_mov_b32_e32 v53, v0
	v_mov_b32_e32 v54, v0
	v_mov_b32_e32 v55, v0
	v_mov_b32_e32 v56, v0
	v_mov_b32_e32 v57, v0
	v_mov_b32_e32 v58, v0
	v_mov_b32_e32 v59, v0
	v_mov_b32_e32 v60, v0
	v_mov_b32_e32 v61, v0
	v_mov_b32_e32 v62, v0
	v_mov_b32_e32 v63, v0
	v_mov_b32_e32 v64, v0
	v_mov_b32_e32 v65, v0
	v_mov_b32_e32 v66, v0
	v_mov_b32_e32 v67, v0
	v_mov_b32_e32 v68, v0
	v_mov_b32_e32 v69, v0
	v_mov_b32_e32 v70, v0
	v_mov_b32_e32 v71, v0
	v_mov_b32_e32 v72, v0
	v_mov_b32_e32 v73, v0
	v_mov_b32_e32 v74, v0
	v_mov_b32_e32 v75, v0
	v_mov_b32_e32 v76, v0
	v_mov_b32_e32 v77, v0
	v_mov_b32_e32 v78, v0
	v_mov_b32_e32 v79, v0
	v_mov_b32_e32 v80, v0
	v_mov_b32_e32 v81, v0
	v_mov_b32_e32 v82, v0
	v_mov_b32_e32 v83, v0
	v_mov_b32_e32 v84, v0
	v_mov_b32_e32 v85, v0
	v_mov_b32_e32 v86, v0
	v_mov_b32_e32 v87, v0
	v_mov_b32_e32 v88, v0
	v_mov_b32_e32 v89, v0
	v_mov_b32_e32 v90, v0
	v_mov_b32_e32 v91, v0
	v_mov_b32_e32 v92, v0
	v_mov_b32_e32 v93, v0
	v_mov_b32_e32 v94, v0
	v_mov_b32_e32 v95, v0
	v_mov_b32_e32 v96, v0
	v_mov_b32_e32 v97, v0
	v_mov_b32_e32 v98, v0
	v_mov_b32_e32 v99, v0
	v_mov_b32_e32 v100, v0
	v_mov_b32_e32 v101, v0
	v_mov_b32_e32 v102, v0
	v_mov_b32_e32 v103, v0
	v_mov_b32_e32 v104, v0
	v_mov_b32_e32 v105, v0
	v_mov_b32_e32 v106, v0
	v_mov_b32_e32 v107, v0
	v_mov_b32_e32 v108, v0
	v_mov_b32_e32 v109, v0
	v_mov_b32_e32 v110, v0
	v_mov_b32_e32 v111, v0
	v_mov_b32_e32 v112, v0
	v_mov_b32_e32 v113, v0
	v_mov_b32_e32 v114, v0
	v_mov_b32_e32 v115, v0
	v_mov_b32_e32 v116, v0
	v_mov_b32_e32 v117, v0
	v_mov_b32_e32 v118, v0
	v_mov_b32_e32 v119, v0
	v_mov_b32_e32 v120, v0
	v_mov_b32_e32 v121, v0
	v_mov_b32_e32 v122, v0
	v_mov_b32_e32 v123, v0
	v_mov_b32_e32 v124, v0
	v_mov_b32_e32 v125, v0
	v_mov_b32_e32 v126, v0
	v_mov_b32_e32 v127, v0
	v_readfirstlane_b32 s32, v152
	s_barrier
.LBB0_154:
	s_add_u32 s71, s32, 0xc000
	s_mov_b32 m0, s71
	ds_read_b128 v[170:173], v149
	ds_read_b128 v[174:177], v149 offset:1024
	ds_read_b128 v[178:181], v149 offset:2048
	ds_read_b128 v[182:185], v149 offset:3072
	ds_read_b128 v[186:189], v149 offset:16384
	ds_read_b128 v[190:193], v149 offset:17408
	ds_read_b128 v[194:197], v149 offset:18432
	ds_read_b128 v[198:201], v149 offset:19456
	ds_read_b128 v[202:205], v151
	ds_read_b128 v[206:209], v151 offset:1024
	ds_read_b128 v[210:213], v151 offset:2048
	ds_read_b128 v[214:217], v151 offset:3072
	ds_read_b128 v[218:221], v151 offset:4096
	ds_read_b128 v[222:225], v151 offset:5120
	ds_read_b128 v[226:229], v151 offset:6144
	ds_read_b128 v[230:233], v151 offset:7168
	s_add_u32 s88, s74, s40
	s_addc_u32 s89, s75, s41
	global_load_lds_dwordx4 v142, s[88:89]
	s_add_u32 s71, s32, 0xe000
	s_mov_b32 m0, s71
	s_nop 0
	s_add_u32 s90, s74, s40
	s_addc_u32 s91, s75, s41
	global_load_lds_dwordx4 v144, s[90:91]
	s_waitcnt lgkmcnt(0)
	s_barrier
	s_setprio 1
	s_waitcnt lgkmcnt(0)
	v_mfma_f32_16x16x32_bf16 v[124:127], v[202:205], v[170:173], v[124:127]
	v_mfma_f32_16x16x32_bf16 v[120:123], v[202:205], v[178:181], v[120:123]
	v_mfma_f32_16x16x32_bf16 v[116:119], v[210:213], v[170:173], v[116:119]
	v_mfma_f32_16x16x32_bf16 v[112:115], v[210:213], v[178:181], v[112:115]
	v_mfma_f32_16x16x32_bf16 v[108:111], v[218:221], v[170:173], v[108:111]
	v_mfma_f32_16x16x32_bf16 v[104:107], v[218:221], v[178:181], v[104:107]
	v_mfma_f32_16x16x32_bf16 v[100:103], v[226:229], v[170:173], v[100:103]
	v_mfma_f32_16x16x32_bf16 v[96:99], v[226:229], v[178:181], v[96:99]
	v_mfma_f32_16x16x32_bf16 v[92:95], v[202:205], v[186:189], v[92:95]
	v_mfma_f32_16x16x32_bf16 v[88:91], v[202:205], v[194:197], v[88:91]
	v_mfma_f32_16x16x32_bf16 v[84:87], v[210:213], v[186:189], v[84:87]
	v_mfma_f32_16x16x32_bf16 v[80:83], v[210:213], v[194:197], v[80:83]
	v_mfma_f32_16x16x32_bf16 v[76:79], v[218:221], v[186:189], v[76:79]
	v_mfma_f32_16x16x32_bf16 v[72:75], v[218:221], v[194:197], v[72:75]
	v_mfma_f32_16x16x32_bf16 v[68:71], v[226:229], v[186:189], v[68:71]
	v_mfma_f32_16x16x32_bf16 v[64:67], v[226:229], v[194:197], v[64:67]
	v_mfma_f32_16x16x32_bf16 v[124:127], v[206:209], v[174:177], v[124:127]
	v_mfma_f32_16x16x32_bf16 v[120:123], v[206:209], v[182:185], v[120:123]
	v_mfma_f32_16x16x32_bf16 v[116:119], v[214:217], v[174:177], v[116:119]
	v_mfma_f32_16x16x32_bf16 v[112:115], v[214:217], v[182:185], v[112:115]
	v_mfma_f32_16x16x32_bf16 v[108:111], v[222:225], v[174:177], v[108:111]
	v_mfma_f32_16x16x32_bf16 v[104:107], v[222:225], v[182:185], v[104:107]
	v_mfma_f32_16x16x32_bf16 v[100:103], v[230:233], v[174:177], v[100:103]
	v_mfma_f32_16x16x32_bf16 v[96:99], v[230:233], v[182:185], v[96:99]
	v_mfma_f32_16x16x32_bf16 v[92:95], v[206:209], v[190:193], v[92:95]
	v_mfma_f32_16x16x32_bf16 v[88:91], v[206:209], v[198:201], v[88:91]
	v_mfma_f32_16x16x32_bf16 v[84:87], v[214:217], v[190:193], v[84:87]
	v_mfma_f32_16x16x32_bf16 v[80:83], v[214:217], v[198:201], v[80:83]
	v_mfma_f32_16x16x32_bf16 v[76:79], v[222:225], v[190:193], v[76:79]
	v_mfma_f32_16x16x32_bf16 v[72:75], v[222:225], v[198:201], v[72:75]
	v_mfma_f32_16x16x32_bf16 v[68:71], v[230:233], v[190:193], v[68:71]
	v_mfma_f32_16x16x32_bf16 v[64:67], v[230:233], v[198:201], v[64:67]
	s_setprio 0
	s_barrier
; #define STAGE(Pp, BASE, br, kt) do { const u16* _g = (BASE) + ((long)(br) * K + (long)(kt) * BK); \
;     __builtin_amdgcn_global_load_lds((const unsigned*)(_g + voff0), (unsigned*)((char*)(Pp) + tb16), 16, 0, 0); \
;     __builtin_amdgcn_global_load_lds((const unsigned*)(_g + voff1), (unsigned*)((char*)(Pp) + tb16 + 8192), 16, 0, 0); } while (0)
; #define LDA(dst, b, h) _Pragma("unroll") for (int m = 0; m < 4; ++m) _Pragma("unroll") for (int k = 0; k < 2; ++k) \
;     dst[m][k] = *reinterpret_cast<const bf16x8*>((const char*)shm + aB + (((b) * 2 + (h)) * 16384 + (m * 2 + k) * 1024))
; #define LDB(dst, b, h) _Pragma("unroll") for (int n = 0; n < 2; ++n) _Pragma("unroll") for (int k = 0; k < 2; ++k) \
;     dst[n][k] = *reinterpret_cast<const bf16x8*>((const char*)shm + bB + (((b) * 2 + (h)) * 16384 + (n * 2 + k) * 1024))
; #define WAIT_V(n) asm volatile("s_waitcnt vmcnt(" #n ")" ::: "memory")
; #define WAIT_L(n) asm volatile("s_waitcnt lgkmcnt(" #n ")" ::: "memory")
; #define BAR __builtin_amdgcn_s_barrier()
; #define SCHED __builtin_amdgcn_sched_barrier(0)
; template <int MODE> ...
;     ...
;       LDA(At, 0, 1); STAGE(SB(0, 0), Bt, bcol, t + 2); STAGE(SB(0, 1), Bt, bcol + HALF, t + 2); STAGE(SA(0, 0), A, brow, t + 2);
;       WAIT_V(6); WAIT_L(0); BAR; MMA2(1, 0, 1, 1); BAR; SCHED;
;       LDB(B0, 1, 0); LDB(B1, 1, 1); LDA(At, 1, 0); STAGE(SA(0, 1), A, brow + HALF, t + 2);
	s_add_u32 s71, s32, 0x10000
	s_mov_b32 m0, s71
	ds_read_b128 v[202:205], v151 offset:16384
	ds_read_b128 v[206:209], v151 offset:17408
	ds_read_b128 v[210:213], v151 offset:18432
	ds_read_b128 v[214:217], v151 offset:19456
	ds_read_b128 v[218:221], v151 offset:20480
	ds_read_b128 v[222:225], v151 offset:21504
	ds_read_b128 v[226:229], v151 offset:22528
	ds_read_b128 v[230:233], v151 offset:23552
	s_add_u32 s92, s74, s42
	s_addc_u32 s93, s75, s43
	global_load_lds_dwordx4 v138, s[92:93]
	s_add_u32 s71, s32, 0x12000
	s_mov_b32 m0, s71
	s_add_u32 s71, s32, 0x14000
	s_add_u32 s96, s74, s42
	s_addc_u32 s97, s75, s43
	global_load_lds_dwordx4 v140, s[96:97]
	s_mov_b32 m0, s71
	s_add_u32 s71, s32, 0x16000
	s_add_u32 s88, s74, s44
	s_addc_u32 s89, s75, s45
	global_load_lds_dwordx4 v138, s[88:89]
	s_mov_b32 m0, s71
	s_mov_b32 s71, s32
	s_add_u32 s90, s74, s44
	s_addc_u32 s91, s75, s45
	global_load_lds_dwordx4 v140, s[90:91]
	s_mov_b32 m0, s71
	s_add_u32 s71, s32, 0x2000
	s_add_u32 s92, s74, s48
	s_addc_u32 s93, s75, s49
	global_load_lds_dwordx4 v142, s[92:93]
	s_mov_b32 m0, s71
	s_nop 0
	s_add_u32 s96, s74, s48
	s_addc_u32 s97, s75, s49
	global_load_lds_dwordx4 v144, s[96:97]
	s_waitcnt vmcnt(6)
	s_waitcnt lgkmcnt(0)
	s_barrier
	s_setprio 1
	s_waitcnt lgkmcnt(0)
	v_mfma_f32_16x16x32_bf16 v[60:63], v[202:205], v[170:173], v[60:63]
	v_mfma_f32_16x16x32_bf16 v[56:59], v[202:205], v[178:181], v[56:59]
	v_mfma_f32_16x16x32_bf16 v[52:55], v[210:213], v[170:173], v[52:55]
	v_mfma_f32_16x16x32_bf16 v[48:51], v[210:213], v[178:181], v[48:51]
	v_mfma_f32_16x16x32_bf16 v[44:47], v[218:221], v[170:173], v[44:47]
	v_mfma_f32_16x16x32_bf16 v[40:43], v[218:221], v[178:181], v[40:43]
	v_mfma_f32_16x16x32_bf16 v[36:39], v[226:229], v[170:173], v[36:39]
	v_mfma_f32_16x16x32_bf16 v[32:35], v[226:229], v[178:181], v[32:35]
	v_mfma_f32_16x16x32_bf16 v[28:31], v[202:205], v[186:189], v[28:31]
	v_mfma_f32_16x16x32_bf16 v[24:27], v[202:205], v[194:197], v[24:27]
	v_mfma_f32_16x16x32_bf16 v[20:23], v[210:213], v[186:189], v[20:23]
	v_mfma_f32_16x16x32_bf16 v[16:19], v[210:213], v[194:197], v[16:19]
	v_mfma_f32_16x16x32_bf16 v[12:15], v[218:221], v[186:189], v[12:15]
	v_mfma_f32_16x16x32_bf16 v[8:11], v[218:221], v[194:197], v[8:11]
	v_mfma_f32_16x16x32_bf16 v[4:7], v[226:229], v[186:189], v[4:7]
	v_mfma_f32_16x16x32_bf16 v[0:3], v[226:229], v[194:197], v[0:3]
	v_mfma_f32_16x16x32_bf16 v[60:63], v[206:209], v[174:177], v[60:63]
	v_mfma_f32_16x16x32_bf16 v[56:59], v[206:209], v[182:185], v[56:59]
	v_mfma_f32_16x16x32_bf16 v[52:55], v[214:217], v[174:177], v[52:55]
	v_mfma_f32_16x16x32_bf16 v[48:51], v[214:217], v[182:185], v[48:51]
	v_mfma_f32_16x16x32_bf16 v[44:47], v[222:225], v[174:177], v[44:47]
	v_mfma_f32_16x16x32_bf16 v[40:43], v[222:225], v[182:185], v[40:43]
	v_mfma_f32_16x16x32_bf16 v[36:39], v[230:233], v[174:177], v[36:39]
	v_mfma_f32_16x16x32_bf16 v[32:35], v[230:233], v[182:185], v[32:35]
	v_mfma_f32_16x16x32_bf16 v[28:31], v[206:209], v[190:193], v[28:31]
	v_mfma_f32_16x16x32_bf16 v[24:27], v[206:209], v[198:201], v[24:27]
	v_mfma_f32_16x16x32_bf16 v[20:23], v[214:217], v[190:193], v[20:23]
	v_mfma_f32_16x16x32_bf16 v[16:19], v[214:217], v[198:201], v[16:19]
	v_mfma_f32_16x16x32_bf16 v[12:15], v[222:225], v[190:193], v[12:15]
	v_mfma_f32_16x16x32_bf16 v[8:11], v[222:225], v[198:201], v[8:11]
	v_mfma_f32_16x16x32_bf16 v[4:7], v[230:233], v[190:193], v[4:7]
	v_mfma_f32_16x16x32_bf16 v[0:3], v[230:233], v[198:201], v[0:3]
	s_setprio 0
	s_barrier
	s_add_u32 s71, s32, 0x4000
	s_mov_b32 m0, s71
	s_add_u32 s71, s32, 0x6000
	ds_read_b128 v[170:173], v149 offset:32768
	ds_read_b128 v[174:177], v149 offset:33792
	ds_read_b128 v[178:181], v149 offset:34816
	ds_read_b128 v[182:185], v149 offset:35840
	ds_read_b128 v[186:189], v149 offset:49152
	ds_read_b128 v[190:193], v149 offset:50176
	ds_read_b128 v[194:197], v149 offset:51200
	ds_read_b128 v[198:201], v149 offset:52224
	ds_read_b128 v[202:205], v151 offset:32768
	ds_read_b128 v[206:209], v151 offset:33792
	ds_read_b128 v[210:213], v151 offset:34816
	ds_read_b128 v[214:217], v151 offset:35840
	ds_read_b128 v[218:221], v151 offset:36864
	ds_read_b128 v[222:225], v151 offset:37888
	ds_read_b128 v[226:229], v151 offset:38912
	ds_read_b128 v[230:233], v151 offset:39936
	s_add_u32 s88, s74, s50
	s_addc_u32 s89, s75, s51
	global_load_lds_dwordx4 v142, s[88:89]
	s_mov_b32 m0, s71
	s_nop 0
	s_add_u32 s90, s74, s50
	s_addc_u32 s91, s75, s51
	global_load_lds_dwordx4 v144, s[90:91]
	s_waitcnt lgkmcnt(0)
	s_barrier
; #define STAGE(Pp, BASE, br, kt) do { const u16* _g = (BASE) + ((long)(br) * K + (long)(kt) * BK); \
;     __builtin_amdgcn_global_load_lds((const unsigned*)(_g + voff0), (unsigned*)((char*)(Pp) + tb16), 16, 0, 0); \
;     __builtin_amdgcn_global_load_lds((const unsigned*)(_g + voff1), (unsigned*)((char*)(Pp) + tb16 + 8192), 16, 0, 0); } while (0)
; #define LDA(dst, b, h) _Pragma("unroll") for (int m = 0; m < 4; ++m) _Pragma("unroll") for (int k = 0; k < 2; ++k) \
;     dst[m][k] = *reinterpret_cast<const bf16x8*>((const char*)shm + aB + (((b) * 2 + (h)) * 16384 + (m * 2 + k) * 1024))
; #define WAIT_V(n) asm volatile("s_waitcnt vmcnt(" #n ")" ::: "memory")
; #define WAIT_L(n) asm volatile("s_waitcnt lgkmcnt(" #n ")" ::: "memory")
; #define BAR __builtin_amdgcn_s_barrier()
; #define SCHED __builtin_amdgcn_sched_barrier(0)
; template <int MODE> ...
;     ...
;       WAIT_L(0); BAR; MMA2(0, 0, 0, 1); BAR; SCHED;
;       LDA(At, 1, 1); STAGE(SB(1, 0), Bt, bcol, t + 3); STAGE(SB(1, 1), Bt, bcol + HALF, t + 3); STAGE(SA(1, 0), A, brow, t + 3);
;       WAIT_V(6); WAIT_L(0); BAR; MMA2(1, 0, 1, 1); BAR; SCHED;
	s_setprio 1
	s_waitcnt lgkmcnt(0)
	v_mfma_f32_16x16x32_bf16 v[124:127], v[202:205], v[170:173], v[124:127]
	v_mfma_f32_16x16x32_bf16 v[120:123], v[202:205], v[178:181], v[120:123]
	v_mfma_f32_16x16x32_bf16 v[116:119], v[210:213], v[170:173], v[116:119]
	v_mfma_f32_16x16x32_bf16 v[112:115], v[210:213], v[178:181], v[112:115]
	v_mfma_f32_16x16x32_bf16 v[108:111], v[218:221], v[170:173], v[108:111]
	v_mfma_f32_16x16x32_bf16 v[104:107], v[218:221], v[178:181], v[104:107]
	v_mfma_f32_16x16x32_bf16 v[100:103], v[226:229], v[170:173], v[100:103]
	v_mfma_f32_16x16x32_bf16 v[96:99], v[226:229], v[178:181], v[96:99]
	v_mfma_f32_16x16x32_bf16 v[92:95], v[202:205], v[186:189], v[92:95]
	v_mfma_f32_16x16x32_bf16 v[88:91], v[202:205], v[194:197], v[88:91]
	v_mfma_f32_16x16x32_bf16 v[84:87], v[210:213], v[186:189], v[84:87]
	v_mfma_f32_16x16x32_bf16 v[80:83], v[210:213], v[194:197], v[80:83]
	v_mfma_f32_16x16x32_bf16 v[76:79], v[218:221], v[186:189], v[76:79]
	v_mfma_f32_16x16x32_bf16 v[72:75], v[218:221], v[194:197], v[72:75]
	v_mfma_f32_16x16x32_bf16 v[68:71], v[226:229], v[186:189], v[68:71]
	v_mfma_f32_16x16x32_bf16 v[64:67], v[226:229], v[194:197], v[64:67]
	v_mfma_f32_16x16x32_bf16 v[124:127], v[206:209], v[174:177], v[124:127]
	v_mfma_f32_16x16x32_bf16 v[120:123], v[206:209], v[182:185], v[120:123]
	v_mfma_f32_16x16x32_bf16 v[116:119], v[214:217], v[174:177], v[116:119]
	v_mfma_f32_16x16x32_bf16 v[112:115], v[214:217], v[182:185], v[112:115]
	v_mfma_f32_16x16x32_bf16 v[108:111], v[222:225], v[174:177], v[108:111]
	v_mfma_f32_16x16x32_bf16 v[104:107], v[222:225], v[182:185], v[104:107]
	v_mfma_f32_16x16x32_bf16 v[100:103], v[230:233], v[174:177], v[100:103]
	v_mfma_f32_16x16x32_bf16 v[96:99], v[230:233], v[182:185], v[96:99]
	v_mfma_f32_16x16x32_bf16 v[92:95], v[206:209], v[190:193], v[92:95]
	v_mfma_f32_16x16x32_bf16 v[88:91], v[206:209], v[198:201], v[88:91]
	v_mfma_f32_16x16x32_bf16 v[84:87], v[214:217], v[190:193], v[84:87]
	v_mfma_f32_16x16x32_bf16 v[80:83], v[214:217], v[198:201], v[80:83]
	v_mfma_f32_16x16x32_bf16 v[76:79], v[222:225], v[190:193], v[76:79]
	v_mfma_f32_16x16x32_bf16 v[72:75], v[222:225], v[198:201], v[72:75]
	v_mfma_f32_16x16x32_bf16 v[68:71], v[230:233], v[190:193], v[68:71]
	v_mfma_f32_16x16x32_bf16 v[64:67], v[230:233], v[198:201], v[64:67]
	s_setprio 0
	s_barrier
	s_add_u32 s71, s32, 0x18000
	s_mov_b32 m0, s71
	s_add_u32 s71, s32, 0x1a000
	ds_read_b128 v[202:205], v151 offset:49152
	ds_read_b128 v[206:209], v151 offset:50176
	ds_read_b128 v[210:213], v151 offset:51200
	ds_read_b128 v[214:217], v151 offset:52224
	ds_read_b128 v[218:221], v151 offset:53248
	ds_read_b128 v[222:225], v151 offset:54272
	ds_read_b128 v[226:229], v151 offset:55296
	ds_read_b128 v[230:233], v151 offset:56320
	s_add_u32 s92, s74, s60
	s_addc_u32 s93, s75, s61
	global_load_lds_dwordx4 v138, s[92:93]
	s_mov_b32 m0, s71
	s_add_u32 s71, s32, 0x1c000
	s_add_u32 s96, s74, s60
	s_addc_u32 s97, s75, s61
	global_load_lds_dwordx4 v140, s[96:97]
	s_mov_b32 m0, s71
	s_add_u32 s71, s32, 0x1e000
	s_add_u32 s88, s74, s62
	s_addc_u32 s89, s75, s63
	global_load_lds_dwordx4 v138, s[88:89]
	s_mov_b32 m0, s71
	s_add_u32 s71, s32, 0x8000
	s_add_u32 s90, s74, s62
	s_addc_u32 s91, s75, s63
	global_load_lds_dwordx4 v140, s[90:91]
	s_mov_b32 m0, s71
	s_add_u32 s71, s32, 0xa000
	s_add_u32 s92, s74, s64
	s_addc_u32 s93, s75, s65
	global_load_lds_dwordx4 v142, s[92:93]
	s_mov_b32 m0, s71
	s_nop 0
	s_add_u32 s96, s74, s64
	s_addc_u32 s97, s75, s65
	global_load_lds_dwordx4 v144, s[96:97]
	s_waitcnt vmcnt(6)
	s_waitcnt lgkmcnt(0)
	s_barrier
	s_setprio 1
	s_waitcnt lgkmcnt(0)
	v_mfma_f32_16x16x32_bf16 v[60:63], v[202:205], v[170:173], v[60:63]
	v_mfma_f32_16x16x32_bf16 v[56:59], v[202:205], v[178:181], v[56:59]
	v_mfma_f32_16x16x32_bf16 v[52:55], v[210:213], v[170:173], v[52:55]
	v_mfma_f32_16x16x32_bf16 v[48:51], v[210:213], v[178:181], v[48:51]
	v_mfma_f32_16x16x32_bf16 v[44:47], v[218:221], v[170:173], v[44:47]
	v_mfma_f32_16x16x32_bf16 v[40:43], v[218:221], v[178:181], v[40:43]
	v_mfma_f32_16x16x32_bf16 v[36:39], v[226:229], v[170:173], v[36:39]
	v_mfma_f32_16x16x32_bf16 v[32:35], v[226:229], v[178:181], v[32:35]
	v_mfma_f32_16x16x32_bf16 v[28:31], v[202:205], v[186:189], v[28:31]
	v_mfma_f32_16x16x32_bf16 v[24:27], v[202:205], v[194:197], v[24:27]
	v_mfma_f32_16x16x32_bf16 v[20:23], v[210:213], v[186:189], v[20:23]
	v_mfma_f32_16x16x32_bf16 v[16:19], v[210:213], v[194:197], v[16:19]
	v_mfma_f32_16x16x32_bf16 v[12:15], v[218:221], v[186:189], v[12:15]
	v_mfma_f32_16x16x32_bf16 v[8:11], v[218:221], v[194:197], v[8:11]
	v_mfma_f32_16x16x32_bf16 v[4:7], v[226:229], v[186:189], v[4:7]
	v_mfma_f32_16x16x32_bf16 v[0:3], v[226:229], v[194:197], v[0:3]
	v_mfma_f32_16x16x32_bf16 v[60:63], v[206:209], v[174:177], v[60:63]
	v_mfma_f32_16x16x32_bf16 v[56:59], v[206:209], v[182:185], v[56:59]
	v_mfma_f32_16x16x32_bf16 v[52:55], v[214:217], v[174:177], v[52:55]
	v_mfma_f32_16x16x32_bf16 v[48:51], v[214:217], v[182:185], v[48:51]
	v_mfma_f32_16x16x32_bf16 v[44:47], v[222:225], v[174:177], v[44:47]
	v_mfma_f32_16x16x32_bf16 v[40:43], v[222:225], v[182:185], v[40:43]
	v_mfma_f32_16x16x32_bf16 v[36:39], v[230:233], v[174:177], v[36:39]
	v_mfma_f32_16x16x32_bf16 v[32:35], v[230:233], v[182:185], v[32:35]
	v_mfma_f32_16x16x32_bf16 v[28:31], v[206:209], v[190:193], v[28:31]
	v_mfma_f32_16x16x32_bf16 v[24:27], v[206:209], v[198:201], v[24:27]
	v_mfma_f32_16x16x32_bf16 v[20:23], v[214:217], v[190:193], v[20:23]
	v_mfma_f32_16x16x32_bf16 v[16:19], v[214:217], v[198:201], v[16:19]
	v_mfma_f32_16x16x32_bf16 v[12:15], v[222:225], v[190:193], v[12:15]
	v_mfma_f32_16x16x32_bf16 v[8:11], v[222:225], v[198:201], v[8:11]
	v_mfma_f32_16x16x32_bf16 v[4:7], v[230:233], v[190:193], v[4:7]
	v_mfma_f32_16x16x32_bf16 v[0:3], v[230:233], v[198:201], v[0:3]
	s_setprio 0
	s_barrier
; #define STAGE(Pp, BASE, br, kt) do { const u16* _g = (BASE) + ((long)(br) * K + (long)(kt) * BK); \
;     __builtin_amdgcn_global_load_lds((const unsigned*)(_g + voff0), (unsigned*)((char*)(Pp) + tb16), 16, 0, 0); \
;     __builtin_amdgcn_global_load_lds((const unsigned*)(_g + voff1), (unsigned*)((char*)(Pp) + tb16 + 8192), 16, 0, 0); } while (0)
; #define LDA(dst, b, h) _Pragma("unroll") for (int m = 0; m < 4; ++m) _Pragma("unroll") for (int k = 0; k < 2; ++k) \
;     dst[m][k] = *reinterpret_cast<const bf16x8*>((const char*)shm + aB + (((b) * 2 + (h)) * 16384 + (m * 2 + k) * 1024))
; #define LDB(dst, b, h) _Pragma("unroll") for (int n = 0; n < 2; ++n) _Pragma("unroll") for (int k = 0; k < 2; ++k) \
;     dst[n][k] = *reinterpret_cast<const bf16x8*>((const char*)shm + bB + (((b) * 2 + (h)) * 16384 + (n * 2 + k) * 1024))
; #define WAIT_V(n) asm volatile("s_waitcnt vmcnt(" #n ")" ::: "memory")
; #define WAIT_L(n) asm volatile("s_waitcnt lgkmcnt(" #n ")" ::: "memory")
; #define BAR __builtin_amdgcn_s_barrier()
; #define SCHED __builtin_amdgcn_sched_barrier(0)
; template <int MODE> ...
;     ...
;     }
;     {
;       LDB(B0, 0, 0); LDB(B1, 0, 1); LDA(At, 0, 0); STAGE(SA(1, 1), A, brow + HALF, nt - 1);
;       WAIT_L(0); BAR; MMA2(0, 0, 0, 1); BAR; SCHED;
;       LDA(At, 0, 1); WAIT_V(0); WAIT_L(0); BAR; MMA2(1, 0, 1, 1); BAR; SCHED;
	s_add_i32 s69, s69, 2
	s_add_u32 s74, s74, 0x100
	s_addc_u32 s75, s75, 0
	s_cmp_lt_u32 s69, 60
	s_cbranch_scc1 .LBB0_154
	s_add_u32 s72, s72, 0x1f80
	v_readfirstlane_b32 s69, v167
	s_addc_u32 s73, s73, 0
	s_mov_b32 m0, s69
	v_readfirstlane_b32 s69, v168
	ds_read_b128 v[138:141], v149
	ds_read_b128 v[142:145], v149 offset:1024
	ds_read_b128 v[170:173], v149 offset:2048
	ds_read_b128 v[174:177], v149 offset:3072
	ds_read_b128 v[178:181], v149 offset:16384
	ds_read_b128 v[182:185], v149 offset:17408
	ds_read_b128 v[186:189], v149 offset:18432
	ds_read_b128 v[190:193], v149 offset:19456
	ds_read_b128 v[194:197], v151
	ds_read_b128 v[198:201], v151 offset:1024
	ds_read_b128 v[202:205], v151 offset:2048
	ds_read_b128 v[206:209], v151 offset:3072
	ds_read_b128 v[210:213], v151 offset:4096
	ds_read_b128 v[214:217], v151 offset:5120
	ds_read_b128 v[218:221], v151 offset:6144
	ds_read_b128 v[222:225], v151 offset:7168
	global_load_lds_dwordx4 v134, s[72:73]
	s_mov_b32 m0, s69
	s_nop 0
	global_load_lds_dwordx4 v136, s[72:73]
	s_waitcnt lgkmcnt(0)
	s_barrier
	s_setprio 1
	s_waitcnt lgkmcnt(0)
	v_mfma_f32_16x16x32_bf16 v[124:127], v[194:197], v[138:141], v[124:127]
	v_mfma_f32_16x16x32_bf16 v[120:123], v[194:197], v[170:173], v[120:123]
	v_mfma_f32_16x16x32_bf16 v[116:119], v[202:205], v[138:141], v[116:119]
	v_mfma_f32_16x16x32_bf16 v[112:115], v[202:205], v[170:173], v[112:115]
	v_mfma_f32_16x16x32_bf16 v[108:111], v[210:213], v[138:141], v[108:111]
	v_mfma_f32_16x16x32_bf16 v[104:107], v[210:213], v[170:173], v[104:107]
	v_mfma_f32_16x16x32_bf16 v[100:103], v[218:221], v[138:141], v[100:103]
	v_mfma_f32_16x16x32_bf16 v[96:99], v[218:221], v[170:173], v[96:99]
	v_mfma_f32_16x16x32_bf16 v[92:95], v[194:197], v[178:181], v[92:95]
	v_mfma_f32_16x16x32_bf16 v[88:91], v[194:197], v[186:189], v[88:91]
	v_mfma_f32_16x16x32_bf16 v[84:87], v[202:205], v[178:181], v[84:87]
	v_mfma_f32_16x16x32_bf16 v[80:83], v[202:205], v[186:189], v[80:83]
	v_mfma_f32_16x16x32_bf16 v[76:79], v[210:213], v[178:181], v[76:79]
	v_mfma_f32_16x16x32_bf16 v[72:75], v[210:213], v[186:189], v[72:75]
	v_mfma_f32_16x16x32_bf16 v[68:71], v[218:221], v[178:181], v[68:71]
	v_mfma_f32_16x16x32_bf16 v[64:67], v[218:221], v[186:189], v[64:67]
	v_mfma_f32_16x16x32_bf16 v[124:127], v[198:201], v[142:145], v[124:127]
	v_mfma_f32_16x16x32_bf16 v[120:123], v[198:201], v[174:177], v[120:123]
	v_mfma_f32_16x16x32_bf16 v[116:119], v[206:209], v[142:145], v[116:119]
	v_mfma_f32_16x16x32_bf16 v[112:115], v[206:209], v[174:177], v[112:115]
	v_mfma_f32_16x16x32_bf16 v[108:111], v[214:217], v[142:145], v[108:111]
	v_mfma_f32_16x16x32_bf16 v[104:107], v[214:217], v[174:177], v[104:107]
	v_mfma_f32_16x16x32_bf16 v[100:103], v[222:225], v[142:145], v[100:103]
	v_mfma_f32_16x16x32_bf16 v[96:99], v[222:225], v[174:177], v[96:99]
	v_mfma_f32_16x16x32_bf16 v[92:95], v[198:201], v[182:185], v[92:95]
	v_mfma_f32_16x16x32_bf16 v[88:91], v[198:201], v[190:193], v[88:91]
	v_mfma_f32_16x16x32_bf16 v[84:87], v[206:209], v[182:185], v[84:87]
	v_mfma_f32_16x16x32_bf16 v[80:83], v[206:209], v[190:193], v[80:83]
	v_mfma_f32_16x16x32_bf16 v[76:79], v[214:217], v[182:185], v[76:79]
	v_mfma_f32_16x16x32_bf16 v[72:75], v[214:217], v[190:193], v[72:75]
	v_mfma_f32_16x16x32_bf16 v[68:71], v[222:225], v[182:185], v[68:71]
	v_mfma_f32_16x16x32_bf16 v[64:67], v[222:225], v[190:193], v[64:67]
	s_setprio 0
	s_barrier
	ds_read_b128 v[194:197], v151 offset:16384
	ds_read_b128 v[198:201], v151 offset:17408
	ds_read_b128 v[202:205], v151 offset:18432
	ds_read_b128 v[206:209], v151 offset:19456
	ds_read_b128 v[210:213], v151 offset:20480
	ds_read_b128 v[214:217], v151 offset:21504
	ds_read_b128 v[218:221], v151 offset:22528
	ds_read_b128 v[222:225], v151 offset:23552
	s_waitcnt vmcnt(0)
	s_waitcnt lgkmcnt(0)
	s_barrier
	s_setprio 1
	s_waitcnt lgkmcnt(0)
	v_mfma_f32_16x16x32_bf16 v[56:59], v[194:197], v[170:173], v[56:59]
	v_mfma_f32_16x16x32_bf16 v[52:55], v[202:205], v[138:141], v[52:55]
	v_mfma_f32_16x16x32_bf16 v[48:51], v[202:205], v[170:173], v[48:51]
	v_mfma_f32_16x16x32_bf16 v[44:47], v[210:213], v[138:141], v[44:47]
	v_mfma_f32_16x16x32_bf16 v[40:43], v[210:213], v[170:173], v[40:43]
	v_mfma_f32_16x16x32_bf16 v[36:39], v[218:221], v[138:141], v[36:39]
	v_mfma_f32_16x16x32_bf16 v[32:35], v[218:221], v[170:173], v[32:35]
	v_mfma_f32_16x16x32_bf16 v[28:31], v[194:197], v[178:181], v[28:31]
	v_mfma_f32_16x16x32_bf16 v[24:27], v[194:197], v[186:189], v[24:27]
	v_mfma_f32_16x16x32_bf16 v[20:23], v[202:205], v[178:181], v[20:23]
	v_mfma_f32_16x16x32_bf16 v[16:19], v[202:205], v[186:189], v[16:19]
	v_mfma_f32_16x16x32_bf16 v[12:15], v[210:213], v[178:181], v[12:15]
	v_mfma_f32_16x16x32_bf16 v[8:11], v[210:213], v[186:189], v[8:11]
	v_mfma_f32_16x16x32_bf16 v[4:7], v[218:221], v[178:181], v[4:7]
	v_mfma_f32_16x16x32_bf16 v[0:3], v[218:221], v[186:189], v[0:3]
	v_mfma_f32_16x16x32_bf16 v[60:63], v[194:197], v[138:141], v[60:63]
	v_mfma_f32_16x16x32_bf16 v[56:59], v[198:201], v[174:177], v[56:59]
	v_mfma_f32_16x16x32_bf16 v[52:55], v[206:209], v[142:145], v[52:55]
	v_mfma_f32_16x16x32_bf16 v[48:51], v[206:209], v[174:177], v[48:51]
	v_mfma_f32_16x16x32_bf16 v[44:47], v[214:217], v[142:145], v[44:47]
	v_mfma_f32_16x16x32_bf16 v[40:43], v[214:217], v[174:177], v[40:43]
	v_mfma_f32_16x16x32_bf16 v[36:39], v[222:225], v[142:145], v[36:39]
	v_mfma_f32_16x16x32_bf16 v[32:35], v[222:225], v[174:177], v[32:35]
	v_mfma_f32_16x16x32_bf16 v[28:31], v[198:201], v[182:185], v[28:31]
	v_mfma_f32_16x16x32_bf16 v[24:27], v[198:201], v[190:193], v[24:27]
	v_mfma_f32_16x16x32_bf16 v[20:23], v[206:209], v[182:185], v[20:23]
	v_mfma_f32_16x16x32_bf16 v[16:19], v[206:209], v[190:193], v[16:19]
	v_mfma_f32_16x16x32_bf16 v[12:15], v[214:217], v[182:185], v[12:15]
	v_mfma_f32_16x16x32_bf16 v[8:11], v[214:217], v[190:193], v[8:11]
	v_mfma_f32_16x16x32_bf16 v[4:7], v[222:225], v[182:185], v[4:7]
	v_mfma_f32_16x16x32_bf16 v[0:3], v[222:225], v[190:193], v[0:3]
	v_mfma_f32_16x16x32_bf16 v[226:229], v[198:201], v[142:145], v[60:63]
	s_setprio 0
	s_barrier
; #define LDA(dst, b, h) _Pragma("unroll") for (int m = 0; m < 4; ++m) _Pragma("unroll") for (int k = 0; k < 2; ++k) \
;     dst[m][k] = *reinterpret_cast<const bf16x8*>((const char*)shm + aB + (((b) * 2 + (h)) * 16384 + (m * 2 + k) * 1024))
; #define LDB(dst, b, h) _Pragma("unroll") for (int n = 0; n < 2; ++n) _Pragma("unroll") for (int k = 0; k < 2; ++k) \
;     dst[n][k] = *reinterpret_cast<const bf16x8*>((const char*)shm + bB + (((b) * 2 + (h)) * 16384 + (n * 2 + k) * 1024))
; #define WAIT_L(n) asm volatile("s_waitcnt lgkmcnt(" #n ")" ::: "memory")
; #define BAR __builtin_amdgcn_s_barrier()
; #define SCHED __builtin_amdgcn_sched_barrier(0)
; template <int MODE> ...
;     ...
;       LDB(B0, 1, 0); LDB(B1, 1, 1); LDA(At, 1, 0); WAIT_L(0); BAR; MMA2(0, 0, 0, 1); BAR; SCHED;
;       LDA(At, 1, 1); WAIT_L(0); BAR; MMA2(1, 0, 1, 1); BAR; SCHED;
;     }
;     ...
;     if (wr == 0) BAR;
	ds_read_b128 v[138:141], v149 offset:32768
	ds_read_b128 v[142:145], v149 offset:33792
	ds_read_b128 v[170:173], v149 offset:34816
	ds_read_b128 v[174:177], v149 offset:35840
	ds_read_b128 v[178:181], v149 offset:49152
	ds_read_b128 v[182:185], v149 offset:50176
	ds_read_b128 v[186:189], v149 offset:51200
	ds_read_b128 v[190:193], v149 offset:52224
	ds_read_b128 v[60:63], v151 offset:32768
	ds_read_b128 v[194:197], v151 offset:33792
	ds_read_b128 v[198:201], v151 offset:34816
	ds_read_b128 v[202:205], v151 offset:35840
	ds_read_b128 v[206:209], v151 offset:36864
	ds_read_b128 v[210:213], v151 offset:37888
	ds_read_b128 v[214:217], v151 offset:38912
	ds_read_b128 v[218:221], v151 offset:39936
	s_waitcnt lgkmcnt(0)
	s_barrier
	s_setprio 1
	s_waitcnt lgkmcnt(0)
	v_mfma_f32_16x16x32_bf16 v[124:127], v[60:63], v[138:141], v[124:127]
	v_mfma_f32_16x16x32_bf16 v[120:123], v[60:63], v[170:173], v[120:123]
	v_mfma_f32_16x16x32_bf16 v[92:95], v[60:63], v[178:181], v[92:95]
	v_mfma_f32_16x16x32_bf16 v[60:63], v[60:63], v[186:189], v[88:91]
	v_mfma_f32_16x16x32_bf16 v[88:91], v[194:197], v[190:193], v[60:63]
	v_mfma_f32_16x16x32_bf16 v[60:63], v[198:201], v[178:181], v[84:87]
	v_mfma_f32_16x16x32_bf16 v[84:87], v[202:205], v[182:185], v[60:63]
	v_mfma_f32_16x16x32_bf16 v[60:63], v[198:201], v[186:189], v[80:83]
	v_mfma_f32_16x16x32_bf16 v[80:83], v[202:205], v[190:193], v[60:63]
	v_mfma_f32_16x16x32_bf16 v[60:63], v[206:209], v[178:181], v[76:79]
	v_mfma_f32_16x16x32_bf16 v[76:79], v[210:213], v[182:185], v[60:63]
	v_mfma_f32_16x16x32_bf16 v[60:63], v[206:209], v[186:189], v[72:75]
	v_mfma_f32_16x16x32_bf16 v[72:75], v[210:213], v[190:193], v[60:63]
	v_mfma_f32_16x16x32_bf16 v[60:63], v[214:217], v[178:181], v[68:71]
	v_mfma_f32_16x16x32_bf16 v[116:119], v[198:201], v[138:141], v[116:119]
	v_mfma_f32_16x16x32_bf16 v[112:115], v[198:201], v[170:173], v[112:115]
	v_mfma_f32_16x16x32_bf16 v[108:111], v[206:209], v[138:141], v[108:111]
	v_mfma_f32_16x16x32_bf16 v[104:107], v[206:209], v[170:173], v[104:107]
	v_mfma_f32_16x16x32_bf16 v[100:103], v[214:217], v[138:141], v[100:103]
	v_mfma_f32_16x16x32_bf16 v[96:99], v[214:217], v[170:173], v[96:99]
	v_mfma_f32_16x16x32_bf16 v[68:71], v[218:221], v[182:185], v[60:63]
	v_mfma_f32_16x16x32_bf16 v[60:63], v[214:217], v[186:189], v[64:67]
	v_mfma_f32_16x16x32_bf16 v[124:127], v[194:197], v[142:145], v[124:127]
	v_mfma_f32_16x16x32_bf16 v[120:123], v[194:197], v[174:177], v[120:123]
	v_mfma_f32_16x16x32_bf16 v[116:119], v[202:205], v[142:145], v[116:119]
	v_mfma_f32_16x16x32_bf16 v[112:115], v[202:205], v[174:177], v[112:115]
	v_mfma_f32_16x16x32_bf16 v[108:111], v[210:213], v[142:145], v[108:111]
	v_mfma_f32_16x16x32_bf16 v[104:107], v[210:213], v[174:177], v[104:107]
	v_mfma_f32_16x16x32_bf16 v[100:103], v[218:221], v[142:145], v[100:103]
	v_mfma_f32_16x16x32_bf16 v[96:99], v[218:221], v[174:177], v[96:99]
	v_mfma_f32_16x16x32_bf16 v[92:95], v[194:197], v[182:185], v[92:95]
	v_mfma_f32_16x16x32_bf16 v[60:63], v[218:221], v[190:193], v[60:63]
	s_setprio 0
	s_barrier
	ds_read_b128 v[194:197], v151 offset:49152
	ds_read_b128 v[198:201], v151 offset:50176
	ds_read_b128 v[202:205], v151 offset:51200
	ds_read_b128 v[206:209], v151 offset:52224
	ds_read_b128 v[210:213], v151 offset:53248
	ds_read_b128 v[214:217], v151 offset:54272
	ds_read_b128 v[218:221], v151 offset:55296
	ds_read_b128 v[222:225], v151 offset:56320
	s_waitcnt lgkmcnt(0)
	s_barrier
	s_setprio 1
	s_waitcnt lgkmcnt(0)
	v_mfma_f32_16x16x32_bf16 v[64:67], v[194:197], v[138:141], v[226:229]
	v_mfma_f32_16x16x32_bf16 v[56:59], v[194:197], v[170:173], v[56:59]
	v_mfma_f32_16x16x32_bf16 v[52:55], v[202:205], v[138:141], v[52:55]
	v_mfma_f32_16x16x32_bf16 v[48:51], v[202:205], v[170:173], v[48:51]
	v_mfma_f32_16x16x32_bf16 v[44:47], v[210:213], v[138:141], v[44:47]
	v_mfma_f32_16x16x32_bf16 v[40:43], v[210:213], v[170:173], v[40:43]
	v_mfma_f32_16x16x32_bf16 v[36:39], v[218:221], v[138:141], v[36:39]
	v_mfma_f32_16x16x32_bf16 v[32:35], v[218:221], v[170:173], v[32:35]
	v_mfma_f32_16x16x32_bf16 v[28:31], v[194:197], v[178:181], v[28:31]
	v_mfma_f32_16x16x32_bf16 v[24:27], v[194:197], v[186:189], v[24:27]
	v_mfma_f32_16x16x32_bf16 v[20:23], v[202:205], v[178:181], v[20:23]
	v_mfma_f32_16x16x32_bf16 v[16:19], v[202:205], v[186:189], v[16:19]
	v_mfma_f32_16x16x32_bf16 v[12:15], v[210:213], v[178:181], v[12:15]
	v_mfma_f32_16x16x32_bf16 v[8:11], v[210:213], v[186:189], v[8:11]
	v_mfma_f32_16x16x32_bf16 v[4:7], v[218:221], v[178:181], v[4:7]
	v_mfma_f32_16x16x32_bf16 v[0:3], v[218:221], v[186:189], v[0:3]
	v_mfma_f32_16x16x32_bf16 v[64:67], v[198:201], v[142:145], v[64:67]
	v_mfma_f32_16x16x32_bf16 v[56:59], v[198:201], v[174:177], v[56:59]
	v_mfma_f32_16x16x32_bf16 v[52:55], v[206:209], v[142:145], v[52:55]
	v_mfma_f32_16x16x32_bf16 v[48:51], v[206:209], v[174:177], v[48:51]
	v_mfma_f32_16x16x32_bf16 v[44:47], v[214:217], v[142:145], v[44:47]
	v_mfma_f32_16x16x32_bf16 v[40:43], v[214:217], v[174:177], v[40:43]
	v_mfma_f32_16x16x32_bf16 v[36:39], v[222:225], v[142:145], v[36:39]
	v_mfma_f32_16x16x32_bf16 v[32:35], v[222:225], v[174:177], v[32:35]
	v_mfma_f32_16x16x32_bf16 v[28:31], v[198:201], v[182:185], v[28:31]
	v_mfma_f32_16x16x32_bf16 v[24:27], v[198:201], v[190:193], v[24:27]
	v_mfma_f32_16x16x32_bf16 v[20:23], v[206:209], v[182:185], v[20:23]
	v_mfma_f32_16x16x32_bf16 v[16:19], v[206:209], v[190:193], v[16:19]
	v_mfma_f32_16x16x32_bf16 v[12:15], v[214:217], v[182:185], v[12:15]
	v_mfma_f32_16x16x32_bf16 v[8:11], v[214:217], v[190:193], v[8:11]
	v_mfma_f32_16x16x32_bf16 v[4:7], v[222:225], v[182:185], v[4:7]
	v_mfma_f32_16x16x32_bf16 v[0:3], v[222:225], v[190:193], v[0:3]
	s_setprio 0
	s_barrier
	s_and_saveexec_b64 s[72:73], s[6:7]
	s_cbranch_execz .LBB0_157
	s_barrier

; #define STAGE(Pp, BASE, br, kt) do { const u16* _g = (BASE) + ((long)(br) * K + (long)(kt) * BK); \
;     __builtin_amdgcn_global_load_lds((const unsigned*)(_g + voff0), (unsigned*)((char*)(Pp) + tb16), 16, 0, 0); \
;     __builtin_amdgcn_global_load_lds((const unsigned*)(_g + voff1), (unsigned*)((char*)(Pp) + tb16 + 8192), 16, 0, 0); } while (0)
; #define LDA(dst, b, h) _Pragma("unroll") for (int m = 0; m < 4; ++m) _Pragma("unroll") for (int k = 0; k < 2; ++k) \
;     dst[m][k] = *reinterpret_cast<const bf16x8*>((const char*)shm + aB + (((b) * 2 + (h)) * 16384 + (m * 2 + k) * 1024))
; #define LDB(dst, b, h) _Pragma("unroll") for (int n = 0; n < 2; ++n) _Pragma("unroll") for (int k = 0; k < 2; ++k) \
;     dst[n][k] = *reinterpret_cast<const bf16x8*>((const char*)shm + bB + (((b) * 2 + (h)) * 16384 + (n * 2 + k) * 1024))
; #define WAIT_V(n) asm volatile("s_waitcnt vmcnt(" #n ")" ::: "memory")
; #define WAIT_L(n) asm volatile("s_waitcnt lgkmcnt(" #n ")" ::: "memory")
; #define BAR __builtin_amdgcn_s_barrier()
; #define SCHED __builtin_amdgcn_sched_barrier(0)
; template <int MODE> ...
;     ...
;     f32x4 acc[2][2][4][2] = {};
;     bf16x8 At[4][2], B0[2][2], B1[2][2];
;     ...
;     STAGE(SB(0, 0), Bt, bcol, 0); STAGE(SA(0, 0), A, brow, 0); STAGE(SB(0, 1), Bt, bcol + HALF, 0); STAGE(SA(0, 1), A, brow + HALF, 0);
;     STAGE(SB(1, 0), Bt, bcol, 1); STAGE(SA(1, 0), A, brow, 1); STAGE(SB(1, 1), Bt, bcol + HALF, 1);
;     WAIT_V(6);
;     if (wr == 1) BAR;
;     BAR;
;     for (int t = 0; t < nt - 2; t += 2) {
;       LDB(B0, 0, 0); LDB(B1, 0, 1); LDA(At, 0, 0); STAGE(SA(1, 1), A, brow + HALF, t + 1);
;       WAIT_L(0); BAR; MMA2(0, 0, 0, 1); BAR; SCHED;
.LBB0_176:
	s_or_b64 exec, exec, s[70:71]
	v_lshl_add_u64 v[138:139], v[130:131], 0, s[68:69]
	v_lshl_add_u64 v[140:141], v[132:133], 0, s[68:69]
	s_lshl_b32 s68, s75, 11
	s_lshl_b32 s69, s76, 8
	s_add_i32 s68, s68, s69
	s_ashr_i32 s69, s68, 31
	s_lshl_b64 s[68:69], s[68:69], 13
	v_mov_b32_e32 v0, 0
	s_lshl_b64 s[64:65], s[64:65], 12
	v_lshl_add_u64 v[142:143], v[130:131], 0, s[68:69]
	v_lshl_add_u64 v[144:145], v[132:133], 0, s[68:69]
	s_mov_b32 s70, -2
	s_mov_b64 s[68:69], s[56:57]
	v_mov_b32_e32 v1, v0
	v_mov_b32_e32 v2, v0
	v_mov_b32_e32 v3, v0
	v_mov_b32_e32 v4, v0
	v_mov_b32_e32 v5, v0
	v_mov_b32_e32 v6, v0
	v_mov_b32_e32 v7, v0
	v_mov_b32_e32 v8, v0
	v_mov_b32_e32 v9, v0
	v_mov_b32_e32 v10, v0
	v_mov_b32_e32 v11, v0
	v_mov_b32_e32 v12, v0
	v_mov_b32_e32 v13, v0
	v_mov_b32_e32 v14, v0
	v_mov_b32_e32 v15, v0
	v_mov_b32_e32 v16, v0
	v_mov_b32_e32 v17, v0
	v_mov_b32_e32 v18, v0
	v_mov_b32_e32 v19, v0
	v_mov_b32_e32 v20, v0
	v_mov_b32_e32 v21, v0
	v_mov_b32_e32 v22, v0
	v_mov_b32_e32 v23, v0
	v_mov_b32_e32 v24, v0
	v_mov_b32_e32 v25, v0
	v_mov_b32_e32 v26, v0
	v_mov_b32_e32 v27, v0
	v_mov_b32_e32 v28, v0
	v_mov_b32_e32 v29, v0
	v_mov_b32_e32 v30, v0
	v_mov_b32_e32 v31, v0
	v_mov_b32_e32 v32, v0
	v_mov_b32_e32 v33, v0
	v_mov_b32_e32 v34, v0
	v_mov_b32_e32 v35, v0
	v_mov_b32_e32 v36, v0
	v_mov_b32_e32 v37, v0
	v_mov_b32_e32 v38, v0
	v_mov_b32_e32 v39, v0
	v_mov_b32_e32 v40, v0
	v_mov_b32_e32 v41, v0
	v_mov_b32_e32 v42, v0
	v_mov_b32_e32 v43, v0
	v_mov_b32_e32 v44, v0
	v_mov_b32_e32 v45, v0
	v_mov_b32_e32 v46, v0
	v_mov_b32_e32 v47, v0
	v_mov_b32_e32 v48, v0
	v_mov_b32_e32 v49, v0
	v_mov_b32_e32 v50, v0
	v_mov_b32_e32 v51, v0
	v_mov_b32_e32 v52, v0
	v_mov_b32_e32 v53, v0
	v_mov_b32_e32 v54, v0
	v_mov_b32_e32 v55, v0
	v_mov_b32_e32 v56, v0
	v_mov_b32_e32 v57, v0
	v_mov_b32_e32 v58, v0
	v_mov_b32_e32 v59, v0
	v_mov_b32_e32 v60, v0
	v_mov_b32_e32 v61, v0
	v_mov_b32_e32 v62, v0
	v_mov_b32_e32 v63, v0
	v_mov_b32_e32 v64, v0
	v_mov_b32_e32 v65, v0
	v_mov_b32_e32 v66, v0
	v_mov_b32_e32 v67, v0
	v_mov_b32_e32 v68, v0
	v_mov_b32_e32 v69, v0
	v_mov_b32_e32 v70, v0
	v_mov_b32_e32 v71, v0
	v_mov_b32_e32 v72, v0
	v_mov_b32_e32 v73, v0
	v_mov_b32_e32 v74, v0
	v_mov_b32_e32 v75, v0
	v_mov_b32_e32 v76, v0
	v_mov_b32_e32 v77, v0
	v_mov_b32_e32 v78, v0
	v_mov_b32_e32 v79, v0
	v_mov_b32_e32 v80, v0
	v_mov_b32_e32 v81, v0
	v_mov_b32_e32 v82, v0
	v_mov_b32_e32 v83, v0
	v_mov_b32_e32 v84, v0
	v_mov_b32_e32 v85, v0
	v_mov_b32_e32 v86, v0
	v_mov_b32_e32 v87, v0
	v_mov_b32_e32 v88, v0
	v_mov_b32_e32 v89, v0
	v_mov_b32_e32 v90, v0
	v_mov_b32_e32 v91, v0
	v_mov_b32_e32 v92, v0
	v_mov_b32_e32 v93, v0
	v_mov_b32_e32 v94, v0
	v_mov_b32_e32 v95, v0
	v_mov_b32_e32 v96, v0
	v_mov_b32_e32 v97, v0
	v_mov_b32_e32 v98, v0
	v_mov_b32_e32 v99, v0
	v_mov_b32_e32 v100, v0
	v_mov_b32_e32 v101, v0
	v_mov_b32_e32 v102, v0
	v_mov_b32_e32 v103, v0
	v_mov_b32_e32 v104, v0
	v_mov_b32_e32 v105, v0
	v_mov_b32_e32 v106, v0
	v_mov_b32_e32 v107, v0
	v_mov_b32_e32 v108, v0
	v_mov_b32_e32 v109, v0
	v_mov_b32_e32 v110, v0
	v_mov_b32_e32 v111, v0
	v_mov_b32_e32 v112, v0
	v_mov_b32_e32 v113, v0
	v_mov_b32_e32 v114, v0
	v_mov_b32_e32 v115, v0
	v_mov_b32_e32 v116, v0
	v_mov_b32_e32 v117, v0
	v_mov_b32_e32 v118, v0
	v_mov_b32_e32 v119, v0
	v_mov_b32_e32 v120, v0
	v_mov_b32_e32 v121, v0
	v_mov_b32_e32 v122, v0
	v_mov_b32_e32 v123, v0
	v_mov_b32_e32 v124, v0
	v_mov_b32_e32 v125, v0
	v_mov_b32_e32 v126, v0
	v_mov_b32_e32 v127, v0
	v_readfirstlane_b32 s32, v151
	s_barrier
.LBB0_177:
	s_add_u32 s71, s32, 0xc000
	s_mov_b32 m0, s71
	ds_read_b128 v[168:171], v148
	ds_read_b128 v[172:175], v148 offset:1024
	ds_read_b128 v[176:179], v148 offset:2048
	ds_read_b128 v[180:183], v148 offset:3072
	ds_read_b128 v[184:187], v148 offset:16384
	ds_read_b128 v[188:191], v148 offset:17408
	ds_read_b128 v[192:195], v148 offset:18432
	ds_read_b128 v[196:199], v148 offset:19456
	ds_read_b128 v[200:203], v147
	ds_read_b128 v[204:207], v147 offset:1024
	ds_read_b128 v[208:211], v147 offset:2048
	ds_read_b128 v[212:215], v147 offset:3072
	ds_read_b128 v[216:219], v147 offset:4096
	ds_read_b128 v[220:223], v147 offset:5120
	ds_read_b128 v[224:227], v147 offset:6144
	ds_read_b128 v[228:231], v147 offset:7168
	s_add_u32 s88, s68, s12
	s_addc_u32 s89, s69, s13
	global_load_lds_dwordx4 v142, s[88:89]
	s_add_u32 s71, s32, 0xe000
	s_mov_b32 m0, s71
	s_nop 0
	s_add_u32 s90, s68, s12
	s_addc_u32 s91, s69, s13
	global_load_lds_dwordx4 v144, s[90:91]
	s_waitcnt lgkmcnt(0)
	s_barrier
	s_setprio 1
	s_waitcnt lgkmcnt(0)
	v_mfma_f32_16x16x32_bf16 v[124:127], v[200:203], v[168:171], v[124:127]
	v_mfma_f32_16x16x32_bf16 v[120:123], v[200:203], v[176:179], v[120:123]
	v_mfma_f32_16x16x32_bf16 v[116:119], v[208:211], v[168:171], v[116:119]
	v_mfma_f32_16x16x32_bf16 v[112:115], v[208:211], v[176:179], v[112:115]
	v_mfma_f32_16x16x32_bf16 v[108:111], v[216:219], v[168:171], v[108:111]
	v_mfma_f32_16x16x32_bf16 v[104:107], v[216:219], v[176:179], v[104:107]
	v_mfma_f32_16x16x32_bf16 v[100:103], v[224:227], v[168:171], v[100:103]
	v_mfma_f32_16x16x32_bf16 v[96:99], v[224:227], v[176:179], v[96:99]
	v_mfma_f32_16x16x32_bf16 v[92:95], v[200:203], v[184:187], v[92:95]
	v_mfma_f32_16x16x32_bf16 v[88:91], v[200:203], v[192:195], v[88:91]
	v_mfma_f32_16x16x32_bf16 v[84:87], v[208:211], v[184:187], v[84:87]
	v_mfma_f32_16x16x32_bf16 v[80:83], v[208:211], v[192:195], v[80:83]
	v_mfma_f32_16x16x32_bf16 v[76:79], v[216:219], v[184:187], v[76:79]
	v_mfma_f32_16x16x32_bf16 v[72:75], v[216:219], v[192:195], v[72:75]
	v_mfma_f32_16x16x32_bf16 v[68:71], v[224:227], v[184:187], v[68:71]
	v_mfma_f32_16x16x32_bf16 v[64:67], v[224:227], v[192:195], v[64:67]
	v_mfma_f32_16x16x32_bf16 v[124:127], v[204:207], v[172:175], v[124:127]
	v_mfma_f32_16x16x32_bf16 v[120:123], v[204:207], v[180:183], v[120:123]
	v_mfma_f32_16x16x32_bf16 v[116:119], v[212:215], v[172:175], v[116:119]
	v_mfma_f32_16x16x32_bf16 v[112:115], v[212:215], v[180:183], v[112:115]
	v_mfma_f32_16x16x32_bf16 v[108:111], v[220:223], v[172:175], v[108:111]
	v_mfma_f32_16x16x32_bf16 v[104:107], v[220:223], v[180:183], v[104:107]
	v_mfma_f32_16x16x32_bf16 v[100:103], v[228:231], v[172:175], v[100:103]
	v_mfma_f32_16x16x32_bf16 v[96:99], v[228:231], v[180:183], v[96:99]
	v_mfma_f32_16x16x32_bf16 v[92:95], v[204:207], v[188:191], v[92:95]
	v_mfma_f32_16x16x32_bf16 v[88:91], v[204:207], v[196:199], v[88:91]
	v_mfma_f32_16x16x32_bf16 v[84:87], v[212:215], v[188:191], v[84:87]
	v_mfma_f32_16x16x32_bf16 v[80:83], v[212:215], v[196:199], v[80:83]
	v_mfma_f32_16x16x32_bf16 v[76:79], v[220:223], v[188:191], v[76:79]
	v_mfma_f32_16x16x32_bf16 v[72:75], v[220:223], v[196:199], v[72:75]
	v_mfma_f32_16x16x32_bf16 v[68:71], v[228:231], v[188:191], v[68:71]
	v_mfma_f32_16x16x32_bf16 v[64:67], v[228:231], v[196:199], v[64:67]
	s_setprio 0
	s_barrier
; #define STAGE(Pp, BASE, br, kt) do { const u16* _g = (BASE) + ((long)(br) * K + (long)(kt) * BK); \
;     __builtin_amdgcn_global_load_lds((const unsigned*)(_g + voff0), (unsigned*)((char*)(Pp) + tb16), 16, 0, 0); \
;     __builtin_amdgcn_global_load_lds((const unsigned*)(_g + voff1), (unsigned*)((char*)(Pp) + tb16 + 8192), 16, 0, 0); } while (0)
; #define LDA(dst, b, h) _Pragma("unroll") for (int m = 0; m < 4; ++m) _Pragma("unroll") for (int k = 0; k < 2; ++k) \
;     dst[m][k] = *reinterpret_cast<const bf16x8*>((const char*)shm + aB + (((b) * 2 + (h)) * 16384 + (m * 2 + k) * 1024))
; #define LDB(dst, b, h) _Pragma("unroll") for (int n = 0; n < 2; ++n) _Pragma("unroll") for (int k = 0; k < 2; ++k) \
;     dst[n][k] = *reinterpret_cast<const bf16x8*>((const char*)shm + bB + (((b) * 2 + (h)) * 16384 + (n * 2 + k) * 1024))
; #define WAIT_V(n) asm volatile("s_waitcnt vmcnt(" #n ")" ::: "memory")
; #define WAIT_L(n) asm volatile("s_waitcnt lgkmcnt(" #n ")" ::: "memory")
; #define BAR __builtin_amdgcn_s_barrier()
; #define SCHED __builtin_amdgcn_sched_barrier(0)
; template <int MODE> ...
;     ...
;       LDA(At, 0, 1); STAGE(SB(0, 0), Bt, bcol, t + 2); STAGE(SB(0, 1), Bt, bcol + HALF, t + 2); STAGE(SA(0, 0), A, brow, t + 2);
;       WAIT_V(6); WAIT_L(0); BAR; MMA2(1, 0, 1, 1); BAR; SCHED;
;       LDB(B0, 1, 0); LDB(B1, 1, 1); LDA(At, 1, 0); STAGE(SA(0, 1), A, brow + HALF, t + 2);
	s_add_u32 s71, s32, 0x10000
	s_mov_b32 m0, s71
	ds_read_b128 v[200:203], v147 offset:16384
	ds_read_b128 v[204:207], v147 offset:17408
	ds_read_b128 v[208:211], v147 offset:18432
	ds_read_b128 v[212:215], v147 offset:19456
	ds_read_b128 v[216:219], v147 offset:20480
	ds_read_b128 v[220:223], v147 offset:21504
	ds_read_b128 v[224:227], v147 offset:22528
	ds_read_b128 v[228:231], v147 offset:23552
	s_add_u32 s92, s68, s38
	s_addc_u32 s93, s69, s39
	global_load_lds_dwordx4 v138, s[92:93]
	s_add_u32 s71, s32, 0x12000
	s_mov_b32 m0, s71
	s_add_u32 s71, s32, 0x14000
	s_add_u32 s96, s68, s38
	s_addc_u32 s97, s69, s39
	global_load_lds_dwordx4 v140, s[96:97]
	s_mov_b32 m0, s71
	s_add_u32 s71, s32, 0x16000
	s_add_u32 s88, s68, s40
	s_addc_u32 s89, s69, s41
	global_load_lds_dwordx4 v138, s[88:89]
	s_mov_b32 m0, s71
	s_mov_b32 s71, s32
	s_add_u32 s90, s68, s40
	s_addc_u32 s91, s69, s41
	global_load_lds_dwordx4 v140, s[90:91]
	s_mov_b32 m0, s71
	s_add_u32 s71, s32, 0x2000
	s_add_u32 s92, s68, s42
	s_addc_u32 s93, s69, s43
	global_load_lds_dwordx4 v142, s[92:93]
	s_mov_b32 m0, s71
	s_nop 0
	s_add_u32 s96, s68, s42
	s_addc_u32 s97, s69, s43
	global_load_lds_dwordx4 v144, s[96:97]
	s_waitcnt vmcnt(6)
	s_waitcnt lgkmcnt(0)
	s_barrier
	s_setprio 1
	s_waitcnt lgkmcnt(0)
	v_mfma_f32_16x16x32_bf16 v[60:63], v[200:203], v[168:171], v[60:63]
	v_mfma_f32_16x16x32_bf16 v[56:59], v[200:203], v[176:179], v[56:59]
	v_mfma_f32_16x16x32_bf16 v[52:55], v[208:211], v[168:171], v[52:55]
	v_mfma_f32_16x16x32_bf16 v[48:51], v[208:211], v[176:179], v[48:51]
	v_mfma_f32_16x16x32_bf16 v[44:47], v[216:219], v[168:171], v[44:47]
	v_mfma_f32_16x16x32_bf16 v[40:43], v[216:219], v[176:179], v[40:43]
	v_mfma_f32_16x16x32_bf16 v[36:39], v[224:227], v[168:171], v[36:39]
	v_mfma_f32_16x16x32_bf16 v[32:35], v[224:227], v[176:179], v[32:35]
	v_mfma_f32_16x16x32_bf16 v[28:31], v[200:203], v[184:187], v[28:31]
	v_mfma_f32_16x16x32_bf16 v[24:27], v[200:203], v[192:195], v[24:27]
	v_mfma_f32_16x16x32_bf16 v[20:23], v[208:211], v[184:187], v[20:23]
	v_mfma_f32_16x16x32_bf16 v[16:19], v[208:211], v[192:195], v[16:19]
	v_mfma_f32_16x16x32_bf16 v[12:15], v[216:219], v[184:187], v[12:15]
	v_mfma_f32_16x16x32_bf16 v[8:11], v[216:219], v[192:195], v[8:11]
	v_mfma_f32_16x16x32_bf16 v[4:7], v[224:227], v[184:187], v[4:7]
	v_mfma_f32_16x16x32_bf16 v[0:3], v[224:227], v[192:195], v[0:3]
	v_mfma_f32_16x16x32_bf16 v[60:63], v[204:207], v[172:175], v[60:63]
	v_mfma_f32_16x16x32_bf16 v[56:59], v[204:207], v[180:183], v[56:59]
	v_mfma_f32_16x16x32_bf16 v[52:55], v[212:215], v[172:175], v[52:55]
	v_mfma_f32_16x16x32_bf16 v[48:51], v[212:215], v[180:183], v[48:51]
	v_mfma_f32_16x16x32_bf16 v[44:47], v[220:223], v[172:175], v[44:47]
	v_mfma_f32_16x16x32_bf16 v[40:43], v[220:223], v[180:183], v[40:43]
	v_mfma_f32_16x16x32_bf16 v[36:39], v[228:231], v[172:175], v[36:39]
	v_mfma_f32_16x16x32_bf16 v[32:35], v[228:231], v[180:183], v[32:35]
	v_mfma_f32_16x16x32_bf16 v[28:31], v[204:207], v[188:191], v[28:31]
	v_mfma_f32_16x16x32_bf16 v[24:27], v[204:207], v[196:199], v[24:27]
	v_mfma_f32_16x16x32_bf16 v[20:23], v[212:215], v[188:191], v[20:23]
	v_mfma_f32_16x16x32_bf16 v[16:19], v[212:215], v[196:199], v[16:19]
	v_mfma_f32_16x16x32_bf16 v[12:15], v[220:223], v[188:191], v[12:15]
	v_mfma_f32_16x16x32_bf16 v[8:11], v[220:223], v[196:199], v[8:11]
	v_mfma_f32_16x16x32_bf16 v[4:7], v[228:231], v[188:191], v[4:7]
	v_mfma_f32_16x16x32_bf16 v[0:3], v[228:231], v[196:199], v[0:3]
	s_setprio 0
	s_barrier
	s_add_u32 s71, s32, 0x4000
	s_mov_b32 m0, s71
	s_add_u32 s71, s32, 0x6000
	ds_read_b128 v[168:171], v148 offset:32768
	ds_read_b128 v[172:175], v148 offset:33792
	ds_read_b128 v[176:179], v148 offset:34816
	ds_read_b128 v[180:183], v148 offset:35840
	ds_read_b128 v[184:187], v148 offset:49152
	ds_read_b128 v[188:191], v148 offset:50176
	ds_read_b128 v[192:195], v148 offset:51200
	ds_read_b128 v[196:199], v148 offset:52224
	ds_read_b128 v[200:203], v147 offset:32768
	ds_read_b128 v[204:207], v147 offset:33792
	ds_read_b128 v[208:211], v147 offset:34816
	ds_read_b128 v[212:215], v147 offset:35840
	ds_read_b128 v[216:219], v147 offset:36864
	ds_read_b128 v[220:223], v147 offset:37888
	ds_read_b128 v[224:227], v147 offset:38912
	ds_read_b128 v[228:231], v147 offset:39936
	s_add_u32 s88, s68, s44
	s_addc_u32 s89, s69, s45
	global_load_lds_dwordx4 v142, s[88:89]
	s_mov_b32 m0, s71
	s_nop 0
	s_add_u32 s90, s68, s44
	s_addc_u32 s91, s69, s45
	global_load_lds_dwordx4 v144, s[90:91]
	s_waitcnt lgkmcnt(0)
	s_barrier
; #define STAGE(Pp, BASE, br, kt) do { const u16* _g = (BASE) + ((long)(br) * K + (long)(kt) * BK); \
;     __builtin_amdgcn_global_load_lds((const unsigned*)(_g + voff0), (unsigned*)((char*)(Pp) + tb16), 16, 0, 0); \
;     __builtin_amdgcn_global_load_lds((const unsigned*)(_g + voff1), (unsigned*)((char*)(Pp) + tb16 + 8192), 16, 0, 0); } while (0)
; #define LDA(dst, b, h) _Pragma("unroll") for (int m = 0; m < 4; ++m) _Pragma("unroll") for (int k = 0; k < 2; ++k) \
;     dst[m][k] = *reinterpret_cast<const bf16x8*>((const char*)shm + aB + (((b) * 2 + (h)) * 16384 + (m * 2 + k) * 1024))
; #define WAIT_V(n) asm volatile("s_waitcnt vmcnt(" #n ")" ::: "memory")
; #define WAIT_L(n) asm volatile("s_waitcnt lgkmcnt(" #n ")" ::: "memory")
; #define BAR __builtin_amdgcn_s_barrier()
; #define SCHED __builtin_amdgcn_sched_barrier(0)
; template <int MODE> ...
;     ...
;       WAIT_L(0); BAR; MMA2(0, 0, 0, 1); BAR; SCHED;
;       LDA(At, 1, 1); STAGE(SB(1, 0), Bt, bcol, t + 3); STAGE(SB(1, 1), Bt, bcol + HALF, t + 3); STAGE(SA(1, 0), A, brow, t + 3);
;       WAIT_V(6); WAIT_L(0); BAR; MMA2(1, 0, 1, 1); BAR; SCHED;
	s_setprio 1
	s_waitcnt lgkmcnt(0)
	v_mfma_f32_16x16x32_bf16 v[124:127], v[200:203], v[168:171], v[124:127]
	v_mfma_f32_16x16x32_bf16 v[120:123], v[200:203], v[176:179], v[120:123]
	v_mfma_f32_16x16x32_bf16 v[116:119], v[208:211], v[168:171], v[116:119]
	v_mfma_f32_16x16x32_bf16 v[112:115], v[208:211], v[176:179], v[112:115]
	v_mfma_f32_16x16x32_bf16 v[108:111], v[216:219], v[168:171], v[108:111]
	v_mfma_f32_16x16x32_bf16 v[104:107], v[216:219], v[176:179], v[104:107]
	v_mfma_f32_16x16x32_bf16 v[100:103], v[224:227], v[168:171], v[100:103]
	v_mfma_f32_16x16x32_bf16 v[96:99], v[224:227], v[176:179], v[96:99]
	v_mfma_f32_16x16x32_bf16 v[92:95], v[200:203], v[184:187], v[92:95]
	v_mfma_f32_16x16x32_bf16 v[88:91], v[200:203], v[192:195], v[88:91]
	v_mfma_f32_16x16x32_bf16 v[84:87], v[208:211], v[184:187], v[84:87]
	v_mfma_f32_16x16x32_bf16 v[80:83], v[208:211], v[192:195], v[80:83]
	v_mfma_f32_16x16x32_bf16 v[76:79], v[216:219], v[184:187], v[76:79]
	v_mfma_f32_16x16x32_bf16 v[72:75], v[216:219], v[192:195], v[72:75]
	v_mfma_f32_16x16x32_bf16 v[68:71], v[224:227], v[184:187], v[68:71]
	v_mfma_f32_16x16x32_bf16 v[64:67], v[224:227], v[192:195], v[64:67]
	v_mfma_f32_16x16x32_bf16 v[124:127], v[204:207], v[172:175], v[124:127]
	v_mfma_f32_16x16x32_bf16 v[120:123], v[204:207], v[180:183], v[120:123]
	v_mfma_f32_16x16x32_bf16 v[116:119], v[212:215], v[172:175], v[116:119]
	v_mfma_f32_16x16x32_bf16 v[112:115], v[212:215], v[180:183], v[112:115]
	v_mfma_f32_16x16x32_bf16 v[108:111], v[220:223], v[172:175], v[108:111]
	v_mfma_f32_16x16x32_bf16 v[104:107], v[220:223], v[180:183], v[104:107]
	v_mfma_f32_16x16x32_bf16 v[100:103], v[228:231], v[172:175], v[100:103]
	v_mfma_f32_16x16x32_bf16 v[96:99], v[228:231], v[180:183], v[96:99]
	v_mfma_f32_16x16x32_bf16 v[92:95], v[204:207], v[188:191], v[92:95]
	v_mfma_f32_16x16x32_bf16 v[88:91], v[204:207], v[196:199], v[88:91]
	v_mfma_f32_16x16x32_bf16 v[84:87], v[212:215], v[188:191], v[84:87]
	v_mfma_f32_16x16x32_bf16 v[80:83], v[212:215], v[196:199], v[80:83]
	v_mfma_f32_16x16x32_bf16 v[76:79], v[220:223], v[188:191], v[76:79]
	v_mfma_f32_16x16x32_bf16 v[72:75], v[220:223], v[196:199], v[72:75]
	v_mfma_f32_16x16x32_bf16 v[68:71], v[228:231], v[188:191], v[68:71]
	v_mfma_f32_16x16x32_bf16 v[64:67], v[228:231], v[196:199], v[64:67]
	s_setprio 0
	s_barrier
	s_add_u32 s71, s32, 0x18000
	s_mov_b32 m0, s71
	s_add_u32 s71, s32, 0x1a000
	ds_read_b128 v[200:203], v147 offset:49152
	ds_read_b128 v[204:207], v147 offset:50176
	ds_read_b128 v[208:211], v147 offset:51200
	ds_read_b128 v[212:215], v147 offset:52224
	ds_read_b128 v[216:219], v147 offset:53248
	ds_read_b128 v[220:223], v147 offset:54272
	ds_read_b128 v[224:227], v147 offset:55296
	ds_read_b128 v[228:231], v147 offset:56320
	s_add_u32 s92, s68, s48
	s_addc_u32 s93, s69, s49
	global_load_lds_dwordx4 v138, s[92:93]
	s_mov_b32 m0, s71
	s_add_u32 s71, s32, 0x1c000
	s_add_u32 s96, s68, s48
	s_addc_u32 s97, s69, s49
	global_load_lds_dwordx4 v140, s[96:97]
	s_mov_b32 m0, s71
	s_add_u32 s71, s32, 0x1e000
	s_add_u32 s88, s68, s50
	s_addc_u32 s89, s69, s51
	global_load_lds_dwordx4 v138, s[88:89]
	s_mov_b32 m0, s71
	s_add_u32 s71, s32, 0x8000
	s_add_u32 s90, s68, s50
	s_addc_u32 s91, s69, s51
	global_load_lds_dwordx4 v140, s[90:91]
	s_mov_b32 m0, s71
	s_add_u32 s71, s32, 0xa000
	s_add_u32 s92, s68, s60
	s_addc_u32 s93, s69, s61
	global_load_lds_dwordx4 v142, s[92:93]
	s_mov_b32 m0, s71
	s_nop 0
	s_add_u32 s96, s68, s60
	s_addc_u32 s97, s69, s61
	global_load_lds_dwordx4 v144, s[96:97]
	s_waitcnt vmcnt(6)
	s_waitcnt lgkmcnt(0)
	s_barrier
	s_setprio 1
	s_waitcnt lgkmcnt(0)
	v_mfma_f32_16x16x32_bf16 v[60:63], v[200:203], v[168:171], v[60:63]
	v_mfma_f32_16x16x32_bf16 v[56:59], v[200:203], v[176:179], v[56:59]
	v_mfma_f32_16x16x32_bf16 v[52:55], v[208:211], v[168:171], v[52:55]
	v_mfma_f32_16x16x32_bf16 v[48:51], v[208:211], v[176:179], v[48:51]
	v_mfma_f32_16x16x32_bf16 v[44:47], v[216:219], v[168:171], v[44:47]
	v_mfma_f32_16x16x32_bf16 v[40:43], v[216:219], v[176:179], v[40:43]
	v_mfma_f32_16x16x32_bf16 v[36:39], v[224:227], v[168:171], v[36:39]
	v_mfma_f32_16x16x32_bf16 v[32:35], v[224:227], v[176:179], v[32:35]
	v_mfma_f32_16x16x32_bf16 v[28:31], v[200:203], v[184:187], v[28:31]
	v_mfma_f32_16x16x32_bf16 v[24:27], v[200:203], v[192:195], v[24:27]
	v_mfma_f32_16x16x32_bf16 v[20:23], v[208:211], v[184:187], v[20:23]
	v_mfma_f32_16x16x32_bf16 v[16:19], v[208:211], v[192:195], v[16:19]
	v_mfma_f32_16x16x32_bf16 v[12:15], v[216:219], v[184:187], v[12:15]
	v_mfma_f32_16x16x32_bf16 v[8:11], v[216:219], v[192:195], v[8:11]
	v_mfma_f32_16x16x32_bf16 v[4:7], v[224:227], v[184:187], v[4:7]
	v_mfma_f32_16x16x32_bf16 v[0:3], v[224:227], v[192:195], v[0:3]
	v_mfma_f32_16x16x32_bf16 v[60:63], v[204:207], v[172:175], v[60:63]
	v_mfma_f32_16x16x32_bf16 v[56:59], v[204:207], v[180:183], v[56:59]
	v_mfma_f32_16x16x32_bf16 v[52:55], v[212:215], v[172:175], v[52:55]
	v_mfma_f32_16x16x32_bf16 v[48:51], v[212:215], v[180:183], v[48:51]
	v_mfma_f32_16x16x32_bf16 v[44:47], v[220:223], v[172:175], v[44:47]
	v_mfma_f32_16x16x32_bf16 v[40:43], v[220:223], v[180:183], v[40:43]
	v_mfma_f32_16x16x32_bf16 v[36:39], v[228:231], v[172:175], v[36:39]
	v_mfma_f32_16x16x32_bf16 v[32:35], v[228:231], v[180:183], v[32:35]
	v_mfma_f32_16x16x32_bf16 v[28:31], v[204:207], v[188:191], v[28:31]
	v_mfma_f32_16x16x32_bf16 v[24:27], v[204:207], v[196:199], v[24:27]
	v_mfma_f32_16x16x32_bf16 v[20:23], v[212:215], v[188:191], v[20:23]
	v_mfma_f32_16x16x32_bf16 v[16:19], v[212:215], v[196:199], v[16:19]
	v_mfma_f32_16x16x32_bf16 v[12:15], v[220:223], v[188:191], v[12:15]
	v_mfma_f32_16x16x32_bf16 v[8:11], v[220:223], v[196:199], v[8:11]
	v_mfma_f32_16x16x32_bf16 v[4:7], v[228:231], v[188:191], v[4:7]
	v_mfma_f32_16x16x32_bf16 v[0:3], v[228:231], v[196:199], v[0:3]
	s_setprio 0
	s_barrier
; #define STAGE(Pp, BASE, br, kt) do { const u16* _g = (BASE) + ((long)(br) * K + (long)(kt) * BK); \
;     __builtin_amdgcn_global_load_lds((const unsigned*)(_g + voff0), (unsigned*)((char*)(Pp) + tb16), 16, 0, 0); \
;     __builtin_amdgcn_global_load_lds((const unsigned*)(_g + voff1), (unsigned*)((char*)(Pp) + tb16 + 8192), 16, 0, 0); } while (0)
; #define LDA(dst, b, h) _Pragma("unroll") for (int m = 0; m < 4; ++m) _Pragma("unroll") for (int k = 0; k < 2; ++k) \
;     dst[m][k] = *reinterpret_cast<const bf16x8*>((const char*)shm + aB + (((b) * 2 + (h)) * 16384 + (m * 2 + k) * 1024))
; #define LDB(dst, b, h) _Pragma("unroll") for (int n = 0; n < 2; ++n) _Pragma("unroll") for (int k = 0; k < 2; ++k) \
;     dst[n][k] = *reinterpret_cast<const bf16x8*>((const char*)shm + bB + (((b) * 2 + (h)) * 16384 + (n * 2 + k) * 1024))
; #define WAIT_V(n) asm volatile("s_waitcnt vmcnt(" #n ")" ::: "memory")
; #define WAIT_L(n) asm volatile("s_waitcnt lgkmcnt(" #n ")" ::: "memory")
; #define BAR __builtin_amdgcn_s_barrier()
; #define SCHED __builtin_amdgcn_sched_barrier(0)
; template <int MODE> ...
;     ...
;     }
;     {
;       LDB(B0, 0, 0); LDB(B1, 0, 1); LDA(At, 0, 0); STAGE(SA(1, 1), A, brow + HALF, nt - 1);
;       WAIT_L(0); BAR; MMA2(0, 0, 0, 1); BAR; SCHED;
;       LDA(At, 0, 1); WAIT_V(0); WAIT_L(0); BAR; MMA2(1, 0, 1, 1); BAR; SCHED;
	s_add_i32 s70, s70, 2
	s_add_u32 s68, s68, 0x100
	s_addc_u32 s69, s69, 0
	s_cmp_lt_u32 s70, 60
	s_cbranch_scc1 .LBB0_177
	s_add_u32 s66, s66, 0x1f80
	v_readfirstlane_b32 s68, v165
	s_addc_u32 s67, s67, 0
	s_mov_b32 m0, s68
	v_readfirstlane_b32 s68, v166
	ds_read_b128 v[138:141], v148
	ds_read_b128 v[142:145], v148 offset:1024
	ds_read_b128 v[168:171], v148 offset:2048
	ds_read_b128 v[172:175], v148 offset:3072
	ds_read_b128 v[176:179], v148 offset:16384
	ds_read_b128 v[180:183], v148 offset:17408
	ds_read_b128 v[184:187], v148 offset:18432
	ds_read_b128 v[188:191], v148 offset:19456
	ds_read_b128 v[192:195], v147
	ds_read_b128 v[196:199], v147 offset:1024
	ds_read_b128 v[200:203], v147 offset:2048
	ds_read_b128 v[204:207], v147 offset:3072
	ds_read_b128 v[208:211], v147 offset:4096
	ds_read_b128 v[212:215], v147 offset:5120
	ds_read_b128 v[216:219], v147 offset:6144
	ds_read_b128 v[220:223], v147 offset:7168
	global_load_lds_dwordx4 v134, s[66:67]
	s_mov_b32 m0, s68
	s_nop 0
	global_load_lds_dwordx4 v136, s[66:67]
	s_waitcnt lgkmcnt(0)
	s_barrier
	s_setprio 1
	s_waitcnt lgkmcnt(0)
	v_mfma_f32_16x16x32_bf16 v[124:127], v[192:195], v[138:141], v[124:127]
	v_mfma_f32_16x16x32_bf16 v[120:123], v[192:195], v[168:171], v[120:123]
	v_mfma_f32_16x16x32_bf16 v[116:119], v[200:203], v[138:141], v[116:119]
	v_mfma_f32_16x16x32_bf16 v[112:115], v[200:203], v[168:171], v[112:115]
	v_mfma_f32_16x16x32_bf16 v[108:111], v[208:211], v[138:141], v[108:111]
	v_mfma_f32_16x16x32_bf16 v[104:107], v[208:211], v[168:171], v[104:107]
	v_mfma_f32_16x16x32_bf16 v[100:103], v[216:219], v[138:141], v[100:103]
	v_mfma_f32_16x16x32_bf16 v[96:99], v[216:219], v[168:171], v[96:99]
	v_mfma_f32_16x16x32_bf16 v[92:95], v[192:195], v[176:179], v[92:95]
	v_mfma_f32_16x16x32_bf16 v[88:91], v[192:195], v[184:187], v[88:91]
	v_mfma_f32_16x16x32_bf16 v[84:87], v[200:203], v[176:179], v[84:87]
	v_mfma_f32_16x16x32_bf16 v[80:83], v[200:203], v[184:187], v[80:83]
	v_mfma_f32_16x16x32_bf16 v[76:79], v[208:211], v[176:179], v[76:79]
	v_mfma_f32_16x16x32_bf16 v[72:75], v[208:211], v[184:187], v[72:75]
	v_mfma_f32_16x16x32_bf16 v[68:71], v[216:219], v[176:179], v[68:71]
	v_mfma_f32_16x16x32_bf16 v[64:67], v[216:219], v[184:187], v[64:67]
	v_mfma_f32_16x16x32_bf16 v[124:127], v[196:199], v[142:145], v[124:127]
	v_mfma_f32_16x16x32_bf16 v[120:123], v[196:199], v[172:175], v[120:123]
	v_mfma_f32_16x16x32_bf16 v[116:119], v[204:207], v[142:145], v[116:119]
	v_mfma_f32_16x16x32_bf16 v[112:115], v[204:207], v[172:175], v[112:115]
	v_mfma_f32_16x16x32_bf16 v[108:111], v[212:215], v[142:145], v[108:111]
	v_mfma_f32_16x16x32_bf16 v[104:107], v[212:215], v[172:175], v[104:107]
	v_mfma_f32_16x16x32_bf16 v[100:103], v[220:223], v[142:145], v[100:103]
	v_mfma_f32_16x16x32_bf16 v[96:99], v[220:223], v[172:175], v[96:99]
	v_mfma_f32_16x16x32_bf16 v[92:95], v[196:199], v[180:183], v[92:95]
	v_mfma_f32_16x16x32_bf16 v[88:91], v[196:199], v[188:191], v[88:91]
	v_mfma_f32_16x16x32_bf16 v[84:87], v[204:207], v[180:183], v[84:87]
	v_mfma_f32_16x16x32_bf16 v[80:83], v[204:207], v[188:191], v[80:83]
	v_mfma_f32_16x16x32_bf16 v[76:79], v[212:215], v[180:183], v[76:79]
	v_mfma_f32_16x16x32_bf16 v[72:75], v[212:215], v[188:191], v[72:75]
	v_mfma_f32_16x16x32_bf16 v[68:71], v[220:223], v[180:183], v[68:71]
	v_mfma_f32_16x16x32_bf16 v[64:67], v[220:223], v[188:191], v[64:67]
	s_setprio 0
	s_barrier
	ds_read_b128 v[192:195], v147 offset:16384
	ds_read_b128 v[196:199], v147 offset:17408
	ds_read_b128 v[200:203], v147 offset:18432
	ds_read_b128 v[204:207], v147 offset:19456
	ds_read_b128 v[208:211], v147 offset:20480
	ds_read_b128 v[212:215], v147 offset:21504
	ds_read_b128 v[216:219], v147 offset:22528
	ds_read_b128 v[220:223], v147 offset:23552
	s_waitcnt vmcnt(0)
	s_waitcnt lgkmcnt(0)
	s_barrier
	s_setprio 1
	s_waitcnt lgkmcnt(0)
	v_mfma_f32_16x16x32_bf16 v[56:59], v[192:195], v[168:171], v[56:59]
	v_mfma_f32_16x16x32_bf16 v[52:55], v[200:203], v[138:141], v[52:55]
	v_mfma_f32_16x16x32_bf16 v[48:51], v[200:203], v[168:171], v[48:51]
	v_mfma_f32_16x16x32_bf16 v[44:47], v[208:211], v[138:141], v[44:47]
	v_mfma_f32_16x16x32_bf16 v[40:43], v[208:211], v[168:171], v[40:43]
	v_mfma_f32_16x16x32_bf16 v[36:39], v[216:219], v[138:141], v[36:39]
	v_mfma_f32_16x16x32_bf16 v[32:35], v[216:219], v[168:171], v[32:35]
	v_mfma_f32_16x16x32_bf16 v[28:31], v[192:195], v[176:179], v[28:31]
	v_mfma_f32_16x16x32_bf16 v[24:27], v[192:195], v[184:187], v[24:27]
	v_mfma_f32_16x16x32_bf16 v[20:23], v[200:203], v[176:179], v[20:23]
	v_mfma_f32_16x16x32_bf16 v[16:19], v[200:203], v[184:187], v[16:19]
	v_mfma_f32_16x16x32_bf16 v[12:15], v[208:211], v[176:179], v[12:15]
	v_mfma_f32_16x16x32_bf16 v[8:11], v[208:211], v[184:187], v[8:11]
	v_mfma_f32_16x16x32_bf16 v[4:7], v[216:219], v[176:179], v[4:7]
	v_mfma_f32_16x16x32_bf16 v[0:3], v[216:219], v[184:187], v[0:3]
	v_mfma_f32_16x16x32_bf16 v[60:63], v[192:195], v[138:141], v[60:63]
	v_mfma_f32_16x16x32_bf16 v[56:59], v[196:199], v[172:175], v[56:59]
	v_mfma_f32_16x16x32_bf16 v[52:55], v[204:207], v[142:145], v[52:55]
	v_mfma_f32_16x16x32_bf16 v[48:51], v[204:207], v[172:175], v[48:51]
	v_mfma_f32_16x16x32_bf16 v[44:47], v[212:215], v[142:145], v[44:47]
	v_mfma_f32_16x16x32_bf16 v[40:43], v[212:215], v[172:175], v[40:43]
	v_mfma_f32_16x16x32_bf16 v[36:39], v[220:223], v[142:145], v[36:39]
	v_mfma_f32_16x16x32_bf16 v[32:35], v[220:223], v[172:175], v[32:35]
	v_mfma_f32_16x16x32_bf16 v[28:31], v[196:199], v[180:183], v[28:31]
	v_mfma_f32_16x16x32_bf16 v[24:27], v[196:199], v[188:191], v[24:27]
	v_mfma_f32_16x16x32_bf16 v[20:23], v[204:207], v[180:183], v[20:23]
	v_mfma_f32_16x16x32_bf16 v[16:19], v[204:207], v[188:191], v[16:19]
	v_mfma_f32_16x16x32_bf16 v[12:15], v[212:215], v[180:183], v[12:15]
	v_mfma_f32_16x16x32_bf16 v[8:11], v[212:215], v[188:191], v[8:11]
	v_mfma_f32_16x16x32_bf16 v[4:7], v[220:223], v[180:183], v[4:7]
	v_mfma_f32_16x16x32_bf16 v[0:3], v[220:223], v[188:191], v[0:3]
	v_mfma_f32_16x16x32_bf16 v[224:227], v[196:199], v[142:145], v[60:63]
	s_setprio 0
	s_barrier
; #define LDA(dst, b, h) _Pragma("unroll") for (int m = 0; m < 4; ++m) _Pragma("unroll") for (int k = 0; k < 2; ++k) \
;     dst[m][k] = *reinterpret_cast<const bf16x8*>((const char*)shm + aB + (((b) * 2 + (h)) * 16384 + (m * 2 + k) * 1024))
; #define LDB(dst, b, h) _Pragma("unroll") for (int n = 0; n < 2; ++n) _Pragma("unroll") for (int k = 0; k < 2; ++k) \
;     dst[n][k] = *reinterpret_cast<const bf16x8*>((const char*)shm + bB + (((b) * 2 + (h)) * 16384 + (n * 2 + k) * 1024))
; #define WAIT_L(n) asm volatile("s_waitcnt lgkmcnt(" #n ")" ::: "memory")
; #define BAR __builtin_amdgcn_s_barrier()
; #define SCHED __builtin_amdgcn_sched_barrier(0)
; template <int MODE> ...
;     ...
;       LDB(B0, 1, 0); LDB(B1, 1, 1); LDA(At, 1, 0); WAIT_L(0); BAR; MMA2(0, 0, 0, 1); BAR; SCHED;
;       LDA(At, 1, 1); WAIT_L(0); BAR; MMA2(1, 0, 1, 1); BAR; SCHED;
;     }
;     ...
;     if (wr == 0) BAR;
	ds_read_b128 v[138:141], v148 offset:32768
	ds_read_b128 v[142:145], v148 offset:33792
	ds_read_b128 v[168:171], v148 offset:34816
	ds_read_b128 v[172:175], v148 offset:35840
	ds_read_b128 v[176:179], v148 offset:49152
	ds_read_b128 v[180:183], v148 offset:50176
	ds_read_b128 v[184:187], v148 offset:51200
	ds_read_b128 v[188:191], v148 offset:52224
	ds_read_b128 v[60:63], v147 offset:32768
	ds_read_b128 v[192:195], v147 offset:33792
	ds_read_b128 v[196:199], v147 offset:34816
	ds_read_b128 v[200:203], v147 offset:35840
	ds_read_b128 v[204:207], v147 offset:36864
	ds_read_b128 v[208:211], v147 offset:37888
	ds_read_b128 v[212:215], v147 offset:38912
	ds_read_b128 v[216:219], v147 offset:39936
	s_waitcnt lgkmcnt(0)
	s_barrier
	s_setprio 1
	s_waitcnt lgkmcnt(0)
	v_mfma_f32_16x16x32_bf16 v[124:127], v[60:63], v[138:141], v[124:127]
	v_mfma_f32_16x16x32_bf16 v[120:123], v[60:63], v[168:171], v[120:123]
	v_mfma_f32_16x16x32_bf16 v[92:95], v[60:63], v[176:179], v[92:95]
	v_mfma_f32_16x16x32_bf16 v[60:63], v[60:63], v[184:187], v[88:91]
	v_mfma_f32_16x16x32_bf16 v[88:91], v[192:195], v[188:191], v[60:63]
	v_mfma_f32_16x16x32_bf16 v[60:63], v[196:199], v[176:179], v[84:87]
	v_mfma_f32_16x16x32_bf16 v[84:87], v[200:203], v[180:183], v[60:63]
	v_mfma_f32_16x16x32_bf16 v[60:63], v[196:199], v[184:187], v[80:83]
	v_mfma_f32_16x16x32_bf16 v[80:83], v[200:203], v[188:191], v[60:63]
	v_mfma_f32_16x16x32_bf16 v[60:63], v[204:207], v[176:179], v[76:79]
	v_mfma_f32_16x16x32_bf16 v[76:79], v[208:211], v[180:183], v[60:63]
	v_mfma_f32_16x16x32_bf16 v[60:63], v[204:207], v[184:187], v[72:75]
	v_mfma_f32_16x16x32_bf16 v[72:75], v[208:211], v[188:191], v[60:63]
	v_mfma_f32_16x16x32_bf16 v[60:63], v[212:215], v[176:179], v[68:71]
	v_mfma_f32_16x16x32_bf16 v[116:119], v[196:199], v[138:141], v[116:119]
	v_mfma_f32_16x16x32_bf16 v[112:115], v[196:199], v[168:171], v[112:115]
	v_mfma_f32_16x16x32_bf16 v[108:111], v[204:207], v[138:141], v[108:111]
	v_mfma_f32_16x16x32_bf16 v[104:107], v[204:207], v[168:171], v[104:107]
	v_mfma_f32_16x16x32_bf16 v[100:103], v[212:215], v[138:141], v[100:103]
	v_mfma_f32_16x16x32_bf16 v[96:99], v[212:215], v[168:171], v[96:99]
	v_mfma_f32_16x16x32_bf16 v[68:71], v[216:219], v[180:183], v[60:63]
	v_mfma_f32_16x16x32_bf16 v[60:63], v[212:215], v[184:187], v[64:67]
	v_mfma_f32_16x16x32_bf16 v[124:127], v[192:195], v[142:145], v[124:127]
	v_mfma_f32_16x16x32_bf16 v[120:123], v[192:195], v[172:175], v[120:123]
	v_mfma_f32_16x16x32_bf16 v[116:119], v[200:203], v[142:145], v[116:119]
	v_mfma_f32_16x16x32_bf16 v[112:115], v[200:203], v[172:175], v[112:115]
	v_mfma_f32_16x16x32_bf16 v[108:111], v[208:211], v[142:145], v[108:111]
	v_mfma_f32_16x16x32_bf16 v[104:107], v[208:211], v[172:175], v[104:107]
	v_mfma_f32_16x16x32_bf16 v[100:103], v[216:219], v[142:145], v[100:103]
	v_mfma_f32_16x16x32_bf16 v[96:99], v[216:219], v[172:175], v[96:99]
	v_mfma_f32_16x16x32_bf16 v[92:95], v[192:195], v[180:183], v[92:95]
	v_mfma_f32_16x16x32_bf16 v[60:63], v[216:219], v[188:191], v[60:63]
	s_setprio 0
	s_barrier
	ds_read_b128 v[192:195], v147 offset:49152
	ds_read_b128 v[196:199], v147 offset:50176
	ds_read_b128 v[200:203], v147 offset:51200
	ds_read_b128 v[204:207], v147 offset:52224
	ds_read_b128 v[208:211], v147 offset:53248
	ds_read_b128 v[212:215], v147 offset:54272
	ds_read_b128 v[216:219], v147 offset:55296
	ds_read_b128 v[220:223], v147 offset:56320
	s_waitcnt lgkmcnt(0)
	s_barrier
	s_setprio 1
	s_waitcnt lgkmcnt(0)
	v_mfma_f32_16x16x32_bf16 v[64:67], v[192:195], v[138:141], v[224:227]
	v_mfma_f32_16x16x32_bf16 v[56:59], v[192:195], v[168:171], v[56:59]
	v_mfma_f32_16x16x32_bf16 v[52:55], v[200:203], v[138:141], v[52:55]
	v_mfma_f32_16x16x32_bf16 v[48:51], v[200:203], v[168:171], v[48:51]
	v_mfma_f32_16x16x32_bf16 v[44:47], v[208:211], v[138:141], v[44:47]
	v_mfma_f32_16x16x32_bf16 v[40:43], v[208:211], v[168:171], v[40:43]
	v_mfma_f32_16x16x32_bf16 v[36:39], v[216:219], v[138:141], v[36:39]
	v_mfma_f32_16x16x32_bf16 v[32:35], v[216:219], v[168:171], v[32:35]
	v_mfma_f32_16x16x32_bf16 v[28:31], v[192:195], v[176:179], v[28:31]
	v_mfma_f32_16x16x32_bf16 v[24:27], v[192:195], v[184:187], v[24:27]
	v_mfma_f32_16x16x32_bf16 v[20:23], v[200:203], v[176:179], v[20:23]
	v_mfma_f32_16x16x32_bf16 v[16:19], v[200:203], v[184:187], v[16:19]
	v_mfma_f32_16x16x32_bf16 v[12:15], v[208:211], v[176:179], v[12:15]
	v_mfma_f32_16x16x32_bf16 v[8:11], v[208:211], v[184:187], v[8:11]
	v_mfma_f32_16x16x32_bf16 v[4:7], v[216:219], v[176:179], v[4:7]
	v_mfma_f32_16x16x32_bf16 v[0:3], v[216:219], v[184:187], v[0:3]
	v_mfma_f32_16x16x32_bf16 v[64:67], v[196:199], v[142:145], v[64:67]
	v_mfma_f32_16x16x32_bf16 v[56:59], v[196:199], v[172:175], v[56:59]
	v_mfma_f32_16x16x32_bf16 v[52:55], v[204:207], v[142:145], v[52:55]
	v_mfma_f32_16x16x32_bf16 v[48:51], v[204:207], v[172:175], v[48:51]
	v_mfma_f32_16x16x32_bf16 v[44:47], v[212:215], v[142:145], v[44:47]
	v_mfma_f32_16x16x32_bf16 v[40:43], v[212:215], v[172:175], v[40:43]
	v_mfma_f32_16x16x32_bf16 v[36:39], v[220:223], v[142:145], v[36:39]
	v_mfma_f32_16x16x32_bf16 v[32:35], v[220:223], v[172:175], v[32:35]
	v_mfma_f32_16x16x32_bf16 v[28:31], v[196:199], v[180:183], v[28:31]
	v_mfma_f32_16x16x32_bf16 v[24:27], v[196:199], v[188:191], v[24:27]
	v_mfma_f32_16x16x32_bf16 v[20:23], v[204:207], v[180:183], v[20:23]
	v_mfma_f32_16x16x32_bf16 v[16:19], v[204:207], v[188:191], v[16:19]
	v_mfma_f32_16x16x32_bf16 v[12:15], v[212:215], v[180:183], v[12:15]
	v_mfma_f32_16x16x32_bf16 v[8:11], v[212:215], v[188:191], v[8:11]
	v_mfma_f32_16x16x32_bf16 v[4:7], v[220:223], v[180:183], v[4:7]
	v_mfma_f32_16x16x32_bf16 v[0:3], v[220:223], v[188:191], v[0:3]
	s_setprio 0
	s_barrier
	s_and_saveexec_b64 s[66:67], s[6:7]
	s_cbranch_execz .LBB0_180
	s_barrier

; #define STAGE(Pp, BASE, br, kt) do { const u16* _g = (BASE) + ((long)(br) * K + (long)(kt) * BK); \
;     __builtin_amdgcn_global_load_lds((const unsigned*)(_g + voff0), (unsigned*)((char*)(Pp) + tb16), 16, 0, 0); \
;     __builtin_amdgcn_global_load_lds((const unsigned*)(_g + voff1), (unsigned*)((char*)(Pp) + tb16 + 8192), 16, 0, 0); } while (0)
; #define LDA(dst, b, h) _Pragma("unroll") for (int m = 0; m < 4; ++m) _Pragma("unroll") for (int k = 0; k < 2; ++k) \
;     dst[m][k] = *reinterpret_cast<const bf16x8*>((const char*)shm + aB + (((b) * 2 + (h)) * 16384 + (m * 2 + k) * 1024))
; #define LDB(dst, b, h) _Pragma("unroll") for (int n = 0; n < 2; ++n) _Pragma("unroll") for (int k = 0; k < 2; ++k) \
;     dst[n][k] = *reinterpret_cast<const bf16x8*>((const char*)shm + bB + (((b) * 2 + (h)) * 16384 + (n * 2 + k) * 1024))
; #define WAIT_V(n) asm volatile("s_waitcnt vmcnt(" #n ")" ::: "memory")
; #define WAIT_L(n) asm volatile("s_waitcnt lgkmcnt(" #n ")" ::: "memory")
; #define BAR __builtin_amdgcn_s_barrier()
; #define SCHED __builtin_amdgcn_sched_barrier(0)
; template <int MODE> ...
;     ...
;     f32x4 acc[2][2][4][2] = {};
;     bf16x8 At[4][2], B0[2][2], B1[2][2];
;     ...
;     STAGE(SB(0, 0), Bt, bcol, 0); STAGE(SA(0, 0), A, brow, 0); STAGE(SB(0, 1), Bt, bcol + HALF, 0); STAGE(SA(0, 1), A, brow + HALF, 0);
;     STAGE(SB(1, 0), Bt, bcol, 1); STAGE(SA(1, 0), A, brow, 1); STAGE(SB(1, 1), Bt, bcol + HALF, 1);
;     WAIT_V(6);
;     if (wr == 1) BAR;
;     BAR;
;     for (int t = 0; t < nt - 2; t += 2) {
;       LDB(B0, 0, 0); LDB(B1, 0, 1); LDA(At, 0, 0); STAGE(SA(1, 1), A, brow + HALF, t + 1);
;       WAIT_L(0); BAR; MMA2(0, 0, 0, 1); BAR; SCHED;
.LBB0_485:
	s_or_b64 exec, exec, s[76:77]
	v_mov_b32_e32 v0, 0
	v_lshl_add_u64 v[136:137], v[130:131], 0, s[72:73]
	v_lshl_add_u64 v[138:139], v[128:129], 0, s[72:73]
	v_lshl_add_u64 v[140:141], v[130:131], 0, s[74:75]
	v_lshl_add_u64 v[142:143], v[128:129], 0, s[74:75]
	s_mov_b32 s63, -2
	s_mov_b64 s[72:73], s[56:57]
	v_mov_b32_e32 v1, v0
	v_mov_b32_e32 v2, v0
	v_mov_b32_e32 v3, v0
	v_mov_b32_e32 v4, v0
	v_mov_b32_e32 v5, v0
	v_mov_b32_e32 v6, v0
	v_mov_b32_e32 v7, v0
	v_mov_b32_e32 v8, v0
	v_mov_b32_e32 v9, v0
	v_mov_b32_e32 v10, v0
	v_mov_b32_e32 v11, v0
	v_mov_b32_e32 v12, v0
	v_mov_b32_e32 v13, v0
	v_mov_b32_e32 v14, v0
	v_mov_b32_e32 v15, v0
	v_mov_b32_e32 v16, v0
	v_mov_b32_e32 v17, v0
	v_mov_b32_e32 v18, v0
	v_mov_b32_e32 v19, v0
	v_mov_b32_e32 v20, v0
	v_mov_b32_e32 v21, v0
	v_mov_b32_e32 v22, v0
	v_mov_b32_e32 v23, v0
	v_mov_b32_e32 v24, v0
	v_mov_b32_e32 v25, v0
	v_mov_b32_e32 v26, v0
	v_mov_b32_e32 v27, v0
	v_mov_b32_e32 v28, v0
	v_mov_b32_e32 v29, v0
	v_mov_b32_e32 v30, v0
	v_mov_b32_e32 v31, v0
	v_mov_b32_e32 v32, v0
	v_mov_b32_e32 v33, v0
	v_mov_b32_e32 v34, v0
	v_mov_b32_e32 v35, v0
	v_mov_b32_e32 v36, v0
	v_mov_b32_e32 v37, v0
	v_mov_b32_e32 v38, v0
	v_mov_b32_e32 v39, v0
	v_mov_b32_e32 v40, v0
	v_mov_b32_e32 v41, v0
	v_mov_b32_e32 v42, v0
	v_mov_b32_e32 v43, v0
	v_mov_b32_e32 v44, v0
	v_mov_b32_e32 v45, v0
	v_mov_b32_e32 v46, v0
	v_mov_b32_e32 v47, v0
	v_mov_b32_e32 v48, v0
	v_mov_b32_e32 v49, v0
	v_mov_b32_e32 v50, v0
	v_mov_b32_e32 v51, v0
	v_mov_b32_e32 v52, v0
	v_mov_b32_e32 v53, v0
	v_mov_b32_e32 v54, v0
	v_mov_b32_e32 v55, v0
	v_mov_b32_e32 v56, v0
	v_mov_b32_e32 v57, v0
	v_mov_b32_e32 v58, v0
	v_mov_b32_e32 v59, v0
	v_mov_b32_e32 v60, v0
	v_mov_b32_e32 v61, v0
	v_mov_b32_e32 v62, v0
	v_mov_b32_e32 v63, v0
	v_mov_b32_e32 v64, v0
	v_mov_b32_e32 v65, v0
	v_mov_b32_e32 v66, v0
	v_mov_b32_e32 v67, v0
	v_mov_b32_e32 v68, v0
	v_mov_b32_e32 v69, v0
	v_mov_b32_e32 v70, v0
	v_mov_b32_e32 v71, v0
	v_mov_b32_e32 v72, v0
	v_mov_b32_e32 v73, v0
	v_mov_b32_e32 v74, v0
	v_mov_b32_e32 v75, v0
	v_mov_b32_e32 v76, v0
	v_mov_b32_e32 v77, v0
	v_mov_b32_e32 v78, v0
	v_mov_b32_e32 v79, v0
	v_mov_b32_e32 v80, v0
	v_mov_b32_e32 v81, v0
	v_mov_b32_e32 v82, v0
	v_mov_b32_e32 v83, v0
	v_mov_b32_e32 v84, v0
	v_mov_b32_e32 v85, v0
	v_mov_b32_e32 v86, v0
	v_mov_b32_e32 v87, v0
	v_mov_b32_e32 v88, v0
	v_mov_b32_e32 v89, v0
	v_mov_b32_e32 v90, v0
	v_mov_b32_e32 v91, v0
	v_mov_b32_e32 v92, v0
	v_mov_b32_e32 v93, v0
	v_mov_b32_e32 v94, v0
	v_mov_b32_e32 v95, v0
	v_mov_b32_e32 v96, v0
	v_mov_b32_e32 v97, v0
	v_mov_b32_e32 v98, v0
	v_mov_b32_e32 v99, v0
	v_mov_b32_e32 v100, v0
	v_mov_b32_e32 v101, v0
	v_mov_b32_e32 v102, v0
	v_mov_b32_e32 v103, v0
	v_mov_b32_e32 v104, v0
	v_mov_b32_e32 v105, v0
	v_mov_b32_e32 v106, v0
	v_mov_b32_e32 v107, v0
	v_mov_b32_e32 v108, v0
	v_mov_b32_e32 v109, v0
	v_mov_b32_e32 v110, v0
	v_mov_b32_e32 v111, v0
	v_mov_b32_e32 v112, v0
	v_mov_b32_e32 v113, v0
	v_mov_b32_e32 v114, v0
	v_mov_b32_e32 v115, v0
	v_mov_b32_e32 v116, v0
	v_mov_b32_e32 v117, v0
	v_mov_b32_e32 v118, v0
	v_mov_b32_e32 v119, v0
	v_mov_b32_e32 v120, v0
	v_mov_b32_e32 v121, v0
	v_mov_b32_e32 v122, v0
	v_mov_b32_e32 v123, v0
	v_mov_b32_e32 v124, v0
	v_mov_b32_e32 v125, v0
	v_mov_b32_e32 v126, v0
	v_mov_b32_e32 v127, v0
	v_readfirstlane_b32 s32, v146
	s_barrier
.LBB0_486:
	s_add_u32 s74, s32, 0xc000
	s_mov_b32 m0, s74
	ds_read_b128 v[166:169], v145
	ds_read_b128 v[170:173], v145 offset:1024
	ds_read_b128 v[174:177], v145 offset:2048
	ds_read_b128 v[178:181], v145 offset:3072
	ds_read_b128 v[182:185], v145 offset:16384
	ds_read_b128 v[186:189], v145 offset:17408
	ds_read_b128 v[190:193], v145 offset:18432
	ds_read_b128 v[194:197], v145 offset:19456
	ds_read_b128 v[198:201], v144
	ds_read_b128 v[202:205], v144 offset:1024
	ds_read_b128 v[206:209], v144 offset:2048
	ds_read_b128 v[210:213], v144 offset:3072
	ds_read_b128 v[214:217], v144 offset:4096
	ds_read_b128 v[218:221], v144 offset:5120
	ds_read_b128 v[222:225], v144 offset:6144
	ds_read_b128 v[226:229], v144 offset:7168
	s_add_u32 s88, s72, s16
	s_addc_u32 s89, s73, s17
	global_load_lds_dwordx4 v140, s[88:89]
	s_add_u32 s74, s32, 0xe000
	s_mov_b32 m0, s74
	s_nop 0
	s_add_u32 s90, s72, s16
	s_addc_u32 s91, s73, s17
	global_load_lds_dwordx4 v142, s[90:91]
	s_waitcnt lgkmcnt(0)
	s_barrier
	s_setprio 1
	s_waitcnt lgkmcnt(0)
	v_mfma_f32_16x16x32_bf16 v[124:127], v[198:201], v[166:169], v[124:127]
	v_mfma_f32_16x16x32_bf16 v[120:123], v[198:201], v[174:177], v[120:123]
	v_mfma_f32_16x16x32_bf16 v[116:119], v[206:209], v[166:169], v[116:119]
	v_mfma_f32_16x16x32_bf16 v[112:115], v[206:209], v[174:177], v[112:115]
	v_mfma_f32_16x16x32_bf16 v[108:111], v[214:217], v[166:169], v[108:111]
	v_mfma_f32_16x16x32_bf16 v[104:107], v[214:217], v[174:177], v[104:107]
	v_mfma_f32_16x16x32_bf16 v[100:103], v[222:225], v[166:169], v[100:103]
	v_mfma_f32_16x16x32_bf16 v[96:99], v[222:225], v[174:177], v[96:99]
	v_mfma_f32_16x16x32_bf16 v[92:95], v[198:201], v[182:185], v[92:95]
	v_mfma_f32_16x16x32_bf16 v[88:91], v[198:201], v[190:193], v[88:91]
	v_mfma_f32_16x16x32_bf16 v[84:87], v[206:209], v[182:185], v[84:87]
	v_mfma_f32_16x16x32_bf16 v[80:83], v[206:209], v[190:193], v[80:83]
	v_mfma_f32_16x16x32_bf16 v[76:79], v[214:217], v[182:185], v[76:79]
	v_mfma_f32_16x16x32_bf16 v[72:75], v[214:217], v[190:193], v[72:75]
	v_mfma_f32_16x16x32_bf16 v[68:71], v[222:225], v[182:185], v[68:71]
	v_mfma_f32_16x16x32_bf16 v[64:67], v[222:225], v[190:193], v[64:67]
	v_mfma_f32_16x16x32_bf16 v[124:127], v[202:205], v[170:173], v[124:127]
	v_mfma_f32_16x16x32_bf16 v[120:123], v[202:205], v[178:181], v[120:123]
	v_mfma_f32_16x16x32_bf16 v[116:119], v[210:213], v[170:173], v[116:119]
	v_mfma_f32_16x16x32_bf16 v[112:115], v[210:213], v[178:181], v[112:115]
	v_mfma_f32_16x16x32_bf16 v[108:111], v[218:221], v[170:173], v[108:111]
	v_mfma_f32_16x16x32_bf16 v[104:107], v[218:221], v[178:181], v[104:107]
	v_mfma_f32_16x16x32_bf16 v[100:103], v[226:229], v[170:173], v[100:103]
	v_mfma_f32_16x16x32_bf16 v[96:99], v[226:229], v[178:181], v[96:99]
	v_mfma_f32_16x16x32_bf16 v[92:95], v[202:205], v[186:189], v[92:95]
	v_mfma_f32_16x16x32_bf16 v[88:91], v[202:205], v[194:197], v[88:91]
	v_mfma_f32_16x16x32_bf16 v[84:87], v[210:213], v[186:189], v[84:87]
	v_mfma_f32_16x16x32_bf16 v[80:83], v[210:213], v[194:197], v[80:83]
	v_mfma_f32_16x16x32_bf16 v[76:79], v[218:221], v[186:189], v[76:79]
	v_mfma_f32_16x16x32_bf16 v[72:75], v[218:221], v[194:197], v[72:75]
	v_mfma_f32_16x16x32_bf16 v[68:71], v[226:229], v[186:189], v[68:71]
	v_mfma_f32_16x16x32_bf16 v[64:67], v[226:229], v[194:197], v[64:67]
	s_setprio 0
	s_barrier
; #define STAGE(Pp, BASE, br, kt) do { const u16* _g = (BASE) + ((long)(br) * K + (long)(kt) * BK); \
;     __builtin_amdgcn_global_load_lds((const unsigned*)(_g + voff0), (unsigned*)((char*)(Pp) + tb16), 16, 0, 0); \
;     __builtin_amdgcn_global_load_lds((const unsigned*)(_g + voff1), (unsigned*)((char*)(Pp) + tb16 + 8192), 16, 0, 0); } while (0)
; #define LDA(dst, b, h) _Pragma("unroll") for (int m = 0; m < 4; ++m) _Pragma("unroll") for (int k = 0; k < 2; ++k) \
;     dst[m][k] = *reinterpret_cast<const bf16x8*>((const char*)shm + aB + (((b) * 2 + (h)) * 16384 + (m * 2 + k) * 1024))
; #define LDB(dst, b, h) _Pragma("unroll") for (int n = 0; n < 2; ++n) _Pragma("unroll") for (int k = 0; k < 2; ++k) \
;     dst[n][k] = *reinterpret_cast<const bf16x8*>((const char*)shm + bB + (((b) * 2 + (h)) * 16384 + (n * 2 + k) * 1024))
; #define WAIT_V(n) asm volatile("s_waitcnt vmcnt(" #n ")" ::: "memory")
; #define WAIT_L(n) asm volatile("s_waitcnt lgkmcnt(" #n ")" ::: "memory")
; #define BAR __builtin_amdgcn_s_barrier()
; #define SCHED __builtin_amdgcn_sched_barrier(0)
; template <int MODE> ...
;     ...
;       LDA(At, 0, 1); STAGE(SB(0, 0), Bt, bcol, t + 2); STAGE(SB(0, 1), Bt, bcol + HALF, t + 2); STAGE(SA(0, 0), A, brow, t + 2);
;       WAIT_V(6); WAIT_L(0); BAR; MMA2(1, 0, 1, 1); BAR; SCHED;
;       LDB(B0, 1, 0); LDB(B1, 1, 1); LDA(At, 1, 0); STAGE(SA(0, 1), A, brow + HALF, t + 2);
	s_add_u32 s74, s32, 0x10000
	s_mov_b32 m0, s74
	ds_read_b128 v[198:201], v144 offset:16384
	ds_read_b128 v[202:205], v144 offset:17408
	ds_read_b128 v[206:209], v144 offset:18432
	ds_read_b128 v[210:213], v144 offset:19456
	ds_read_b128 v[214:217], v144 offset:20480
	ds_read_b128 v[218:221], v144 offset:21504
	ds_read_b128 v[222:225], v144 offset:22528
	ds_read_b128 v[226:229], v144 offset:23552
	s_add_u32 s92, s72, s38
	s_addc_u32 s93, s73, s39
	global_load_lds_dwordx4 v136, s[92:93]
	s_add_u32 s74, s32, 0x12000
	s_mov_b32 m0, s74
	s_add_u32 s74, s32, 0x14000
	s_add_u32 s96, s72, s38
	s_addc_u32 s97, s73, s39
	global_load_lds_dwordx4 v138, s[96:97]
	s_mov_b32 m0, s74
	s_add_u32 s74, s32, 0x16000
	s_add_u32 s88, s72, s40
	s_addc_u32 s89, s73, s41
	global_load_lds_dwordx4 v136, s[88:89]
	s_mov_b32 m0, s74
	s_mov_b32 s74, s32
	s_add_u32 s90, s72, s40
	s_addc_u32 s91, s73, s41
	global_load_lds_dwordx4 v138, s[90:91]
	s_mov_b32 m0, s74
	s_add_u32 s74, s32, 0x2000
	s_add_u32 s92, s72, s42
	s_addc_u32 s93, s73, s43
	global_load_lds_dwordx4 v140, s[92:93]
	s_mov_b32 m0, s74
	s_nop 0
	s_add_u32 s96, s72, s42
	s_addc_u32 s97, s73, s43
	global_load_lds_dwordx4 v142, s[96:97]
	s_waitcnt vmcnt(6)
	s_waitcnt lgkmcnt(0)
	s_barrier
	s_setprio 1
	s_waitcnt lgkmcnt(0)
	v_mfma_f32_16x16x32_bf16 v[60:63], v[198:201], v[166:169], v[60:63]
	v_mfma_f32_16x16x32_bf16 v[56:59], v[198:201], v[174:177], v[56:59]
	v_mfma_f32_16x16x32_bf16 v[52:55], v[206:209], v[166:169], v[52:55]
	v_mfma_f32_16x16x32_bf16 v[48:51], v[206:209], v[174:177], v[48:51]
	v_mfma_f32_16x16x32_bf16 v[44:47], v[214:217], v[166:169], v[44:47]
	v_mfma_f32_16x16x32_bf16 v[40:43], v[214:217], v[174:177], v[40:43]
	v_mfma_f32_16x16x32_bf16 v[36:39], v[222:225], v[166:169], v[36:39]
	v_mfma_f32_16x16x32_bf16 v[32:35], v[222:225], v[174:177], v[32:35]
	v_mfma_f32_16x16x32_bf16 v[28:31], v[198:201], v[182:185], v[28:31]
	v_mfma_f32_16x16x32_bf16 v[24:27], v[198:201], v[190:193], v[24:27]
	v_mfma_f32_16x16x32_bf16 v[20:23], v[206:209], v[182:185], v[20:23]
	v_mfma_f32_16x16x32_bf16 v[16:19], v[206:209], v[190:193], v[16:19]
	v_mfma_f32_16x16x32_bf16 v[12:15], v[214:217], v[182:185], v[12:15]
	v_mfma_f32_16x16x32_bf16 v[8:11], v[214:217], v[190:193], v[8:11]
	v_mfma_f32_16x16x32_bf16 v[4:7], v[222:225], v[182:185], v[4:7]
	v_mfma_f32_16x16x32_bf16 v[0:3], v[222:225], v[190:193], v[0:3]
	v_mfma_f32_16x16x32_bf16 v[60:63], v[202:205], v[170:173], v[60:63]
	v_mfma_f32_16x16x32_bf16 v[56:59], v[202:205], v[178:181], v[56:59]
	v_mfma_f32_16x16x32_bf16 v[52:55], v[210:213], v[170:173], v[52:55]
	v_mfma_f32_16x16x32_bf16 v[48:51], v[210:213], v[178:181], v[48:51]
	v_mfma_f32_16x16x32_bf16 v[44:47], v[218:221], v[170:173], v[44:47]
	v_mfma_f32_16x16x32_bf16 v[40:43], v[218:221], v[178:181], v[40:43]
	v_mfma_f32_16x16x32_bf16 v[36:39], v[226:229], v[170:173], v[36:39]
	v_mfma_f32_16x16x32_bf16 v[32:35], v[226:229], v[178:181], v[32:35]
	v_mfma_f32_16x16x32_bf16 v[28:31], v[202:205], v[186:189], v[28:31]
	v_mfma_f32_16x16x32_bf16 v[24:27], v[202:205], v[194:197], v[24:27]
	v_mfma_f32_16x16x32_bf16 v[20:23], v[210:213], v[186:189], v[20:23]
	v_mfma_f32_16x16x32_bf16 v[16:19], v[210:213], v[194:197], v[16:19]
	v_mfma_f32_16x16x32_bf16 v[12:15], v[218:221], v[186:189], v[12:15]
	v_mfma_f32_16x16x32_bf16 v[8:11], v[218:221], v[194:197], v[8:11]
	v_mfma_f32_16x16x32_bf16 v[4:7], v[226:229], v[186:189], v[4:7]
	v_mfma_f32_16x16x32_bf16 v[0:3], v[226:229], v[194:197], v[0:3]
	s_setprio 0
	s_barrier
	s_add_u32 s74, s32, 0x4000
	s_mov_b32 m0, s74
	s_add_u32 s74, s32, 0x6000
	ds_read_b128 v[166:169], v145 offset:32768
	ds_read_b128 v[170:173], v145 offset:33792
	ds_read_b128 v[174:177], v145 offset:34816
	ds_read_b128 v[178:181], v145 offset:35840
	ds_read_b128 v[182:185], v145 offset:49152
	ds_read_b128 v[186:189], v145 offset:50176
	ds_read_b128 v[190:193], v145 offset:51200
	ds_read_b128 v[194:197], v145 offset:52224
	ds_read_b128 v[198:201], v144 offset:32768
	ds_read_b128 v[202:205], v144 offset:33792
	ds_read_b128 v[206:209], v144 offset:34816
	ds_read_b128 v[210:213], v144 offset:35840
	ds_read_b128 v[214:217], v144 offset:36864
	ds_read_b128 v[218:221], v144 offset:37888
	ds_read_b128 v[222:225], v144 offset:38912
	ds_read_b128 v[226:229], v144 offset:39936
	s_add_u32 s88, s72, s44
	s_addc_u32 s89, s73, s45
	global_load_lds_dwordx4 v140, s[88:89]
	s_mov_b32 m0, s74
	s_nop 0
	s_add_u32 s90, s72, s44
	s_addc_u32 s91, s73, s45
	global_load_lds_dwordx4 v142, s[90:91]
	s_waitcnt lgkmcnt(0)
	s_barrier
; #define STAGE(Pp, BASE, br, kt) do { const u16* _g = (BASE) + ((long)(br) * K + (long)(kt) * BK); \
;     __builtin_amdgcn_global_load_lds((const unsigned*)(_g + voff0), (unsigned*)((char*)(Pp) + tb16), 16, 0, 0); \
;     __builtin_amdgcn_global_load_lds((const unsigned*)(_g + voff1), (unsigned*)((char*)(Pp) + tb16 + 8192), 16, 0, 0); } while (0)
; #define LDA(dst, b, h) _Pragma("unroll") for (int m = 0; m < 4; ++m) _Pragma("unroll") for (int k = 0; k < 2; ++k) \
;     dst[m][k] = *reinterpret_cast<const bf16x8*>((const char*)shm + aB + (((b) * 2 + (h)) * 16384 + (m * 2 + k) * 1024))
; #define WAIT_V(n) asm volatile("s_waitcnt vmcnt(" #n ")" ::: "memory")
; #define WAIT_L(n) asm volatile("s_waitcnt lgkmcnt(" #n ")" ::: "memory")
; #define BAR __builtin_amdgcn_s_barrier()
; #define SCHED __builtin_amdgcn_sched_barrier(0)
; template <int MODE> ...
;     ...
;       WAIT_L(0); BAR; MMA2(0, 0, 0, 1); BAR; SCHED;
;       LDA(At, 1, 1); STAGE(SB(1, 0), Bt, bcol, t + 3); STAGE(SB(1, 1), Bt, bcol + HALF, t + 3); STAGE(SA(1, 0), A, brow, t + 3);
;       WAIT_V(6); WAIT_L(0); BAR; MMA2(1, 0, 1, 1); BAR; SCHED;
	s_setprio 1
	s_waitcnt lgkmcnt(0)
	v_mfma_f32_16x16x32_bf16 v[124:127], v[198:201], v[166:169], v[124:127]
	v_mfma_f32_16x16x32_bf16 v[120:123], v[198:201], v[174:177], v[120:123]
	v_mfma_f32_16x16x32_bf16 v[116:119], v[206:209], v[166:169], v[116:119]
	v_mfma_f32_16x16x32_bf16 v[112:115], v[206:209], v[174:177], v[112:115]
	v_mfma_f32_16x16x32_bf16 v[108:111], v[214:217], v[166:169], v[108:111]
	v_mfma_f32_16x16x32_bf16 v[104:107], v[214:217], v[174:177], v[104:107]
	v_mfma_f32_16x16x32_bf16 v[100:103], v[222:225], v[166:169], v[100:103]
	v_mfma_f32_16x16x32_bf16 v[96:99], v[222:225], v[174:177], v[96:99]
	v_mfma_f32_16x16x32_bf16 v[92:95], v[198:201], v[182:185], v[92:95]
	v_mfma_f32_16x16x32_bf16 v[88:91], v[198:201], v[190:193], v[88:91]
	v_mfma_f32_16x16x32_bf16 v[84:87], v[206:209], v[182:185], v[84:87]
	v_mfma_f32_16x16x32_bf16 v[80:83], v[206:209], v[190:193], v[80:83]
	v_mfma_f32_16x16x32_bf16 v[76:79], v[214:217], v[182:185], v[76:79]
	v_mfma_f32_16x16x32_bf16 v[72:75], v[214:217], v[190:193], v[72:75]
	v_mfma_f32_16x16x32_bf16 v[68:71], v[222:225], v[182:185], v[68:71]
	v_mfma_f32_16x16x32_bf16 v[64:67], v[222:225], v[190:193], v[64:67]
	v_mfma_f32_16x16x32_bf16 v[124:127], v[202:205], v[170:173], v[124:127]
	v_mfma_f32_16x16x32_bf16 v[120:123], v[202:205], v[178:181], v[120:123]
	v_mfma_f32_16x16x32_bf16 v[116:119], v[210:213], v[170:173], v[116:119]
	v_mfma_f32_16x16x32_bf16 v[112:115], v[210:213], v[178:181], v[112:115]
	v_mfma_f32_16x16x32_bf16 v[108:111], v[218:221], v[170:173], v[108:111]
	v_mfma_f32_16x16x32_bf16 v[104:107], v[218:221], v[178:181], v[104:107]
	v_mfma_f32_16x16x32_bf16 v[100:103], v[226:229], v[170:173], v[100:103]
	v_mfma_f32_16x16x32_bf16 v[96:99], v[226:229], v[178:181], v[96:99]
	v_mfma_f32_16x16x32_bf16 v[92:95], v[202:205], v[186:189], v[92:95]
	v_mfma_f32_16x16x32_bf16 v[88:91], v[202:205], v[194:197], v[88:91]
	v_mfma_f32_16x16x32_bf16 v[84:87], v[210:213], v[186:189], v[84:87]
	v_mfma_f32_16x16x32_bf16 v[80:83], v[210:213], v[194:197], v[80:83]
	v_mfma_f32_16x16x32_bf16 v[76:79], v[218:221], v[186:189], v[76:79]
	v_mfma_f32_16x16x32_bf16 v[72:75], v[218:221], v[194:197], v[72:75]
	v_mfma_f32_16x16x32_bf16 v[68:71], v[226:229], v[186:189], v[68:71]
	v_mfma_f32_16x16x32_bf16 v[64:67], v[226:229], v[194:197], v[64:67]
	s_setprio 0
	s_barrier
	s_add_u32 s74, s32, 0x18000
	s_mov_b32 m0, s74
	s_add_u32 s74, s32, 0x1a000
	ds_read_b128 v[198:201], v144 offset:49152
	ds_read_b128 v[202:205], v144 offset:50176
	ds_read_b128 v[206:209], v144 offset:51200
	ds_read_b128 v[210:213], v144 offset:52224
	ds_read_b128 v[214:217], v144 offset:53248
	ds_read_b128 v[218:221], v144 offset:54272
	ds_read_b128 v[222:225], v144 offset:55296
	ds_read_b128 v[226:229], v144 offset:56320
	s_add_u32 s92, s72, s48
	s_addc_u32 s93, s73, s49
	global_load_lds_dwordx4 v136, s[92:93]
	s_mov_b32 m0, s74
	s_add_u32 s74, s32, 0x1c000
	s_add_u32 s96, s72, s48
	s_addc_u32 s97, s73, s49
	global_load_lds_dwordx4 v138, s[96:97]
	s_mov_b32 m0, s74
	s_add_u32 s74, s32, 0x1e000
	s_add_u32 s88, s72, s50
	s_addc_u32 s89, s73, s51
	global_load_lds_dwordx4 v136, s[88:89]
	s_mov_b32 m0, s74
	s_add_u32 s74, s32, 0x8000
	s_add_u32 s90, s72, s50
	s_addc_u32 s91, s73, s51
	global_load_lds_dwordx4 v138, s[90:91]
	s_mov_b32 m0, s74
	s_add_u32 s74, s32, 0xa000
	s_add_u32 s92, s72, s60
	s_addc_u32 s93, s73, s61
	global_load_lds_dwordx4 v140, s[92:93]
	s_mov_b32 m0, s74
	s_nop 0
	s_add_u32 s96, s72, s60
	s_addc_u32 s97, s73, s61
	global_load_lds_dwordx4 v142, s[96:97]
	s_waitcnt vmcnt(6)
	s_waitcnt lgkmcnt(0)
	s_barrier
	s_setprio 1
	s_waitcnt lgkmcnt(0)
	v_mfma_f32_16x16x32_bf16 v[60:63], v[198:201], v[166:169], v[60:63]
	v_mfma_f32_16x16x32_bf16 v[56:59], v[198:201], v[174:177], v[56:59]
	v_mfma_f32_16x16x32_bf16 v[52:55], v[206:209], v[166:169], v[52:55]
	v_mfma_f32_16x16x32_bf16 v[48:51], v[206:209], v[174:177], v[48:51]
	v_mfma_f32_16x16x32_bf16 v[44:47], v[214:217], v[166:169], v[44:47]
	v_mfma_f32_16x16x32_bf16 v[40:43], v[214:217], v[174:177], v[40:43]
	v_mfma_f32_16x16x32_bf16 v[36:39], v[222:225], v[166:169], v[36:39]
	v_mfma_f32_16x16x32_bf16 v[32:35], v[222:225], v[174:177], v[32:35]
	v_mfma_f32_16x16x32_bf16 v[28:31], v[198:201], v[182:185], v[28:31]
	v_mfma_f32_16x16x32_bf16 v[24:27], v[198:201], v[190:193], v[24:27]
	v_mfma_f32_16x16x32_bf16 v[20:23], v[206:209], v[182:185], v[20:23]
	v_mfma_f32_16x16x32_bf16 v[16:19], v[206:209], v[190:193], v[16:19]
	v_mfma_f32_16x16x32_bf16 v[12:15], v[214:217], v[182:185], v[12:15]
	v_mfma_f32_16x16x32_bf16 v[8:11], v[214:217], v[190:193], v[8:11]
	v_mfma_f32_16x16x32_bf16 v[4:7], v[222:225], v[182:185], v[4:7]
	v_mfma_f32_16x16x32_bf16 v[0:3], v[222:225], v[190:193], v[0:3]
	v_mfma_f32_16x16x32_bf16 v[60:63], v[202:205], v[170:173], v[60:63]
	v_mfma_f32_16x16x32_bf16 v[56:59], v[202:205], v[178:181], v[56:59]
	v_mfma_f32_16x16x32_bf16 v[52:55], v[210:213], v[170:173], v[52:55]
	v_mfma_f32_16x16x32_bf16 v[48:51], v[210:213], v[178:181], v[48:51]
	v_mfma_f32_16x16x32_bf16 v[44:47], v[218:221], v[170:173], v[44:47]
	v_mfma_f32_16x16x32_bf16 v[40:43], v[218:221], v[178:181], v[40:43]
	v_mfma_f32_16x16x32_bf16 v[36:39], v[226:229], v[170:173], v[36:39]
	v_mfma_f32_16x16x32_bf16 v[32:35], v[226:229], v[178:181], v[32:35]
	v_mfma_f32_16x16x32_bf16 v[28:31], v[202:205], v[186:189], v[28:31]
	v_mfma_f32_16x16x32_bf16 v[24:27], v[202:205], v[194:197], v[24:27]
	v_mfma_f32_16x16x32_bf16 v[20:23], v[210:213], v[186:189], v[20:23]
	v_mfma_f32_16x16x32_bf16 v[16:19], v[210:213], v[194:197], v[16:19]
	v_mfma_f32_16x16x32_bf16 v[12:15], v[218:221], v[186:189], v[12:15]
	v_mfma_f32_16x16x32_bf16 v[8:11], v[218:221], v[194:197], v[8:11]
	v_mfma_f32_16x16x32_bf16 v[4:7], v[226:229], v[186:189], v[4:7]
	v_mfma_f32_16x16x32_bf16 v[0:3], v[226:229], v[194:197], v[0:3]
	s_setprio 0
	s_barrier
; #define STAGE(Pp, BASE, br, kt) do { const u16* _g = (BASE) + ((long)(br) * K + (long)(kt) * BK); \
;     __builtin_amdgcn_global_load_lds((const unsigned*)(_g + voff0), (unsigned*)((char*)(Pp) + tb16), 16, 0, 0); \
;     __builtin_amdgcn_global_load_lds((const unsigned*)(_g + voff1), (unsigned*)((char*)(Pp) + tb16 + 8192), 16, 0, 0); } while (0)
; #define LDA(dst, b, h) _Pragma("unroll") for (int m = 0; m < 4; ++m) _Pragma("unroll") for (int k = 0; k < 2; ++k) \
;     dst[m][k] = *reinterpret_cast<const bf16x8*>((const char*)shm + aB + (((b) * 2 + (h)) * 16384 + (m * 2 + k) * 1024))
; #define LDB(dst, b, h) _Pragma("unroll") for (int n = 0; n < 2; ++n) _Pragma("unroll") for (int k = 0; k < 2; ++k) \
;     dst[n][k] = *reinterpret_cast<const bf16x8*>((const char*)shm + bB + (((b) * 2 + (h)) * 16384 + (n * 2 + k) * 1024))
; #define WAIT_V(n) asm volatile("s_waitcnt vmcnt(" #n ")" ::: "memory")
; #define WAIT_L(n) asm volatile("s_waitcnt lgkmcnt(" #n ")" ::: "memory")
; #define BAR __builtin_amdgcn_s_barrier()
; #define SCHED __builtin_amdgcn_sched_barrier(0)
; template <int MODE> ...
;     ...
;     }
;     {
;       LDB(B0, 0, 0); LDB(B1, 0, 1); LDA(At, 0, 0); STAGE(SA(1, 1), A, brow + HALF, nt - 1);
;       WAIT_L(0); BAR; MMA2(0, 0, 0, 1); BAR; SCHED;
;       LDA(At, 0, 1); WAIT_V(0); WAIT_L(0); BAR; MMA2(1, 0, 1, 1); BAR; SCHED;
	s_add_i32 s63, s63, 2
	s_add_u32 s72, s72, 0x100
	s_addc_u32 s73, s73, 0
	s_cmp_lt_u32 s63, 60
	s_cbranch_scc1 .LBB0_486
	s_add_u32 s70, s70, 0x1f80
	v_readfirstlane_b32 s63, v160
	s_addc_u32 s71, s71, 0
	s_mov_b32 m0, s63
	v_readfirstlane_b32 s63, v161
	ds_read_b128 v[136:139], v145
	ds_read_b128 v[140:143], v145 offset:1024
	ds_read_b128 v[166:169], v145 offset:2048
	ds_read_b128 v[170:173], v145 offset:3072
	ds_read_b128 v[174:177], v145 offset:16384
	ds_read_b128 v[178:181], v145 offset:17408
	ds_read_b128 v[182:185], v145 offset:18432
	ds_read_b128 v[186:189], v145 offset:19456
	ds_read_b128 v[190:193], v144
	ds_read_b128 v[194:197], v144 offset:1024
	ds_read_b128 v[198:201], v144 offset:2048
	ds_read_b128 v[202:205], v144 offset:3072
	ds_read_b128 v[206:209], v144 offset:4096
	ds_read_b128 v[210:213], v144 offset:5120
	ds_read_b128 v[214:217], v144 offset:6144
	ds_read_b128 v[218:221], v144 offset:7168
	global_load_lds_dwordx4 v132, s[70:71]
	s_mov_b32 m0, s63
	s_nop 0
	global_load_lds_dwordx4 v134, s[70:71]
	s_waitcnt lgkmcnt(0)
	s_barrier
	s_setprio 1
	s_waitcnt lgkmcnt(0)
	v_mfma_f32_16x16x32_bf16 v[124:127], v[190:193], v[136:139], v[124:127]
	v_mfma_f32_16x16x32_bf16 v[116:119], v[198:201], v[136:139], v[116:119]
	v_mfma_f32_16x16x32_bf16 v[108:111], v[206:209], v[136:139], v[108:111]
	v_mfma_f32_16x16x32_bf16 v[100:103], v[214:217], v[136:139], v[100:103]
	v_mfma_f32_16x16x32_bf16 v[96:99], v[214:217], v[166:169], v[96:99]
	v_mfma_f32_16x16x32_bf16 v[92:95], v[190:193], v[174:177], v[92:95]
	v_mfma_f32_16x16x32_bf16 v[88:91], v[190:193], v[182:185], v[88:91]
	v_mfma_f32_16x16x32_bf16 v[80:83], v[198:201], v[182:185], v[80:83]
	v_mfma_f32_16x16x32_bf16 v[76:79], v[206:209], v[174:177], v[76:79]
	v_mfma_f32_16x16x32_bf16 v[124:127], v[194:197], v[140:143], v[124:127]
	v_mfma_f32_16x16x32_bf16 v[120:123], v[190:193], v[166:169], v[120:123]
	v_mfma_f32_16x16x32_bf16 v[116:119], v[202:205], v[140:143], v[116:119]
	v_mfma_f32_16x16x32_bf16 v[112:115], v[198:201], v[166:169], v[112:115]
	v_mfma_f32_16x16x32_bf16 v[108:111], v[210:213], v[140:143], v[108:111]
	v_mfma_f32_16x16x32_bf16 v[104:107], v[206:209], v[166:169], v[104:107]
	v_mfma_f32_16x16x32_bf16 v[100:103], v[218:221], v[140:143], v[100:103]
	v_mfma_f32_16x16x32_bf16 v[96:99], v[218:221], v[170:173], v[96:99]
	v_mfma_f32_16x16x32_bf16 v[92:95], v[194:197], v[178:181], v[92:95]
	v_mfma_f32_16x16x32_bf16 v[88:91], v[194:197], v[186:189], v[88:91]
	v_mfma_f32_16x16x32_bf16 v[84:87], v[198:201], v[174:177], v[84:87]
	v_mfma_f32_16x16x32_bf16 v[80:83], v[202:205], v[186:189], v[80:83]
	v_mfma_f32_16x16x32_bf16 v[76:79], v[210:213], v[178:181], v[76:79]
	v_mfma_f32_16x16x32_bf16 v[72:75], v[206:209], v[182:185], v[72:75]
	v_mfma_f32_16x16x32_bf16 v[68:71], v[214:217], v[174:177], v[68:71]
	v_mfma_f32_16x16x32_bf16 v[64:67], v[214:217], v[182:185], v[64:67]
	v_mfma_f32_16x16x32_bf16 v[222:225], v[194:197], v[170:173], v[120:123]
	v_mfma_f32_16x16x32_bf16 v[226:229], v[202:205], v[170:173], v[112:115]
	v_mfma_f32_16x16x32_bf16 v[230:233], v[210:213], v[170:173], v[104:107]
	v_mfma_f32_16x16x32_bf16 v[190:193], v[202:205], v[178:181], v[84:87]
	v_mfma_f32_16x16x32_bf16 v[194:197], v[210:213], v[186:189], v[72:75]
	v_mfma_f32_16x16x32_bf16 v[198:201], v[218:221], v[178:181], v[68:71]
	v_mfma_f32_16x16x32_bf16 v[202:205], v[218:221], v[186:189], v[64:67]
	s_setprio 0
	s_barrier
	s_nop 0
	ds_read_b128 v[64:67], v144 offset:16384
	ds_read_b128 v[68:71], v144 offset:17408
	ds_read_b128 v[72:75], v144 offset:18432
	ds_read_b128 v[84:87], v144 offset:19456
	ds_read_b128 v[104:107], v144 offset:20480
	ds_read_b128 v[112:115], v144 offset:21504
	ds_read_b128 v[120:123], v144 offset:22528
	ds_read_b128 v[206:209], v144 offset:23552
	s_waitcnt vmcnt(0)
	s_waitcnt lgkmcnt(0)
	s_barrier
	s_setprio 1
	s_waitcnt lgkmcnt(0)
	v_mfma_f32_16x16x32_bf16 v[60:63], v[64:67], v[136:139], v[60:63]
	v_mfma_f32_16x16x32_bf16 v[56:59], v[64:67], v[166:169], v[56:59]
	v_mfma_f32_16x16x32_bf16 v[52:55], v[72:75], v[136:139], v[52:55]
	v_mfma_f32_16x16x32_bf16 v[48:51], v[72:75], v[166:169], v[48:51]
	v_mfma_f32_16x16x32_bf16 v[44:47], v[104:107], v[136:139], v[44:47]
	v_mfma_f32_16x16x32_bf16 v[40:43], v[104:107], v[166:169], v[40:43]
	v_mfma_f32_16x16x32_bf16 v[28:31], v[64:67], v[174:177], v[28:31]
	v_mfma_f32_16x16x32_bf16 v[24:27], v[64:67], v[182:185], v[24:27]
	v_mfma_f32_16x16x32_bf16 v[20:23], v[72:75], v[174:177], v[20:23]
	v_mfma_f32_16x16x32_bf16 v[60:63], v[68:71], v[140:143], v[60:63]
	v_mfma_f32_16x16x32_bf16 v[56:59], v[68:71], v[170:173], v[56:59]
	v_mfma_f32_16x16x32_bf16 v[52:55], v[84:87], v[140:143], v[52:55]
	v_mfma_f32_16x16x32_bf16 v[48:51], v[84:87], v[170:173], v[48:51]
	v_mfma_f32_16x16x32_bf16 v[44:47], v[112:115], v[140:143], v[44:47]
	v_mfma_f32_16x16x32_bf16 v[40:43], v[112:115], v[170:173], v[40:43]
	v_mfma_f32_16x16x32_bf16 v[36:39], v[120:123], v[136:139], v[36:39]
	v_mfma_f32_16x16x32_bf16 v[32:35], v[120:123], v[166:169], v[32:35]
	v_mfma_f32_16x16x32_bf16 v[28:31], v[68:71], v[178:181], v[28:31]
	v_mfma_f32_16x16x32_bf16 v[24:27], v[68:71], v[186:189], v[24:27]
	v_mfma_f32_16x16x32_bf16 v[20:23], v[84:87], v[178:181], v[20:23]
	v_mfma_f32_16x16x32_bf16 v[16:19], v[72:75], v[182:185], v[16:19]
	v_mfma_f32_16x16x32_bf16 v[12:15], v[104:107], v[174:177], v[12:15]
	v_mfma_f32_16x16x32_bf16 v[8:11], v[104:107], v[182:185], v[8:11]
	v_mfma_f32_16x16x32_bf16 v[4:7], v[120:123], v[174:177], v[4:7]
	v_mfma_f32_16x16x32_bf16 v[0:3], v[120:123], v[182:185], v[0:3]
	v_mfma_f32_16x16x32_bf16 v[136:139], v[206:209], v[140:143], v[36:39]
	v_mfma_f32_16x16x32_bf16 v[140:143], v[206:209], v[170:173], v[32:35]
	v_mfma_f32_16x16x32_bf16 v[166:169], v[84:87], v[186:189], v[16:19]
	v_mfma_f32_16x16x32_bf16 v[170:173], v[112:115], v[178:181], v[12:15]
	v_mfma_f32_16x16x32_bf16 v[210:213], v[112:115], v[186:189], v[8:11]
	v_mfma_f32_16x16x32_bf16 v[174:177], v[206:209], v[178:181], v[4:7]
	v_mfma_f32_16x16x32_bf16 v[178:181], v[206:209], v[186:189], v[0:3]
	s_setprio 0
	s_barrier
; #define LDA(dst, b, h) _Pragma("unroll") for (int m = 0; m < 4; ++m) _Pragma("unroll") for (int k = 0; k < 2; ++k) \
;     dst[m][k] = *reinterpret_cast<const bf16x8*>((const char*)shm + aB + (((b) * 2 + (h)) * 16384 + (m * 2 + k) * 1024))
; #define LDB(dst, b, h) _Pragma("unroll") for (int n = 0; n < 2; ++n) _Pragma("unroll") for (int k = 0; k < 2; ++k) \
;     dst[n][k] = *reinterpret_cast<const bf16x8*>((const char*)shm + bB + (((b) * 2 + (h)) * 16384 + (n * 2 + k) * 1024))
; #define WAIT_L(n) asm volatile("s_waitcnt lgkmcnt(" #n ")" ::: "memory")
; #define BAR __builtin_amdgcn_s_barrier()
; #define SCHED __builtin_amdgcn_sched_barrier(0)
; template <int MODE> ...
;     ...
;       LDB(B0, 1, 0); LDB(B1, 1, 1); LDA(At, 1, 0); WAIT_L(0); BAR; MMA2(0, 0, 0, 1); BAR; SCHED;
;       LDA(At, 1, 1); WAIT_L(0); BAR; MMA2(1, 0, 1, 1); BAR; SCHED;
;     }
;     ...
;     if (wr == 0) BAR;
	ds_read_b128 v[12:15], v145 offset:32768
	ds_read_b128 v[16:19], v145 offset:33792
	ds_read_b128 v[182:185], v145 offset:34816
	ds_read_b128 v[186:189], v145 offset:35840
	ds_read_b128 v[206:209], v145 offset:49152
	ds_read_b128 v[214:217], v145 offset:50176
	ds_read_b128 v[218:221], v145 offset:51200
	ds_read_b128 v[234:237], v145 offset:52224
	ds_read_b128 v[0:3], v144 offset:32768
	ds_read_b128 v[4:7], v144 offset:33792
	ds_read_b128 v[8:11], v144 offset:34816
	ds_read_b128 v[32:35], v144 offset:35840
	ds_read_b128 v[36:39], v144 offset:36864
	ds_read_b128 v[238:241], v144 offset:37888
	ds_read_b128 v[242:245], v144 offset:38912
	ds_read_b128 v[246:249], v144 offset:39936
	s_waitcnt lgkmcnt(0)
	s_barrier
	s_setprio 1
	s_waitcnt lgkmcnt(0)
	v_mfma_f32_16x16x32_bf16 v[64:67], v[0:3], v[12:15], v[124:127]
	v_mfma_f32_16x16x32_bf16 v[68:71], v[242:245], v[182:185], v[96:99]
	v_mfma_f32_16x16x32_bf16 v[120:123], v[4:7], v[16:19], v[64:67]
	v_mfma_f32_16x16x32_bf16 v[64:67], v[0:3], v[182:185], v[222:225]
	v_mfma_f32_16x16x32_bf16 v[84:87], v[246:249], v[186:189], v[68:71]
	v_mfma_f32_16x16x32_bf16 v[68:71], v[0:3], v[206:209], v[92:95]
	v_mfma_f32_16x16x32_bf16 v[0:3], v[0:3], v[218:221], v[88:91]
	v_mfma_f32_16x16x32_bf16 v[88:91], v[4:7], v[234:237], v[0:3]
	v_mfma_f32_16x16x32_bf16 v[0:3], v[8:11], v[206:209], v[190:193]
	v_mfma_f32_16x16x32_bf16 v[124:127], v[4:7], v[186:189], v[64:67]
	v_mfma_f32_16x16x32_bf16 v[64:67], v[8:11], v[12:15], v[116:119]
	v_mfma_f32_16x16x32_bf16 v[72:75], v[32:35], v[214:217], v[0:3]
	v_mfma_f32_16x16x32_bf16 v[0:3], v[8:11], v[218:221], v[80:83]
	v_mfma_f32_16x16x32_bf16 v[112:115], v[32:35], v[16:19], v[64:67]
	v_mfma_f32_16x16x32_bf16 v[64:67], v[8:11], v[182:185], v[226:229]
	v_mfma_f32_16x16x32_bf16 v[92:95], v[32:35], v[234:237], v[0:3]
	v_mfma_f32_16x16x32_bf16 v[0:3], v[36:39], v[206:209], v[76:79]
	v_mfma_f32_16x16x32_bf16 v[116:119], v[32:35], v[186:189], v[64:67]
	v_mfma_f32_16x16x32_bf16 v[64:67], v[36:39], v[12:15], v[108:111]
	v_mfma_f32_16x16x32_bf16 v[76:79], v[238:241], v[214:217], v[0:3]
	v_mfma_f32_16x16x32_bf16 v[0:3], v[36:39], v[218:221], v[194:197]
	v_mfma_f32_16x16x32_bf16 v[104:107], v[238:241], v[16:19], v[64:67]
	v_mfma_f32_16x16x32_bf16 v[64:67], v[36:39], v[182:185], v[230:233]
	v_mfma_f32_16x16x32_bf16 v[96:99], v[238:241], v[234:237], v[0:3]
	v_mfma_f32_16x16x32_bf16 v[0:3], v[242:245], v[206:209], v[198:201]
	v_mfma_f32_16x16x32_bf16 v[108:111], v[238:241], v[186:189], v[64:67]
	v_mfma_f32_16x16x32_bf16 v[64:67], v[242:245], v[12:15], v[100:103]
	v_mfma_f32_16x16x32_bf16 v[80:83], v[246:249], v[214:217], v[0:3]
	v_mfma_f32_16x16x32_bf16 v[0:3], v[242:245], v[218:221], v[202:205]
	v_mfma_f32_16x16x32_bf16 v[64:67], v[246:249], v[16:19], v[64:67]
	v_mfma_f32_16x16x32_bf16 v[68:71], v[4:7], v[214:217], v[68:71]
	v_mfma_f32_16x16x32_bf16 v[100:103], v[246:249], v[234:237], v[0:3]
	s_setprio 0
	s_barrier
	ds_read_b128 v[190:193], v144 offset:49152
	ds_read_b128 v[194:197], v144 offset:50176
	ds_read_b128 v[198:201], v144 offset:51200
	ds_read_b128 v[202:205], v144 offset:52224
	ds_read_b128 v[222:225], v144 offset:53248
	ds_read_b128 v[226:229], v144 offset:54272
	ds_read_b128 v[230:233], v144 offset:55296
	ds_read_b128 v[238:241], v144 offset:56320
	s_waitcnt lgkmcnt(0)
	s_barrier
	s_setprio 1
	s_waitcnt lgkmcnt(0)
	v_mfma_f32_16x16x32_bf16 v[4:7], v[190:193], v[182:185], v[56:59]
	v_mfma_f32_16x16x32_bf16 v[8:11], v[198:201], v[182:185], v[48:51]
	v_mfma_f32_16x16x32_bf16 v[0:3], v[190:193], v[12:15], v[60:63]
	v_mfma_f32_16x16x32_bf16 v[32:35], v[194:197], v[186:189], v[4:7]
	v_mfma_f32_16x16x32_bf16 v[4:7], v[198:201], v[12:15], v[52:55]
	v_mfma_f32_16x16x32_bf16 v[36:39], v[202:205], v[186:189], v[8:11]
	v_mfma_f32_16x16x32_bf16 v[8:11], v[222:225], v[12:15], v[44:47]
	v_mfma_f32_16x16x32_bf16 v[12:15], v[230:233], v[12:15], v[136:139]
	v_mfma_f32_16x16x32_bf16 v[0:3], v[194:197], v[16:19], v[0:3]
	v_mfma_f32_16x16x32_bf16 v[4:7], v[202:205], v[16:19], v[4:7]
	v_mfma_f32_16x16x32_bf16 v[8:11], v[226:229], v[16:19], v[8:11]
	v_mfma_f32_16x16x32_bf16 v[12:15], v[238:241], v[16:19], v[12:15]
	v_mfma_f32_16x16x32_bf16 v[16:19], v[230:233], v[182:185], v[140:143]
	v_mfma_f32_16x16x32_bf16 v[24:27], v[190:193], v[218:221], v[24:27]
	v_mfma_f32_16x16x32_bf16 v[44:47], v[238:241], v[186:189], v[16:19]
	v_mfma_f32_16x16x32_bf16 v[16:19], v[190:193], v[206:209], v[28:31]
	v_mfma_f32_16x16x32_bf16 v[48:51], v[194:197], v[234:237], v[24:27]
	v_mfma_f32_16x16x32_bf16 v[24:27], v[198:201], v[218:221], v[166:169]
	v_mfma_f32_16x16x32_bf16 v[28:31], v[222:225], v[218:221], v[210:213]
	v_mfma_f32_16x16x32_bf16 v[40:43], v[222:225], v[182:185], v[40:43]
	v_mfma_f32_16x16x32_bf16 v[20:23], v[198:201], v[206:209], v[20:23]
	v_mfma_f32_16x16x32_bf16 v[52:55], v[202:205], v[234:237], v[24:27]
	v_mfma_f32_16x16x32_bf16 v[24:27], v[222:225], v[206:209], v[170:173]
	v_mfma_f32_16x16x32_bf16 v[56:59], v[226:229], v[234:237], v[28:31]
	v_mfma_f32_16x16x32_bf16 v[28:31], v[230:233], v[206:209], v[174:177]
	v_mfma_f32_16x16x32_bf16 v[60:63], v[230:233], v[218:221], v[178:181]
	v_mfma_f32_16x16x32_bf16 v[40:43], v[226:229], v[186:189], v[40:43]
	v_mfma_f32_16x16x32_bf16 v[16:19], v[194:197], v[214:217], v[16:19]
	v_mfma_f32_16x16x32_bf16 v[20:23], v[202:205], v[214:217], v[20:23]
	v_mfma_f32_16x16x32_bf16 v[24:27], v[226:229], v[214:217], v[24:27]
	v_mfma_f32_16x16x32_bf16 v[28:31], v[238:241], v[214:217], v[28:31]
	v_mfma_f32_16x16x32_bf16 v[60:63], v[238:241], v[234:237], v[60:63]
	s_setprio 0
	s_barrier
	s_and_saveexec_b64 s[70:71], s[6:7]
	s_cbranch_execz .LBB0_489
	s_barrier

; #define STAGE(Pp, BASE, br, kt) do { const u16* _g = (BASE) + ((long)(br) * K + (long)(kt) * BK); \
;     __builtin_amdgcn_global_load_lds((const unsigned*)(_g + voff0), (unsigned*)((char*)(Pp) + tb16), 16, 0, 0); \
;     __builtin_amdgcn_global_load_lds((const unsigned*)(_g + voff1), (unsigned*)((char*)(Pp) + tb16 + 8192), 16, 0, 0); } while (0)
; #define LDA(dst, b, h) _Pragma("unroll") for (int m = 0; m < 4; ++m) _Pragma("unroll") for (int k = 0; k < 2; ++k) \
;     dst[m][k] = *reinterpret_cast<const bf16x8*>((const char*)shm + aB + (((b) * 2 + (h)) * 16384 + (m * 2 + k) * 1024))
; #define LDB(dst, b, h) _Pragma("unroll") for (int n = 0; n < 2; ++n) _Pragma("unroll") for (int k = 0; k < 2; ++k) \
;     dst[n][k] = *reinterpret_cast<const bf16x8*>((const char*)shm + bB + (((b) * 2 + (h)) * 16384 + (n * 2 + k) * 1024))
; #define WAIT_V(n) asm volatile("s_waitcnt vmcnt(" #n ")" ::: "memory")
; #define WAIT_L(n) asm volatile("s_waitcnt lgkmcnt(" #n ")" ::: "memory")
; #define BAR __builtin_amdgcn_s_barrier()
; #define SCHED __builtin_amdgcn_sched_barrier(0)
; template <int MODE> ...
;     ...
;     f32x4 acc[2][2][4][2] = {};
;     bf16x8 At[4][2], B0[2][2], B1[2][2];
;     ...
;     STAGE(SB(0, 0), Bt, bcol, 0); STAGE(SA(0, 0), A, brow, 0); STAGE(SB(0, 1), Bt, bcol + HALF, 0); STAGE(SA(0, 1), A, brow + HALF, 0);
;     STAGE(SB(1, 0), Bt, bcol, 1); STAGE(SA(1, 0), A, brow, 1); STAGE(SB(1, 1), Bt, bcol + HALF, 1);
;     WAIT_V(6);
;     if (wr == 1) BAR;
;     BAR;
;     for (int t = 0; t < nt - 2; t += 2) {
;       LDB(B0, 0, 0); LDB(B1, 0, 1); LDA(At, 0, 0); STAGE(SA(1, 1), A, brow + HALF, t + 1);
;       WAIT_L(0); BAR; MMA2(0, 0, 0, 1); BAR; SCHED;
.LBB0_590:
	s_or_b64 exec, exec, s[68:69]
	v_mov_b32_e32 v0, 0
	v_lshl_add_u64 v[138:139], v[146:147], 0, s[10:11]
	v_lshl_add_u64 v[140:141], v[252:253], 0, s[10:11]
	v_lshl_add_u64 v[142:143], v[146:147], 0, s[66:67]
	v_lshl_add_u64 v[144:145], v[252:253], 0, s[66:67]
	s_mov_b32 s35, -2
	s_mov_b64 s[10:11], s[56:57]
	v_mov_b32_e32 v1, v0
	v_mov_b32_e32 v2, v0
	v_mov_b32_e32 v3, v0
	v_mov_b32_e32 v4, v0
	v_mov_b32_e32 v5, v0
	v_mov_b32_e32 v6, v0
	v_mov_b32_e32 v7, v0
	v_mov_b32_e32 v8, v0
	v_mov_b32_e32 v9, v0
	v_mov_b32_e32 v10, v0
	v_mov_b32_e32 v11, v0
	v_mov_b32_e32 v12, v0
	v_mov_b32_e32 v13, v0
	v_mov_b32_e32 v14, v0
	v_mov_b32_e32 v15, v0
	v_mov_b32_e32 v16, v0
	v_mov_b32_e32 v17, v0
	v_mov_b32_e32 v18, v0
	v_mov_b32_e32 v19, v0
	v_mov_b32_e32 v20, v0
	v_mov_b32_e32 v21, v0
	v_mov_b32_e32 v22, v0
	v_mov_b32_e32 v23, v0
	v_mov_b32_e32 v24, v0
	v_mov_b32_e32 v25, v0
	v_mov_b32_e32 v26, v0
	v_mov_b32_e32 v27, v0
	v_mov_b32_e32 v28, v0
	v_mov_b32_e32 v29, v0
	v_mov_b32_e32 v30, v0
	v_mov_b32_e32 v31, v0
	v_mov_b32_e32 v32, v0
	v_mov_b32_e32 v33, v0
	v_mov_b32_e32 v34, v0
	v_mov_b32_e32 v35, v0
	v_mov_b32_e32 v36, v0
	v_mov_b32_e32 v37, v0
	v_mov_b32_e32 v38, v0
	v_mov_b32_e32 v39, v0
	v_mov_b32_e32 v40, v0
	v_mov_b32_e32 v41, v0
	v_mov_b32_e32 v42, v0
	v_mov_b32_e32 v43, v0
	v_mov_b32_e32 v44, v0
	v_mov_b32_e32 v45, v0
	v_mov_b32_e32 v46, v0
	v_mov_b32_e32 v47, v0
	v_mov_b32_e32 v48, v0
	v_mov_b32_e32 v49, v0
	v_mov_b32_e32 v50, v0
	v_mov_b32_e32 v51, v0
	v_mov_b32_e32 v56, v0
	v_mov_b32_e32 v57, v0
	v_mov_b32_e32 v58, v0
	v_mov_b32_e32 v59, v0
	v_mov_b32_e32 v72, v0
	v_mov_b32_e32 v73, v0
	v_mov_b32_e32 v74, v0
	v_mov_b32_e32 v75, v0
	v_mov_b32_e32 v88, v0
	v_mov_b32_e32 v89, v0
	v_mov_b32_e32 v90, v0
	v_mov_b32_e32 v91, v0
	v_mov_b32_e32 v96, v0
	v_mov_b32_e32 v97, v0
	v_mov_b32_e32 v98, v0
	v_mov_b32_e32 v99, v0
	v_mov_b32_e32 v100, v0
	v_mov_b32_e32 v101, v0
	v_mov_b32_e32 v102, v0
	v_mov_b32_e32 v103, v0
	v_mov_b32_e32 v104, v0
	v_mov_b32_e32 v105, v0
	v_mov_b32_e32 v106, v0
	v_mov_b32_e32 v107, v0
	v_mov_b32_e32 v108, v0
	v_mov_b32_e32 v109, v0
	v_mov_b32_e32 v110, v0
	v_mov_b32_e32 v111, v0
	v_mov_b32_e32 v112, v0
	v_mov_b32_e32 v113, v0
	v_mov_b32_e32 v114, v0
	v_mov_b32_e32 v115, v0
	v_mov_b32_e32 v116, v0
	v_mov_b32_e32 v117, v0
	v_mov_b32_e32 v118, v0
	v_mov_b32_e32 v119, v0
	v_mov_b32_e32 v120, v0
	v_mov_b32_e32 v121, v0
	v_mov_b32_e32 v122, v0
	v_mov_b32_e32 v123, v0
	v_mov_b32_e32 v124, v0
	v_mov_b32_e32 v125, v0
	v_mov_b32_e32 v126, v0
	v_mov_b32_e32 v127, v0
	v_mov_b32_e32 v52, v0
	v_mov_b32_e32 v53, v0
	v_mov_b32_e32 v54, v0
	v_mov_b32_e32 v55, v0
	v_mov_b32_e32 v60, v0
	v_mov_b32_e32 v61, v0
	v_mov_b32_e32 v62, v0
	v_mov_b32_e32 v63, v0
	v_mov_b32_e32 v64, v0
	v_mov_b32_e32 v65, v0
	v_mov_b32_e32 v66, v0
	v_mov_b32_e32 v67, v0
	v_mov_b32_e32 v68, v0
	v_mov_b32_e32 v69, v0
	v_mov_b32_e32 v70, v0
	v_mov_b32_e32 v71, v0
	v_mov_b32_e32 v76, v0
	v_mov_b32_e32 v77, v0
	v_mov_b32_e32 v78, v0
	v_mov_b32_e32 v79, v0
	v_mov_b32_e32 v80, v0
	v_mov_b32_e32 v81, v0
	v_mov_b32_e32 v82, v0
	v_mov_b32_e32 v83, v0
	v_mov_b32_e32 v84, v0
	v_mov_b32_e32 v85, v0
	v_mov_b32_e32 v86, v0
	v_mov_b32_e32 v87, v0
	v_mov_b32_e32 v92, v0
	v_mov_b32_e32 v93, v0
	v_mov_b32_e32 v94, v0
	v_mov_b32_e32 v95, v0
	v_readfirstlane_b32 s32, v150
	s_barrier
.LBB0_591:
	s_add_u32 s65, s32, 0xc000
	s_mov_b32 m0, s65
	ds_read_b128 v[168:171], v149
	ds_read_b128 v[172:175], v149 offset:1024
	ds_read_b128 v[176:179], v149 offset:2048
	ds_read_b128 v[180:183], v149 offset:3072
	ds_read_b128 v[184:187], v149 offset:16384
	ds_read_b128 v[188:191], v149 offset:17408
	ds_read_b128 v[192:195], v149 offset:18432
	ds_read_b128 v[196:199], v149 offset:19456
	ds_read_b128 v[200:203], v148
	ds_read_b128 v[204:207], v148 offset:1024
	ds_read_b128 v[208:211], v148 offset:2048
	ds_read_b128 v[212:215], v148 offset:3072
	ds_read_b128 v[216:219], v148 offset:4096
	ds_read_b128 v[220:223], v148 offset:5120
	ds_read_b128 v[224:227], v148 offset:6144
	ds_read_b128 v[228:231], v148 offset:7168
	s_add_u32 s88, s10, s38
	s_addc_u32 s89, s11, s39
	global_load_lds_dwordx4 v142, s[88:89]
	s_add_u32 s65, s32, 0xe000
	s_mov_b32 m0, s65
	s_nop 0
	s_add_u32 s90, s10, s38
	s_addc_u32 s91, s11, s39
	global_load_lds_dwordx4 v144, s[90:91]
	s_waitcnt lgkmcnt(0)
	s_barrier
	s_setprio 1
	s_waitcnt lgkmcnt(0)
	v_mfma_f32_16x16x32_bf16 v[124:127], v[200:203], v[168:171], v[124:127]
	v_mfma_f32_16x16x32_bf16 v[120:123], v[200:203], v[176:179], v[120:123]
	v_mfma_f32_16x16x32_bf16 v[116:119], v[208:211], v[168:171], v[116:119]
	v_mfma_f32_16x16x32_bf16 v[112:115], v[208:211], v[176:179], v[112:115]
	v_mfma_f32_16x16x32_bf16 v[108:111], v[216:219], v[168:171], v[108:111]
	v_mfma_f32_16x16x32_bf16 v[104:107], v[216:219], v[176:179], v[104:107]
	v_mfma_f32_16x16x32_bf16 v[100:103], v[224:227], v[168:171], v[100:103]
	v_mfma_f32_16x16x32_bf16 v[96:99], v[224:227], v[176:179], v[96:99]
	v_mfma_f32_16x16x32_bf16 v[88:91], v[200:203], v[184:187], v[88:91]
	v_mfma_f32_16x16x32_bf16 v[72:75], v[200:203], v[192:195], v[72:75]
	v_mfma_f32_16x16x32_bf16 v[56:59], v[208:211], v[184:187], v[56:59]
	v_mfma_f32_16x16x32_bf16 v[48:51], v[208:211], v[192:195], v[48:51]
	v_mfma_f32_16x16x32_bf16 v[44:47], v[216:219], v[184:187], v[44:47]
	v_mfma_f32_16x16x32_bf16 v[40:43], v[216:219], v[192:195], v[40:43]
	v_mfma_f32_16x16x32_bf16 v[36:39], v[224:227], v[184:187], v[36:39]
	v_mfma_f32_16x16x32_bf16 v[32:35], v[224:227], v[192:195], v[32:35]
	v_mfma_f32_16x16x32_bf16 v[124:127], v[204:207], v[172:175], v[124:127]
	v_mfma_f32_16x16x32_bf16 v[120:123], v[204:207], v[180:183], v[120:123]
	v_mfma_f32_16x16x32_bf16 v[116:119], v[212:215], v[172:175], v[116:119]
	v_mfma_f32_16x16x32_bf16 v[112:115], v[212:215], v[180:183], v[112:115]
	v_mfma_f32_16x16x32_bf16 v[108:111], v[220:223], v[172:175], v[108:111]
	v_mfma_f32_16x16x32_bf16 v[104:107], v[220:223], v[180:183], v[104:107]
	v_mfma_f32_16x16x32_bf16 v[100:103], v[228:231], v[172:175], v[100:103]
	v_mfma_f32_16x16x32_bf16 v[96:99], v[228:231], v[180:183], v[96:99]
	v_mfma_f32_16x16x32_bf16 v[88:91], v[204:207], v[188:191], v[88:91]
	v_mfma_f32_16x16x32_bf16 v[72:75], v[204:207], v[196:199], v[72:75]
	v_mfma_f32_16x16x32_bf16 v[56:59], v[212:215], v[188:191], v[56:59]
	v_mfma_f32_16x16x32_bf16 v[48:51], v[212:215], v[196:199], v[48:51]
	v_mfma_f32_16x16x32_bf16 v[44:47], v[220:223], v[188:191], v[44:47]
	v_mfma_f32_16x16x32_bf16 v[40:43], v[220:223], v[196:199], v[40:43]
	v_mfma_f32_16x16x32_bf16 v[36:39], v[228:231], v[188:191], v[36:39]
	v_mfma_f32_16x16x32_bf16 v[32:35], v[228:231], v[196:199], v[32:35]
	s_setprio 0
	s_barrier
; #define STAGE(Pp, BASE, br, kt) do { const u16* _g = (BASE) + ((long)(br) * K + (long)(kt) * BK); \
;     __builtin_amdgcn_global_load_lds((const unsigned*)(_g + voff0), (unsigned*)((char*)(Pp) + tb16), 16, 0, 0); \
;     __builtin_amdgcn_global_load_lds((const unsigned*)(_g + voff1), (unsigned*)((char*)(Pp) + tb16 + 8192), 16, 0, 0); } while (0)
; #define LDA(dst, b, h) _Pragma("unroll") for (int m = 0; m < 4; ++m) _Pragma("unroll") for (int k = 0; k < 2; ++k) \
;     dst[m][k] = *reinterpret_cast<const bf16x8*>((const char*)shm + aB + (((b) * 2 + (h)) * 16384 + (m * 2 + k) * 1024))
; #define LDB(dst, b, h) _Pragma("unroll") for (int n = 0; n < 2; ++n) _Pragma("unroll") for (int k = 0; k < 2; ++k) \
;     dst[n][k] = *reinterpret_cast<const bf16x8*>((const char*)shm + bB + (((b) * 2 + (h)) * 16384 + (n * 2 + k) * 1024))
; #define WAIT_V(n) asm volatile("s_waitcnt vmcnt(" #n ")" ::: "memory")
; #define WAIT_L(n) asm volatile("s_waitcnt lgkmcnt(" #n ")" ::: "memory")
; #define BAR __builtin_amdgcn_s_barrier()
; #define SCHED __builtin_amdgcn_sched_barrier(0)
; template <int MODE> ...
;     ...
;       LDA(At, 0, 1); STAGE(SB(0, 0), Bt, bcol, t + 2); STAGE(SB(0, 1), Bt, bcol + HALF, t + 2); STAGE(SA(0, 0), A, brow, t + 2);
;       WAIT_V(6); WAIT_L(0); BAR; MMA2(1, 0, 1, 1); BAR; SCHED;
;       LDB(B0, 1, 0); LDB(B1, 1, 1); LDA(At, 1, 0); STAGE(SA(0, 1), A, brow + HALF, t + 2);
	s_add_u32 s65, s32, 0x10000
	s_mov_b32 m0, s65
	ds_read_b128 v[200:203], v148 offset:16384
	ds_read_b128 v[204:207], v148 offset:17408
	ds_read_b128 v[208:211], v148 offset:18432
	ds_read_b128 v[212:215], v148 offset:19456
	ds_read_b128 v[216:219], v148 offset:20480
	ds_read_b128 v[220:223], v148 offset:21504
	ds_read_b128 v[224:227], v148 offset:22528
	ds_read_b128 v[228:231], v148 offset:23552
	s_add_u32 s92, s10, s40
	s_addc_u32 s93, s11, s41
	global_load_lds_dwordx4 v138, s[92:93]
	s_add_u32 s65, s32, 0x12000
	s_mov_b32 m0, s65
	s_add_u32 s65, s32, 0x14000
	s_add_u32 s96, s10, s40
	s_addc_u32 s97, s11, s41
	global_load_lds_dwordx4 v140, s[96:97]
	s_mov_b32 m0, s65
	s_add_u32 s65, s32, 0x16000
	s_add_u32 s88, s10, s42
	s_addc_u32 s89, s11, s43
	global_load_lds_dwordx4 v138, s[88:89]
	s_mov_b32 m0, s65
	s_mov_b32 s65, s32
	s_add_u32 s90, s10, s42
	s_addc_u32 s91, s11, s43
	global_load_lds_dwordx4 v140, s[90:91]
	s_mov_b32 m0, s65
	s_add_u32 s65, s32, 0x2000
	s_add_u32 s92, s10, s44
	s_addc_u32 s93, s11, s45
	global_load_lds_dwordx4 v142, s[92:93]
	s_mov_b32 m0, s65
	s_nop 0
	s_add_u32 s96, s10, s44
	s_addc_u32 s97, s11, s45
	global_load_lds_dwordx4 v144, s[96:97]
	s_waitcnt vmcnt(6)
	s_waitcnt lgkmcnt(0)
	s_barrier
	s_setprio 1
	s_waitcnt lgkmcnt(0)
	v_mfma_f32_16x16x32_bf16 v[28:31], v[200:203], v[168:171], v[28:31]
	v_mfma_f32_16x16x32_bf16 v[24:27], v[200:203], v[176:179], v[24:27]
	v_mfma_f32_16x16x32_bf16 v[20:23], v[208:211], v[168:171], v[20:23]
	v_mfma_f32_16x16x32_bf16 v[16:19], v[208:211], v[176:179], v[16:19]
	v_mfma_f32_16x16x32_bf16 v[12:15], v[216:219], v[168:171], v[12:15]
	v_mfma_f32_16x16x32_bf16 v[8:11], v[216:219], v[176:179], v[8:11]
	v_mfma_f32_16x16x32_bf16 v[4:7], v[224:227], v[168:171], v[4:7]
	v_mfma_f32_16x16x32_bf16 v[0:3], v[224:227], v[176:179], v[0:3]
	v_mfma_f32_16x16x32_bf16 v[52:55], v[200:203], v[184:187], v[52:55]
	v_mfma_f32_16x16x32_bf16 v[60:63], v[200:203], v[192:195], v[60:63]
	v_mfma_f32_16x16x32_bf16 v[64:67], v[208:211], v[184:187], v[64:67]
	v_mfma_f32_16x16x32_bf16 v[68:71], v[208:211], v[192:195], v[68:71]
	v_mfma_f32_16x16x32_bf16 v[76:79], v[216:219], v[184:187], v[76:79]
	v_mfma_f32_16x16x32_bf16 v[80:83], v[216:219], v[192:195], v[80:83]
	v_mfma_f32_16x16x32_bf16 v[84:87], v[224:227], v[184:187], v[84:87]
	v_mfma_f32_16x16x32_bf16 v[92:95], v[224:227], v[192:195], v[92:95]
	v_mfma_f32_16x16x32_bf16 v[28:31], v[204:207], v[172:175], v[28:31]
	v_mfma_f32_16x16x32_bf16 v[24:27], v[204:207], v[180:183], v[24:27]
	v_mfma_f32_16x16x32_bf16 v[20:23], v[212:215], v[172:175], v[20:23]
	v_mfma_f32_16x16x32_bf16 v[16:19], v[212:215], v[180:183], v[16:19]
	v_mfma_f32_16x16x32_bf16 v[12:15], v[220:223], v[172:175], v[12:15]
	v_mfma_f32_16x16x32_bf16 v[8:11], v[220:223], v[180:183], v[8:11]
	v_mfma_f32_16x16x32_bf16 v[4:7], v[228:231], v[172:175], v[4:7]
	v_mfma_f32_16x16x32_bf16 v[0:3], v[228:231], v[180:183], v[0:3]
	v_mfma_f32_16x16x32_bf16 v[52:55], v[204:207], v[188:191], v[52:55]
	v_mfma_f32_16x16x32_bf16 v[60:63], v[204:207], v[196:199], v[60:63]
	v_mfma_f32_16x16x32_bf16 v[64:67], v[212:215], v[188:191], v[64:67]
	v_mfma_f32_16x16x32_bf16 v[68:71], v[212:215], v[196:199], v[68:71]
	v_mfma_f32_16x16x32_bf16 v[76:79], v[220:223], v[188:191], v[76:79]
	v_mfma_f32_16x16x32_bf16 v[80:83], v[220:223], v[196:199], v[80:83]
	v_mfma_f32_16x16x32_bf16 v[84:87], v[228:231], v[188:191], v[84:87]
	v_mfma_f32_16x16x32_bf16 v[92:95], v[228:231], v[196:199], v[92:95]
	s_setprio 0
	s_barrier
	s_add_u32 s65, s32, 0x4000
	s_mov_b32 m0, s65
	s_add_u32 s65, s32, 0x6000
	ds_read_b128 v[168:171], v149 offset:32768
	ds_read_b128 v[172:175], v149 offset:33792
	ds_read_b128 v[176:179], v149 offset:34816
	ds_read_b128 v[180:183], v149 offset:35840
	ds_read_b128 v[184:187], v149 offset:49152
	ds_read_b128 v[188:191], v149 offset:50176
	ds_read_b128 v[192:195], v149 offset:51200
	ds_read_b128 v[196:199], v149 offset:52224
	ds_read_b128 v[200:203], v148 offset:32768
	ds_read_b128 v[204:207], v148 offset:33792
	ds_read_b128 v[208:211], v148 offset:34816
	ds_read_b128 v[212:215], v148 offset:35840
	ds_read_b128 v[216:219], v148 offset:36864
	ds_read_b128 v[220:223], v148 offset:37888
	ds_read_b128 v[224:227], v148 offset:38912
	ds_read_b128 v[228:231], v148 offset:39936
	s_add_u32 s88, s10, s48
	s_addc_u32 s89, s11, s49
	global_load_lds_dwordx4 v142, s[88:89]
	s_mov_b32 m0, s65
	s_nop 0
	s_add_u32 s90, s10, s48
	s_addc_u32 s91, s11, s49
	global_load_lds_dwordx4 v144, s[90:91]
	s_waitcnt lgkmcnt(0)
	s_barrier
; #define STAGE(Pp, BASE, br, kt) do { const u16* _g = (BASE) + ((long)(br) * K + (long)(kt) * BK); \
;     __builtin_amdgcn_global_load_lds((const unsigned*)(_g + voff0), (unsigned*)((char*)(Pp) + tb16), 16, 0, 0); \
;     __builtin_amdgcn_global_load_lds((const unsigned*)(_g + voff1), (unsigned*)((char*)(Pp) + tb16 + 8192), 16, 0, 0); } while (0)
; #define LDA(dst, b, h) _Pragma("unroll") for (int m = 0; m < 4; ++m) _Pragma("unroll") for (int k = 0; k < 2; ++k) \
;     dst[m][k] = *reinterpret_cast<const bf16x8*>((const char*)shm + aB + (((b) * 2 + (h)) * 16384 + (m * 2 + k) * 1024))
; #define WAIT_V(n) asm volatile("s_waitcnt vmcnt(" #n ")" ::: "memory")
; #define WAIT_L(n) asm volatile("s_waitcnt lgkmcnt(" #n ")" ::: "memory")
; #define BAR __builtin_amdgcn_s_barrier()
; #define SCHED __builtin_amdgcn_sched_barrier(0)
; template <int MODE> ...
;     ...
;       WAIT_L(0); BAR; MMA2(0, 0, 0, 1); BAR; SCHED;
;       LDA(At, 1, 1); STAGE(SB(1, 0), Bt, bcol, t + 3); STAGE(SB(1, 1), Bt, bcol + HALF, t + 3); STAGE(SA(1, 0), A, brow, t + 3);
;       WAIT_V(6); WAIT_L(0); BAR; MMA2(1, 0, 1, 1); BAR; SCHED;
	s_setprio 1
	s_waitcnt lgkmcnt(0)
	v_mfma_f32_16x16x32_bf16 v[124:127], v[200:203], v[168:171], v[124:127]
	v_mfma_f32_16x16x32_bf16 v[120:123], v[200:203], v[176:179], v[120:123]
	v_mfma_f32_16x16x32_bf16 v[116:119], v[208:211], v[168:171], v[116:119]
	v_mfma_f32_16x16x32_bf16 v[112:115], v[208:211], v[176:179], v[112:115]
	v_mfma_f32_16x16x32_bf16 v[108:111], v[216:219], v[168:171], v[108:111]
	v_mfma_f32_16x16x32_bf16 v[104:107], v[216:219], v[176:179], v[104:107]
	v_mfma_f32_16x16x32_bf16 v[100:103], v[224:227], v[168:171], v[100:103]
	v_mfma_f32_16x16x32_bf16 v[96:99], v[224:227], v[176:179], v[96:99]
	v_mfma_f32_16x16x32_bf16 v[88:91], v[200:203], v[184:187], v[88:91]
	v_mfma_f32_16x16x32_bf16 v[72:75], v[200:203], v[192:195], v[72:75]
	v_mfma_f32_16x16x32_bf16 v[56:59], v[208:211], v[184:187], v[56:59]
	v_mfma_f32_16x16x32_bf16 v[48:51], v[208:211], v[192:195], v[48:51]
	v_mfma_f32_16x16x32_bf16 v[44:47], v[216:219], v[184:187], v[44:47]
	v_mfma_f32_16x16x32_bf16 v[40:43], v[216:219], v[192:195], v[40:43]
	v_mfma_f32_16x16x32_bf16 v[36:39], v[224:227], v[184:187], v[36:39]
	v_mfma_f32_16x16x32_bf16 v[32:35], v[224:227], v[192:195], v[32:35]
	v_mfma_f32_16x16x32_bf16 v[124:127], v[204:207], v[172:175], v[124:127]
	v_mfma_f32_16x16x32_bf16 v[120:123], v[204:207], v[180:183], v[120:123]
	v_mfma_f32_16x16x32_bf16 v[116:119], v[212:215], v[172:175], v[116:119]
	v_mfma_f32_16x16x32_bf16 v[112:115], v[212:215], v[180:183], v[112:115]
	v_mfma_f32_16x16x32_bf16 v[108:111], v[220:223], v[172:175], v[108:111]
	v_mfma_f32_16x16x32_bf16 v[104:107], v[220:223], v[180:183], v[104:107]
	v_mfma_f32_16x16x32_bf16 v[100:103], v[228:231], v[172:175], v[100:103]
	v_mfma_f32_16x16x32_bf16 v[96:99], v[228:231], v[180:183], v[96:99]
	v_mfma_f32_16x16x32_bf16 v[88:91], v[204:207], v[188:191], v[88:91]
	v_mfma_f32_16x16x32_bf16 v[72:75], v[204:207], v[196:199], v[72:75]
	v_mfma_f32_16x16x32_bf16 v[56:59], v[212:215], v[188:191], v[56:59]
	v_mfma_f32_16x16x32_bf16 v[48:51], v[212:215], v[196:199], v[48:51]
	v_mfma_f32_16x16x32_bf16 v[44:47], v[220:223], v[188:191], v[44:47]
	v_mfma_f32_16x16x32_bf16 v[40:43], v[220:223], v[196:199], v[40:43]
	v_mfma_f32_16x16x32_bf16 v[36:39], v[228:231], v[188:191], v[36:39]
	v_mfma_f32_16x16x32_bf16 v[32:35], v[228:231], v[196:199], v[32:35]
	s_setprio 0
	s_barrier
	s_add_u32 s65, s32, 0x18000
	s_mov_b32 m0, s65
	s_add_u32 s65, s32, 0x1a000
	ds_read_b128 v[200:203], v148 offset:49152
	ds_read_b128 v[204:207], v148 offset:50176
	ds_read_b128 v[208:211], v148 offset:51200
	ds_read_b128 v[212:215], v148 offset:52224
	ds_read_b128 v[216:219], v148 offset:53248
	ds_read_b128 v[220:223], v148 offset:54272
	ds_read_b128 v[224:227], v148 offset:55296
	ds_read_b128 v[228:231], v148 offset:56320
	s_add_u32 s92, s10, s50
	s_addc_u32 s93, s11, s51
	global_load_lds_dwordx4 v138, s[92:93]
	s_mov_b32 m0, s65
	s_add_u32 s65, s32, 0x1c000
	s_add_u32 s96, s10, s50
	s_addc_u32 s97, s11, s51
	global_load_lds_dwordx4 v140, s[96:97]
	s_mov_b32 m0, s65
	s_add_u32 s65, s32, 0x1e000
	s_add_u32 s88, s10, s60
	s_addc_u32 s89, s11, s61
	global_load_lds_dwordx4 v138, s[88:89]
	s_mov_b32 m0, s65
	s_add_u32 s65, s32, 0x8000
	s_add_u32 s90, s10, s60
	s_addc_u32 s91, s11, s61
	global_load_lds_dwordx4 v140, s[90:91]
	s_mov_b32 m0, s65
	s_add_u32 s65, s32, 0xa000
	s_add_u32 s92, s10, s62
	s_addc_u32 s93, s11, s63
	global_load_lds_dwordx4 v142, s[92:93]
	s_mov_b32 m0, s65
	s_nop 0
	s_add_u32 s96, s10, s62
	s_addc_u32 s97, s11, s63
	global_load_lds_dwordx4 v144, s[96:97]
	s_waitcnt vmcnt(6)
	s_waitcnt lgkmcnt(0)
	s_barrier
	s_setprio 1
	s_waitcnt lgkmcnt(0)
	v_mfma_f32_16x16x32_bf16 v[28:31], v[200:203], v[168:171], v[28:31]
	v_mfma_f32_16x16x32_bf16 v[24:27], v[200:203], v[176:179], v[24:27]
	v_mfma_f32_16x16x32_bf16 v[20:23], v[208:211], v[168:171], v[20:23]
	v_mfma_f32_16x16x32_bf16 v[16:19], v[208:211], v[176:179], v[16:19]
	v_mfma_f32_16x16x32_bf16 v[12:15], v[216:219], v[168:171], v[12:15]
	v_mfma_f32_16x16x32_bf16 v[8:11], v[216:219], v[176:179], v[8:11]
	v_mfma_f32_16x16x32_bf16 v[4:7], v[224:227], v[168:171], v[4:7]
	v_mfma_f32_16x16x32_bf16 v[0:3], v[224:227], v[176:179], v[0:3]
	v_mfma_f32_16x16x32_bf16 v[52:55], v[200:203], v[184:187], v[52:55]
	v_mfma_f32_16x16x32_bf16 v[60:63], v[200:203], v[192:195], v[60:63]
	v_mfma_f32_16x16x32_bf16 v[64:67], v[208:211], v[184:187], v[64:67]
	v_mfma_f32_16x16x32_bf16 v[68:71], v[208:211], v[192:195], v[68:71]
	v_mfma_f32_16x16x32_bf16 v[76:79], v[216:219], v[184:187], v[76:79]
	v_mfma_f32_16x16x32_bf16 v[80:83], v[216:219], v[192:195], v[80:83]
	v_mfma_f32_16x16x32_bf16 v[84:87], v[224:227], v[184:187], v[84:87]
	v_mfma_f32_16x16x32_bf16 v[92:95], v[224:227], v[192:195], v[92:95]
	v_mfma_f32_16x16x32_bf16 v[28:31], v[204:207], v[172:175], v[28:31]
	v_mfma_f32_16x16x32_bf16 v[24:27], v[204:207], v[180:183], v[24:27]
	v_mfma_f32_16x16x32_bf16 v[20:23], v[212:215], v[172:175], v[20:23]
	v_mfma_f32_16x16x32_bf16 v[16:19], v[212:215], v[180:183], v[16:19]
	v_mfma_f32_16x16x32_bf16 v[12:15], v[220:223], v[172:175], v[12:15]
	v_mfma_f32_16x16x32_bf16 v[8:11], v[220:223], v[180:183], v[8:11]
	v_mfma_f32_16x16x32_bf16 v[4:7], v[228:231], v[172:175], v[4:7]
	v_mfma_f32_16x16x32_bf16 v[0:3], v[228:231], v[180:183], v[0:3]
	v_mfma_f32_16x16x32_bf16 v[52:55], v[204:207], v[188:191], v[52:55]
	v_mfma_f32_16x16x32_bf16 v[60:63], v[204:207], v[196:199], v[60:63]
	v_mfma_f32_16x16x32_bf16 v[64:67], v[212:215], v[188:191], v[64:67]
	v_mfma_f32_16x16x32_bf16 v[68:71], v[212:215], v[196:199], v[68:71]
	v_mfma_f32_16x16x32_bf16 v[76:79], v[220:223], v[188:191], v[76:79]
	v_mfma_f32_16x16x32_bf16 v[80:83], v[220:223], v[196:199], v[80:83]
	v_mfma_f32_16x16x32_bf16 v[84:87], v[228:231], v[188:191], v[84:87]
	v_mfma_f32_16x16x32_bf16 v[92:95], v[228:231], v[196:199], v[92:95]
	s_setprio 0
	s_barrier
; #define STAGE(Pp, BASE, br, kt) do { const u16* _g = (BASE) + ((long)(br) * K + (long)(kt) * BK); \
;     __builtin_amdgcn_global_load_lds((const unsigned*)(_g + voff0), (unsigned*)((char*)(Pp) + tb16), 16, 0, 0); \
;     __builtin_amdgcn_global_load_lds((const unsigned*)(_g + voff1), (unsigned*)((char*)(Pp) + tb16 + 8192), 16, 0, 0); } while (0)
; #define LDA(dst, b, h) _Pragma("unroll") for (int m = 0; m < 4; ++m) _Pragma("unroll") for (int k = 0; k < 2; ++k) \
;     dst[m][k] = *reinterpret_cast<const bf16x8*>((const char*)shm + aB + (((b) * 2 + (h)) * 16384 + (m * 2 + k) * 1024))
; #define LDB(dst, b, h) _Pragma("unroll") for (int n = 0; n < 2; ++n) _Pragma("unroll") for (int k = 0; k < 2; ++k) \
;     dst[n][k] = *reinterpret_cast<const bf16x8*>((const char*)shm + bB + (((b) * 2 + (h)) * 16384 + (n * 2 + k) * 1024))
; #define WAIT_V(n) asm volatile("s_waitcnt vmcnt(" #n ")" ::: "memory")
; #define WAIT_L(n) asm volatile("s_waitcnt lgkmcnt(" #n ")" ::: "memory")
; #define BAR __builtin_amdgcn_s_barrier()
; #define SCHED __builtin_amdgcn_sched_barrier(0)
; template <int MODE> ...
;     ...
;     }
;     {
;       LDB(B0, 0, 0); LDB(B1, 0, 1); LDA(At, 0, 0); STAGE(SA(1, 1), A, brow + HALF, nt - 1);
;       WAIT_L(0); BAR; MMA2(0, 0, 0, 1); BAR; SCHED;
;       LDA(At, 0, 1); WAIT_V(0); WAIT_L(0); BAR; MMA2(1, 0, 1, 1); BAR; SCHED;
	s_add_i32 s35, s35, 2
	s_add_u32 s10, s10, 0x100
	s_addc_u32 s11, s11, 0
	s_cmp_lt_u32 s35, 60
	s_cbranch_scc1 .LBB0_591
	s_add_u32 s8, s8, 0x1f80
	v_readfirstlane_b32 s10, v165
	s_addc_u32 s9, s9, 0
	s_mov_b32 m0, s10
	v_readfirstlane_b32 s10, v166
	ds_read_b128 v[138:141], v149
	ds_read_b128 v[142:145], v149 offset:1024
	ds_read_b128 v[168:171], v149 offset:2048
	ds_read_b128 v[172:175], v149 offset:3072
	ds_read_b128 v[176:179], v149 offset:16384
	ds_read_b128 v[180:183], v149 offset:17408
	ds_read_b128 v[184:187], v149 offset:18432
	ds_read_b128 v[188:191], v149 offset:19456
	ds_read_b128 v[192:195], v148
	ds_read_b128 v[196:199], v148 offset:1024
	ds_read_b128 v[200:203], v148 offset:2048
	ds_read_b128 v[204:207], v148 offset:3072
	ds_read_b128 v[208:211], v148 offset:4096
	ds_read_b128 v[212:215], v148 offset:5120
	ds_read_b128 v[216:219], v148 offset:6144
	ds_read_b128 v[220:223], v148 offset:7168
	global_load_lds_dwordx4 v134, s[8:9]
	s_mov_b32 m0, s10
	s_nop 0
	global_load_lds_dwordx4 v136, s[8:9]
	s_waitcnt lgkmcnt(0)
	s_barrier
	s_setprio 1
	s_waitcnt lgkmcnt(0)
	v_mfma_f32_16x16x32_bf16 v[124:127], v[192:195], v[138:141], v[124:127]
	v_mfma_f32_16x16x32_bf16 v[120:123], v[192:195], v[168:171], v[120:123]
	v_mfma_f32_16x16x32_bf16 v[116:119], v[200:203], v[138:141], v[116:119]
	v_mfma_f32_16x16x32_bf16 v[112:115], v[200:203], v[168:171], v[112:115]
	v_mfma_f32_16x16x32_bf16 v[108:111], v[208:211], v[138:141], v[108:111]
	v_mfma_f32_16x16x32_bf16 v[104:107], v[208:211], v[168:171], v[104:107]
	v_mfma_f32_16x16x32_bf16 v[96:99], v[216:219], v[168:171], v[96:99]
	v_mfma_f32_16x16x32_bf16 v[88:91], v[192:195], v[176:179], v[88:91]
	v_mfma_f32_16x16x32_bf16 v[72:75], v[192:195], v[184:187], v[72:75]
	v_mfma_f32_16x16x32_bf16 v[56:59], v[200:203], v[176:179], v[56:59]
	v_mfma_f32_16x16x32_bf16 v[48:51], v[200:203], v[184:187], v[48:51]
	v_mfma_f32_16x16x32_bf16 v[44:47], v[208:211], v[176:179], v[44:47]
	v_mfma_f32_16x16x32_bf16 v[40:43], v[208:211], v[184:187], v[40:43]
	v_mfma_f32_16x16x32_bf16 v[36:39], v[216:219], v[176:179], v[36:39]
	v_mfma_f32_16x16x32_bf16 v[32:35], v[216:219], v[184:187], v[32:35]
	v_mfma_f32_16x16x32_bf16 v[124:127], v[196:199], v[142:145], v[124:127]
	v_mfma_f32_16x16x32_bf16 v[120:123], v[196:199], v[172:175], v[120:123]
	v_mfma_f32_16x16x32_bf16 v[116:119], v[204:207], v[142:145], v[116:119]
	v_mfma_f32_16x16x32_bf16 v[112:115], v[204:207], v[172:175], v[112:115]
	v_mfma_f32_16x16x32_bf16 v[108:111], v[212:215], v[142:145], v[108:111]
	v_mfma_f32_16x16x32_bf16 v[104:107], v[212:215], v[172:175], v[104:107]
	v_mfma_f32_16x16x32_bf16 v[100:103], v[216:219], v[138:141], v[100:103]
	v_mfma_f32_16x16x32_bf16 v[96:99], v[220:223], v[172:175], v[96:99]
	v_mfma_f32_16x16x32_bf16 v[88:91], v[196:199], v[180:183], v[88:91]
	v_mfma_f32_16x16x32_bf16 v[72:75], v[196:199], v[188:191], v[72:75]
	v_mfma_f32_16x16x32_bf16 v[56:59], v[204:207], v[180:183], v[56:59]
	v_mfma_f32_16x16x32_bf16 v[48:51], v[204:207], v[188:191], v[48:51]
	v_mfma_f32_16x16x32_bf16 v[44:47], v[212:215], v[180:183], v[44:47]
	v_mfma_f32_16x16x32_bf16 v[40:43], v[212:215], v[188:191], v[40:43]
	v_mfma_f32_16x16x32_bf16 v[36:39], v[220:223], v[180:183], v[36:39]
	v_mfma_f32_16x16x32_bf16 v[32:35], v[220:223], v[188:191], v[32:35]
	v_mfma_f32_16x16x32_bf16 v[224:227], v[220:223], v[142:145], v[100:103]
	s_setprio 0
	s_barrier
	s_nop 0
	ds_read_b128 v[100:103], v148 offset:16384
	ds_read_b128 v[192:195], v148 offset:17408
	ds_read_b128 v[196:199], v148 offset:18432
	ds_read_b128 v[200:203], v148 offset:19456
	ds_read_b128 v[204:207], v148 offset:20480
	ds_read_b128 v[208:211], v148 offset:21504
	ds_read_b128 v[212:215], v148 offset:22528
	ds_read_b128 v[216:219], v148 offset:23552
	s_waitcnt vmcnt(0)
	s_waitcnt lgkmcnt(0)
	s_barrier
	s_setprio 1
	s_waitcnt lgkmcnt(0)
	v_mfma_f32_16x16x32_bf16 v[28:31], v[100:103], v[138:141], v[28:31]
	v_mfma_f32_16x16x32_bf16 v[20:23], v[196:199], v[138:141], v[20:23]
	v_mfma_f32_16x16x32_bf16 v[12:15], v[204:207], v[138:141], v[12:15]
	v_mfma_f32_16x16x32_bf16 v[4:7], v[212:215], v[138:141], v[4:7]
	v_mfma_f32_16x16x32_bf16 v[0:3], v[212:215], v[168:171], v[0:3]
	v_mfma_f32_16x16x32_bf16 v[28:31], v[192:195], v[142:145], v[28:31]
	v_mfma_f32_16x16x32_bf16 v[20:23], v[200:203], v[142:145], v[20:23]
	v_mfma_f32_16x16x32_bf16 v[220:223], v[208:211], v[142:145], v[12:15]
	v_mfma_f32_16x16x32_bf16 v[138:141], v[216:219], v[142:145], v[4:7]
	v_mfma_f32_16x16x32_bf16 v[142:145], v[216:219], v[172:175], v[0:3]
	v_mfma_f32_16x16x32_bf16 v[0:3], v[100:103], v[176:179], v[52:55]
	v_mfma_f32_16x16x32_bf16 v[24:27], v[100:103], v[168:171], v[24:27]
	v_mfma_f32_16x16x32_bf16 v[16:19], v[196:199], v[168:171], v[16:19]
	v_mfma_f32_16x16x32_bf16 v[8:11], v[204:207], v[168:171], v[8:11]
	v_mfma_f32_16x16x32_bf16 v[168:171], v[192:195], v[180:183], v[0:3]
	v_mfma_f32_16x16x32_bf16 v[0:3], v[100:103], v[184:187], v[60:63]
	v_mfma_f32_16x16x32_bf16 v[24:27], v[192:195], v[172:175], v[24:27]
	v_mfma_f32_16x16x32_bf16 v[16:19], v[200:203], v[172:175], v[16:19]
	v_mfma_f32_16x16x32_bf16 v[228:231], v[208:211], v[172:175], v[8:11]
	v_mfma_f32_16x16x32_bf16 v[172:175], v[192:195], v[188:191], v[0:3]
	v_mfma_f32_16x16x32_bf16 v[0:3], v[196:199], v[176:179], v[64:67]
	v_mfma_f32_16x16x32_bf16 v[192:195], v[200:203], v[180:183], v[0:3]
	v_mfma_f32_16x16x32_bf16 v[0:3], v[196:199], v[184:187], v[68:71]
	v_mfma_f32_16x16x32_bf16 v[196:199], v[200:203], v[188:191], v[0:3]
	v_mfma_f32_16x16x32_bf16 v[0:3], v[204:207], v[176:179], v[76:79]
	v_mfma_f32_16x16x32_bf16 v[200:203], v[208:211], v[180:183], v[0:3]
	v_mfma_f32_16x16x32_bf16 v[0:3], v[204:207], v[184:187], v[80:83]
	v_mfma_f32_16x16x32_bf16 v[204:207], v[208:211], v[188:191], v[0:3]
	v_mfma_f32_16x16x32_bf16 v[0:3], v[212:215], v[176:179], v[84:87]
	v_mfma_f32_16x16x32_bf16 v[176:179], v[216:219], v[180:183], v[0:3]
	v_mfma_f32_16x16x32_bf16 v[0:3], v[212:215], v[184:187], v[92:95]
	v_mfma_f32_16x16x32_bf16 v[180:183], v[216:219], v[188:191], v[0:3]
	s_setprio 0
	s_barrier
; #define LDA(dst, b, h) _Pragma("unroll") for (int m = 0; m < 4; ++m) _Pragma("unroll") for (int k = 0; k < 2; ++k) \
;     dst[m][k] = *reinterpret_cast<const bf16x8*>((const char*)shm + aB + (((b) * 2 + (h)) * 16384 + (m * 2 + k) * 1024))
; #define LDB(dst, b, h) _Pragma("unroll") for (int n = 0; n < 2; ++n) _Pragma("unroll") for (int k = 0; k < 2; ++k) \
;     dst[n][k] = *reinterpret_cast<const bf16x8*>((const char*)shm + bB + (((b) * 2 + (h)) * 16384 + (n * 2 + k) * 1024))
; #define WAIT_L(n) asm volatile("s_waitcnt lgkmcnt(" #n ")" ::: "memory")
; #define BAR __builtin_amdgcn_s_barrier()
; #define SCHED __builtin_amdgcn_sched_barrier(0)
; template <int MODE> ...
;     ...
;       LDB(B0, 1, 0); LDB(B1, 1, 1); LDA(At, 1, 0); WAIT_L(0); BAR; MMA2(0, 0, 0, 1); BAR; SCHED;
;       LDA(At, 1, 1); WAIT_L(0); BAR; MMA2(1, 0, 1, 1); BAR; SCHED;
;     }
;     ...
;     if (wr == 0) BAR;
	ds_read_b128 v[64:67], v149 offset:32768
	ds_read_b128 v[184:187], v149 offset:33792
	ds_read_b128 v[188:191], v149 offset:34816
	ds_read_b128 v[208:211], v149 offset:35840
	ds_read_b128 v[212:215], v149 offset:49152
	ds_read_b128 v[216:219], v149 offset:50176
	ds_read_b128 v[232:235], v149 offset:51200
	ds_read_b128 v[236:239], v149 offset:52224
	ds_read_b128 v[8:11], v148 offset:32768
	ds_read_b128 v[52:55], v148 offset:33792
	ds_read_b128 v[60:63], v148 offset:34816
	ds_read_b128 v[68:71], v148 offset:35840
	ds_read_b128 v[76:79], v148 offset:36864
	ds_read_b128 v[80:83], v148 offset:37888
	ds_read_b128 v[240:243], v148 offset:38912
	ds_read_b128 v[244:247], v148 offset:39936
	s_waitcnt lgkmcnt(0)
	s_barrier
	s_setprio 1
	s_waitcnt lgkmcnt(0)
	v_mfma_f32_16x16x32_bf16 v[12:15], v[60:63], v[64:67], v[116:119]
	v_mfma_f32_16x16x32_bf16 v[0:3], v[8:11], v[64:67], v[124:127]
	v_mfma_f32_16x16x32_bf16 v[124:127], v[68:71], v[184:187], v[12:15]
	v_mfma_f32_16x16x32_bf16 v[12:15], v[60:63], v[188:191], v[112:115]
	v_mfma_f32_16x16x32_bf16 v[116:119], v[68:71], v[208:211], v[12:15]
	v_mfma_f32_16x16x32_bf16 v[12:15], v[76:79], v[64:67], v[108:111]
	v_mfma_f32_16x16x32_bf16 v[108:111], v[80:83], v[184:187], v[12:15]
	v_mfma_f32_16x16x32_bf16 v[12:15], v[76:79], v[188:191], v[104:107]
	v_mfma_f32_16x16x32_bf16 v[100:103], v[80:83], v[208:211], v[12:15]
	v_mfma_f32_16x16x32_bf16 v[12:15], v[240:243], v[64:67], v[224:227]
	v_mfma_f32_16x16x32_bf16 v[92:95], v[244:247], v[184:187], v[12:15]
	v_mfma_f32_16x16x32_bf16 v[12:15], v[240:243], v[188:191], v[96:99]
	v_mfma_f32_16x16x32_bf16 v[4:7], v[52:55], v[184:187], v[0:3]
	v_mfma_f32_16x16x32_bf16 v[0:3], v[8:11], v[188:191], v[120:123]
	v_mfma_f32_16x16x32_bf16 v[84:87], v[244:247], v[208:211], v[12:15]
	v_mfma_f32_16x16x32_bf16 v[12:15], v[8:11], v[212:215], v[88:91]
	v_mfma_f32_16x16x32_bf16 v[8:11], v[8:11], v[232:235], v[72:75]
	v_mfma_f32_16x16x32_bf16 v[0:3], v[52:55], v[208:211], v[0:3]
	v_mfma_f32_16x16x32_bf16 v[12:15], v[52:55], v[216:219], v[12:15]
	v_mfma_f32_16x16x32_bf16 v[8:11], v[52:55], v[236:239], v[8:11]
	v_mfma_f32_16x16x32_bf16 v[52:55], v[60:63], v[212:215], v[56:59]
	v_mfma_f32_16x16x32_bf16 v[48:51], v[60:63], v[232:235], v[48:51]
	v_mfma_f32_16x16x32_bf16 v[44:47], v[76:79], v[212:215], v[44:47]
	v_mfma_f32_16x16x32_bf16 v[40:43], v[76:79], v[232:235], v[40:43]
	v_mfma_f32_16x16x32_bf16 v[36:39], v[240:243], v[212:215], v[36:39]
	v_mfma_f32_16x16x32_bf16 v[32:35], v[240:243], v[232:235], v[32:35]
	v_mfma_f32_16x16x32_bf16 v[120:123], v[68:71], v[216:219], v[52:55]
	v_mfma_f32_16x16x32_bf16 v[112:115], v[68:71], v[236:239], v[48:51]
	v_mfma_f32_16x16x32_bf16 v[104:107], v[80:83], v[216:219], v[44:47]
	v_mfma_f32_16x16x32_bf16 v[96:99], v[80:83], v[236:239], v[40:43]
	v_mfma_f32_16x16x32_bf16 v[88:91], v[244:247], v[216:219], v[36:39]
	v_mfma_f32_16x16x32_bf16 v[80:83], v[244:247], v[236:239], v[32:35]
	s_setprio 0
	s_barrier
	s_nop 0
	ds_read_b128 v[32:35], v148 offset:49152
	ds_read_b128 v[40:43], v148 offset:50176
	ds_read_b128 v[48:51], v148 offset:51200
	ds_read_b128 v[224:227], v148 offset:52224
	ds_read_b128 v[240:243], v148 offset:53248
	ds_read_b128 v[244:247], v148 offset:54272
	ds_read_b128 v[248:251], v148 offset:55296
	ds_read_b128 v[130:133], v148 offset:56320
	s_waitcnt lgkmcnt(0)
	s_barrier
	s_setprio 1
	s_waitcnt lgkmcnt(0)
	v_mfma_f32_16x16x32_bf16 v[24:27], v[32:35], v[188:191], v[24:27]
	v_mfma_f32_16x16x32_bf16 v[16:19], v[48:51], v[188:191], v[16:19]
	v_mfma_f32_16x16x32_bf16 v[68:71], v[40:43], v[208:211], v[24:27]
	v_mfma_f32_16x16x32_bf16 v[52:55], v[224:227], v[208:211], v[16:19]
	v_mfma_f32_16x16x32_bf16 v[16:19], v[240:243], v[64:67], v[220:223]
	v_mfma_f32_16x16x32_bf16 v[24:27], v[32:35], v[212:215], v[168:171]
	v_mfma_f32_16x16x32_bf16 v[44:47], v[244:247], v[184:187], v[16:19]
	v_mfma_f32_16x16x32_bf16 v[16:19], v[240:243], v[188:191], v[228:231]
	v_mfma_f32_16x16x32_bf16 v[72:75], v[40:43], v[216:219], v[24:27]
	v_mfma_f32_16x16x32_bf16 v[24:27], v[32:35], v[232:235], v[172:175]
	v_mfma_f32_16x16x32_bf16 v[28:31], v[32:35], v[64:67], v[28:31]
	v_mfma_f32_16x16x32_bf16 v[20:23], v[48:51], v[64:67], v[20:23]
	v_mfma_f32_16x16x32_bf16 v[36:39], v[244:247], v[208:211], v[16:19]
	v_mfma_f32_16x16x32_bf16 v[16:19], v[248:251], v[64:67], v[138:141]
	v_mfma_f32_16x16x32_bf16 v[64:67], v[40:43], v[236:239], v[24:27]
	v_mfma_f32_16x16x32_bf16 v[24:27], v[48:51], v[212:215], v[192:195]
	v_mfma_f32_16x16x32_bf16 v[56:59], v[224:227], v[216:219], v[24:27]
	v_mfma_f32_16x16x32_bf16 v[24:27], v[48:51], v[232:235], v[196:199]
	v_mfma_f32_16x16x32_bf16 v[48:51], v[224:227], v[236:239], v[24:27]
	v_mfma_f32_16x16x32_bf16 v[24:27], v[240:243], v[212:215], v[200:203]
	v_mfma_f32_16x16x32_bf16 v[76:79], v[40:43], v[184:187], v[28:31]
	v_mfma_f32_16x16x32_bf16 v[40:43], v[244:247], v[216:219], v[24:27]
	v_mfma_f32_16x16x32_bf16 v[24:27], v[240:243], v[232:235], v[204:207]
	v_mfma_f32_16x16x32_bf16 v[32:35], v[244:247], v[236:239], v[24:27]
	v_mfma_f32_16x16x32_bf16 v[24:27], v[248:251], v[212:215], v[176:179]
	v_mfma_f32_16x16x32_bf16 v[60:63], v[224:227], v[184:187], v[20:23]
	v_mfma_f32_16x16x32_bf16 v[20:23], v[130:133], v[184:187], v[16:19]
	v_mfma_f32_16x16x32_bf16 v[16:19], v[248:251], v[188:191], v[142:145]
	v_mfma_f32_16x16x32_bf16 v[28:31], v[130:133], v[216:219], v[24:27]
	v_mfma_f32_16x16x32_bf16 v[24:27], v[248:251], v[232:235], v[180:183]
	v_mfma_f32_16x16x32_bf16 v[16:19], v[130:133], v[208:211], v[16:19]
	v_mfma_f32_16x16x32_bf16 v[24:27], v[130:133], v[236:239], v[24:27]
	s_setprio 0
	s_barrier
	s_and_saveexec_b64 s[8:9], s[6:7]
	s_cbranch_execz .LBB0_594
	s_barrier

; #define STAGE(Pp, BASE, br, kt) do { const u16* _g = (BASE) + ((long)(br) * K + (long)(kt) * BK); \
;     __builtin_amdgcn_global_load_lds((const unsigned*)(_g + voff0), (unsigned*)((char*)(Pp) + tb16), 16, 0, 0); \
;     __builtin_amdgcn_global_load_lds((const unsigned*)(_g + voff1), (unsigned*)((char*)(Pp) + tb16 + 8192), 16, 0, 0); } while (0)
; #define LDA(dst, b, h) _Pragma("unroll") for (int m = 0; m < 4; ++m) _Pragma("unroll") for (int k = 0; k < 2; ++k) \
;     dst[m][k] = *reinterpret_cast<const bf16x8*>((const char*)shm + aB + (((b) * 2 + (h)) * 16384 + (m * 2 + k) * 1024))
; #define LDB(dst, b, h) _Pragma("unroll") for (int n = 0; n < 2; ++n) _Pragma("unroll") for (int k = 0; k < 2; ++k) \
;     dst[n][k] = *reinterpret_cast<const bf16x8*>((const char*)shm + bB + (((b) * 2 + (h)) * 16384 + (n * 2 + k) * 1024))
; #define WAIT_L(n) asm volatile("s_waitcnt lgkmcnt(" #n ")" ::: "memory")
; #define BAR __builtin_amdgcn_s_barrier()
; #define SCHED __builtin_amdgcn_sched_barrier(0)
; template <int MODE> ...
;     ...
;     f32x4 acc[2][2][4][2] = {};
;     bf16x8 At[4][2], B0[2][2], B1[2][2];
;     ...
;       LDB(B0, 0, 0); LDB(B1, 0, 1); LDA(At, 0, 0); STAGE(SA(1, 1), A, brow + HALF, t + 1);
;       WAIT_L(0); BAR; MMA2(0, 0, 0, 1); BAR; SCHED;
.LBB0_847:
	s_or_b64 exec, exec, s[68:69]
	v_mov_b32_e32 v0, 0
	s_ashr_i32 s51, s50, 31
	s_ashr_i32 s49, s48, 31
	s_ashr_i32 s47, s46, 31
	v_lshl_add_u64 v[138:139], v[130:131], 0, s[62:63]
	v_lshl_add_u64 v[140:141], v[132:133], 0, s[62:63]
	v_lshl_add_u64 v[142:143], v[130:131], 0, s[66:67]
	v_lshl_add_u64 v[144:145], v[132:133], 0, s[66:67]
	v_lshl_add_u64 v[146:147], v[130:131], 0, s[64:65]
	v_lshl_add_u64 v[148:149], v[132:133], 0, s[64:65]
	s_mov_b32 s45, -2
	s_mov_b64 s[62:63], s[56:57]
	v_mov_b32_e32 v1, v0
	v_mov_b32_e32 v2, v0
	v_mov_b32_e32 v3, v0
	v_mov_b32_e32 v4, v0
	v_mov_b32_e32 v5, v0
	v_mov_b32_e32 v6, v0
	v_mov_b32_e32 v7, v0
	v_mov_b32_e32 v8, v0
	v_mov_b32_e32 v9, v0
	v_mov_b32_e32 v10, v0
	v_mov_b32_e32 v11, v0
	v_mov_b32_e32 v12, v0
	v_mov_b32_e32 v13, v0
	v_mov_b32_e32 v14, v0
	v_mov_b32_e32 v15, v0
	v_mov_b32_e32 v16, v0
	v_mov_b32_e32 v17, v0
	v_mov_b32_e32 v18, v0
	v_mov_b32_e32 v19, v0
	v_mov_b32_e32 v20, v0
	v_mov_b32_e32 v21, v0
	v_mov_b32_e32 v22, v0
	v_mov_b32_e32 v23, v0
	v_mov_b32_e32 v24, v0
	v_mov_b32_e32 v25, v0
	v_mov_b32_e32 v26, v0
	v_mov_b32_e32 v27, v0
	v_mov_b32_e32 v28, v0
	v_mov_b32_e32 v29, v0
	v_mov_b32_e32 v30, v0
	v_mov_b32_e32 v31, v0
	v_mov_b32_e32 v32, v0
	v_mov_b32_e32 v33, v0
	v_mov_b32_e32 v34, v0
	v_mov_b32_e32 v35, v0
	v_mov_b32_e32 v36, v0
	v_mov_b32_e32 v37, v0
	v_mov_b32_e32 v38, v0
	v_mov_b32_e32 v39, v0
	v_mov_b32_e32 v40, v0
	v_mov_b32_e32 v41, v0
	v_mov_b32_e32 v42, v0
	v_mov_b32_e32 v43, v0
	v_mov_b32_e32 v44, v0
	v_mov_b32_e32 v45, v0
	v_mov_b32_e32 v46, v0
	v_mov_b32_e32 v47, v0
	v_mov_b32_e32 v48, v0
	v_mov_b32_e32 v49, v0
	v_mov_b32_e32 v50, v0
	v_mov_b32_e32 v51, v0
	v_mov_b32_e32 v52, v0
	v_mov_b32_e32 v53, v0
	v_mov_b32_e32 v54, v0
	v_mov_b32_e32 v55, v0
	v_mov_b32_e32 v56, v0
	v_mov_b32_e32 v57, v0
	v_mov_b32_e32 v58, v0
	v_mov_b32_e32 v59, v0
	v_mov_b32_e32 v60, v0
	v_mov_b32_e32 v61, v0
	v_mov_b32_e32 v62, v0
	v_mov_b32_e32 v63, v0
	v_mov_b32_e32 v64, v0
	v_mov_b32_e32 v65, v0
	v_mov_b32_e32 v66, v0
	v_mov_b32_e32 v67, v0
	v_mov_b32_e32 v68, v0
	v_mov_b32_e32 v69, v0
	v_mov_b32_e32 v70, v0
	v_mov_b32_e32 v71, v0
	v_mov_b32_e32 v72, v0
	v_mov_b32_e32 v73, v0
	v_mov_b32_e32 v74, v0
	v_mov_b32_e32 v75, v0
	v_mov_b32_e32 v76, v0
	v_mov_b32_e32 v77, v0
	v_mov_b32_e32 v78, v0
	v_mov_b32_e32 v79, v0
	v_mov_b32_e32 v80, v0
	v_mov_b32_e32 v81, v0
	v_mov_b32_e32 v82, v0
	v_mov_b32_e32 v83, v0
	v_mov_b32_e32 v84, v0
	v_mov_b32_e32 v85, v0
	v_mov_b32_e32 v86, v0
	v_mov_b32_e32 v87, v0
	v_mov_b32_e32 v88, v0
	v_mov_b32_e32 v89, v0
	v_mov_b32_e32 v90, v0
	v_mov_b32_e32 v91, v0
	v_mov_b32_e32 v92, v0
	v_mov_b32_e32 v93, v0
	v_mov_b32_e32 v94, v0
	v_mov_b32_e32 v95, v0
	v_mov_b32_e32 v96, v0
	v_mov_b32_e32 v97, v0
	v_mov_b32_e32 v98, v0
	v_mov_b32_e32 v99, v0
	v_mov_b32_e32 v100, v0
	v_mov_b32_e32 v101, v0
	v_mov_b32_e32 v102, v0
	v_mov_b32_e32 v103, v0
	v_mov_b32_e32 v104, v0
	v_mov_b32_e32 v105, v0
	v_mov_b32_e32 v106, v0
	v_mov_b32_e32 v107, v0
	v_mov_b32_e32 v108, v0
	v_mov_b32_e32 v109, v0
	v_mov_b32_e32 v110, v0
	v_mov_b32_e32 v111, v0
	v_mov_b32_e32 v112, v0
	v_mov_b32_e32 v113, v0
	v_mov_b32_e32 v114, v0
	v_mov_b32_e32 v115, v0
	v_mov_b32_e32 v116, v0
	v_mov_b32_e32 v117, v0
	v_mov_b32_e32 v118, v0
	v_mov_b32_e32 v119, v0
	v_mov_b32_e32 v120, v0
	v_mov_b32_e32 v121, v0
	v_mov_b32_e32 v122, v0
	v_mov_b32_e32 v123, v0
	v_mov_b32_e32 v124, v0
	v_mov_b32_e32 v125, v0
	v_mov_b32_e32 v126, v0
	v_mov_b32_e32 v127, v0
	v_readfirstlane_b32 s32, v152
	s_barrier
.LBB0_848:
	s_add_u32 s64, s32, 0xc000
	s_mov_b32 m0, s64
	ds_read_b128 v[170:173], v151
	ds_read_b128 v[174:177], v151 offset:1024
	ds_read_b128 v[178:181], v151 offset:2048
	ds_read_b128 v[182:185], v151 offset:3072
	ds_read_b128 v[186:189], v151 offset:16384
	ds_read_b128 v[190:193], v151 offset:17408
	ds_read_b128 v[194:197], v151 offset:18432
	ds_read_b128 v[198:201], v151 offset:19456
	ds_read_b128 v[202:205], v150
	ds_read_b128 v[206:209], v150 offset:1024
	ds_read_b128 v[210:213], v150 offset:2048
	ds_read_b128 v[214:217], v150 offset:3072
	ds_read_b128 v[218:221], v150 offset:4096
	ds_read_b128 v[222:225], v150 offset:5120
	ds_read_b128 v[226:229], v150 offset:6144
	ds_read_b128 v[230:233], v150 offset:7168
	s_add_u32 s88, s62, s22
	s_addc_u32 s89, s63, s23
	global_load_lds_dwordx4 v146, s[88:89]
	s_add_u32 s64, s32, 0xe000
	s_mov_b32 m0, s64
	s_nop 0
	s_add_u32 s90, s62, s22
	s_addc_u32 s91, s63, s23
	global_load_lds_dwordx4 v148, s[90:91]
	s_waitcnt lgkmcnt(0)
	s_barrier
	s_setprio 1
	s_waitcnt lgkmcnt(0)
	v_mfma_f32_16x16x32_bf16 v[124:127], v[202:205], v[170:173], v[124:127]
	v_mfma_f32_16x16x32_bf16 v[120:123], v[202:205], v[178:181], v[120:123]
	v_mfma_f32_16x16x32_bf16 v[116:119], v[210:213], v[170:173], v[116:119]
	v_mfma_f32_16x16x32_bf16 v[112:115], v[210:213], v[178:181], v[112:115]
	v_mfma_f32_16x16x32_bf16 v[108:111], v[218:221], v[170:173], v[108:111]
	v_mfma_f32_16x16x32_bf16 v[104:107], v[218:221], v[178:181], v[104:107]
	v_mfma_f32_16x16x32_bf16 v[100:103], v[226:229], v[170:173], v[100:103]
	v_mfma_f32_16x16x32_bf16 v[96:99], v[226:229], v[178:181], v[96:99]
	v_mfma_f32_16x16x32_bf16 v[92:95], v[202:205], v[186:189], v[92:95]
	v_mfma_f32_16x16x32_bf16 v[88:91], v[202:205], v[194:197], v[88:91]
	v_mfma_f32_16x16x32_bf16 v[84:87], v[210:213], v[186:189], v[84:87]
	v_mfma_f32_16x16x32_bf16 v[80:83], v[210:213], v[194:197], v[80:83]
	v_mfma_f32_16x16x32_bf16 v[76:79], v[218:221], v[186:189], v[76:79]
	v_mfma_f32_16x16x32_bf16 v[72:75], v[218:221], v[194:197], v[72:75]
	v_mfma_f32_16x16x32_bf16 v[68:71], v[226:229], v[186:189], v[68:71]
	v_mfma_f32_16x16x32_bf16 v[64:67], v[226:229], v[194:197], v[64:67]
	v_mfma_f32_16x16x32_bf16 v[124:127], v[206:209], v[174:177], v[124:127]
	v_mfma_f32_16x16x32_bf16 v[120:123], v[206:209], v[182:185], v[120:123]
	v_mfma_f32_16x16x32_bf16 v[116:119], v[214:217], v[174:177], v[116:119]
	v_mfma_f32_16x16x32_bf16 v[112:115], v[214:217], v[182:185], v[112:115]
	v_mfma_f32_16x16x32_bf16 v[108:111], v[222:225], v[174:177], v[108:111]
	v_mfma_f32_16x16x32_bf16 v[104:107], v[222:225], v[182:185], v[104:107]
	v_mfma_f32_16x16x32_bf16 v[100:103], v[230:233], v[174:177], v[100:103]
	v_mfma_f32_16x16x32_bf16 v[96:99], v[230:233], v[182:185], v[96:99]
	v_mfma_f32_16x16x32_bf16 v[92:95], v[206:209], v[190:193], v[92:95]
	v_mfma_f32_16x16x32_bf16 v[88:91], v[206:209], v[198:201], v[88:91]
	v_mfma_f32_16x16x32_bf16 v[84:87], v[214:217], v[190:193], v[84:87]
	v_mfma_f32_16x16x32_bf16 v[80:83], v[214:217], v[198:201], v[80:83]
	v_mfma_f32_16x16x32_bf16 v[76:79], v[222:225], v[190:193], v[76:79]
	v_mfma_f32_16x16x32_bf16 v[72:75], v[222:225], v[198:201], v[72:75]
	v_mfma_f32_16x16x32_bf16 v[68:71], v[230:233], v[190:193], v[68:71]
	v_mfma_f32_16x16x32_bf16 v[64:67], v[230:233], v[198:201], v[64:67]
	s_setprio 0
	s_barrier
; #define STAGE(Pp, BASE, br, kt) do { const u16* _g = (BASE) + ((long)(br) * K + (long)(kt) * BK); \
;     __builtin_amdgcn_global_load_lds((const unsigned*)(_g + voff0), (unsigned*)((char*)(Pp) + tb16), 16, 0, 0); \
;     __builtin_amdgcn_global_load_lds((const unsigned*)(_g + voff1), (unsigned*)((char*)(Pp) + tb16 + 8192), 16, 0, 0); } while (0)
; #define LDA(dst, b, h) _Pragma("unroll") for (int m = 0; m < 4; ++m) _Pragma("unroll") for (int k = 0; k < 2; ++k) \
;     dst[m][k] = *reinterpret_cast<const bf16x8*>((const char*)shm + aB + (((b) * 2 + (h)) * 16384 + (m * 2 + k) * 1024))
; #define LDB(dst, b, h) _Pragma("unroll") for (int n = 0; n < 2; ++n) _Pragma("unroll") for (int k = 0; k < 2; ++k) \
;     dst[n][k] = *reinterpret_cast<const bf16x8*>((const char*)shm + bB + (((b) * 2 + (h)) * 16384 + (n * 2 + k) * 1024))
; #define WAIT_V(n) asm volatile("s_waitcnt vmcnt(" #n ")" ::: "memory")
; #define WAIT_L(n) asm volatile("s_waitcnt lgkmcnt(" #n ")" ::: "memory")
; #define BAR __builtin_amdgcn_s_barrier()
; #define SCHED __builtin_amdgcn_sched_barrier(0)
; template <int MODE> ...
;     ...
;       LDA(At, 0, 1); STAGE(SB(0, 0), Bt, bcol, t + 2); STAGE(SB(0, 1), Bt, bcol + HALF, t + 2); STAGE(SA(0, 0), A, brow, t + 2);
;       WAIT_V(6); WAIT_L(0); BAR; MMA2(1, 0, 1, 1); BAR; SCHED;
;       LDB(B0, 1, 0); LDB(B1, 1, 1); LDA(At, 1, 0); STAGE(SA(0, 1), A, brow + HALF, t + 2);
	s_add_u32 s64, s32, 0x10000
	s_mov_b32 m0, s64
	ds_read_b128 v[202:205], v150 offset:16384
	ds_read_b128 v[206:209], v150 offset:17408
	ds_read_b128 v[210:213], v150 offset:18432
	ds_read_b128 v[214:217], v150 offset:19456
	ds_read_b128 v[218:221], v150 offset:20480
	ds_read_b128 v[222:225], v150 offset:21504
	ds_read_b128 v[226:229], v150 offset:22528
	ds_read_b128 v[230:233], v150 offset:23552
	s_add_u32 s92, s62, s24
	s_addc_u32 s93, s63, s25
	global_load_lds_dwordx4 v138, s[92:93]
	s_add_u32 s64, s32, 0x12000
	s_mov_b32 m0, s64
	s_add_u32 s64, s32, 0x14000
	s_add_u32 s96, s62, s24
	s_addc_u32 s97, s63, s25
	global_load_lds_dwordx4 v140, s[96:97]
	s_mov_b32 m0, s64
	s_add_u32 s64, s32, 0x16000
	s_add_u32 s88, s62, s26
	s_addc_u32 s89, s63, s27
	global_load_lds_dwordx4 v142, s[88:89]
	s_mov_b32 m0, s64
	s_mov_b32 s64, s32
	s_add_u32 s90, s62, s26
	s_addc_u32 s91, s63, s27
	global_load_lds_dwordx4 v144, s[90:91]
	s_mov_b32 m0, s64
	s_add_u32 s64, s32, 0x2000
	s_add_u32 s92, s62, s28
	s_addc_u32 s93, s63, s29
	global_load_lds_dwordx4 v146, s[92:93]
	s_mov_b32 m0, s64
	s_nop 0
	s_add_u32 s96, s62, s28
	s_addc_u32 s97, s63, s29
	global_load_lds_dwordx4 v148, s[96:97]
	s_waitcnt vmcnt(6)
	s_waitcnt lgkmcnt(0)
	s_barrier
	s_setprio 1
	s_waitcnt lgkmcnt(0)
	v_mfma_f32_16x16x32_bf16 v[60:63], v[202:205], v[170:173], v[60:63]
	v_mfma_f32_16x16x32_bf16 v[56:59], v[202:205], v[178:181], v[56:59]
	v_mfma_f32_16x16x32_bf16 v[52:55], v[210:213], v[170:173], v[52:55]
	v_mfma_f32_16x16x32_bf16 v[48:51], v[210:213], v[178:181], v[48:51]
	v_mfma_f32_16x16x32_bf16 v[44:47], v[218:221], v[170:173], v[44:47]
	v_mfma_f32_16x16x32_bf16 v[40:43], v[218:221], v[178:181], v[40:43]
	v_mfma_f32_16x16x32_bf16 v[36:39], v[226:229], v[170:173], v[36:39]
	v_mfma_f32_16x16x32_bf16 v[32:35], v[226:229], v[178:181], v[32:35]
	v_mfma_f32_16x16x32_bf16 v[28:31], v[202:205], v[186:189], v[28:31]
	v_mfma_f32_16x16x32_bf16 v[24:27], v[202:205], v[194:197], v[24:27]
	v_mfma_f32_16x16x32_bf16 v[20:23], v[210:213], v[186:189], v[20:23]
	v_mfma_f32_16x16x32_bf16 v[16:19], v[210:213], v[194:197], v[16:19]
	v_mfma_f32_16x16x32_bf16 v[12:15], v[218:221], v[186:189], v[12:15]
	v_mfma_f32_16x16x32_bf16 v[8:11], v[218:221], v[194:197], v[8:11]
	v_mfma_f32_16x16x32_bf16 v[4:7], v[226:229], v[186:189], v[4:7]
	v_mfma_f32_16x16x32_bf16 v[0:3], v[226:229], v[194:197], v[0:3]
	v_mfma_f32_16x16x32_bf16 v[60:63], v[206:209], v[174:177], v[60:63]
	v_mfma_f32_16x16x32_bf16 v[56:59], v[206:209], v[182:185], v[56:59]
	v_mfma_f32_16x16x32_bf16 v[52:55], v[214:217], v[174:177], v[52:55]
	v_mfma_f32_16x16x32_bf16 v[48:51], v[214:217], v[182:185], v[48:51]
	v_mfma_f32_16x16x32_bf16 v[44:47], v[222:225], v[174:177], v[44:47]
	v_mfma_f32_16x16x32_bf16 v[40:43], v[222:225], v[182:185], v[40:43]
	v_mfma_f32_16x16x32_bf16 v[36:39], v[230:233], v[174:177], v[36:39]
	v_mfma_f32_16x16x32_bf16 v[32:35], v[230:233], v[182:185], v[32:35]
	v_mfma_f32_16x16x32_bf16 v[28:31], v[206:209], v[190:193], v[28:31]
	v_mfma_f32_16x16x32_bf16 v[24:27], v[206:209], v[198:201], v[24:27]
	v_mfma_f32_16x16x32_bf16 v[20:23], v[214:217], v[190:193], v[20:23]
	v_mfma_f32_16x16x32_bf16 v[16:19], v[214:217], v[198:201], v[16:19]
	v_mfma_f32_16x16x32_bf16 v[12:15], v[222:225], v[190:193], v[12:15]
	v_mfma_f32_16x16x32_bf16 v[8:11], v[222:225], v[198:201], v[8:11]
	v_mfma_f32_16x16x32_bf16 v[4:7], v[230:233], v[190:193], v[4:7]
	v_mfma_f32_16x16x32_bf16 v[0:3], v[230:233], v[198:201], v[0:3]
	s_setprio 0
	s_barrier
	s_add_u32 s64, s32, 0x4000
	s_mov_b32 m0, s64
	s_add_u32 s64, s32, 0x6000
	ds_read_b128 v[170:173], v151 offset:32768
	ds_read_b128 v[174:177], v151 offset:33792
	ds_read_b128 v[178:181], v151 offset:34816
	ds_read_b128 v[182:185], v151 offset:35840
	ds_read_b128 v[186:189], v151 offset:49152
	ds_read_b128 v[190:193], v151 offset:50176
	ds_read_b128 v[194:197], v151 offset:51200
	ds_read_b128 v[198:201], v151 offset:52224
	ds_read_b128 v[202:205], v150 offset:32768
	ds_read_b128 v[206:209], v150 offset:33792
	ds_read_b128 v[210:213], v150 offset:34816
	ds_read_b128 v[214:217], v150 offset:35840
	ds_read_b128 v[218:221], v150 offset:36864
	ds_read_b128 v[222:225], v150 offset:37888
	ds_read_b128 v[226:229], v150 offset:38912
	ds_read_b128 v[230:233], v150 offset:39936
	s_add_u32 s88, s62, s36
	s_addc_u32 s89, s63, s37
	global_load_lds_dwordx4 v146, s[88:89]
	s_mov_b32 m0, s64
	s_nop 0
	s_add_u32 s90, s62, s36
	s_addc_u32 s91, s63, s37
	global_load_lds_dwordx4 v148, s[90:91]
	s_waitcnt lgkmcnt(0)
	s_barrier
; #define STAGE(Pp, BASE, br, kt) do { const u16* _g = (BASE) + ((long)(br) * K + (long)(kt) * BK); \
;     __builtin_amdgcn_global_load_lds((const unsigned*)(_g + voff0), (unsigned*)((char*)(Pp) + tb16), 16, 0, 0); \
;     __builtin_amdgcn_global_load_lds((const unsigned*)(_g + voff1), (unsigned*)((char*)(Pp) + tb16 + 8192), 16, 0, 0); } while (0)
; #define LDA(dst, b, h) _Pragma("unroll") for (int m = 0; m < 4; ++m) _Pragma("unroll") for (int k = 0; k < 2; ++k) \
;     dst[m][k] = *reinterpret_cast<const bf16x8*>((const char*)shm + aB + (((b) * 2 + (h)) * 16384 + (m * 2 + k) * 1024))
; #define WAIT_V(n) asm volatile("s_waitcnt vmcnt(" #n ")" ::: "memory")
; #define WAIT_L(n) asm volatile("s_waitcnt lgkmcnt(" #n ")" ::: "memory")
; #define BAR __builtin_amdgcn_s_barrier()
; #define SCHED __builtin_amdgcn_sched_barrier(0)
; template <int MODE> ...
;     ...
;       WAIT_L(0); BAR; MMA2(0, 0, 0, 1); BAR; SCHED;
;       LDA(At, 1, 1); STAGE(SB(1, 0), Bt, bcol, t + 3); STAGE(SB(1, 1), Bt, bcol + HALF, t + 3); STAGE(SA(1, 0), A, brow, t + 3);
;       WAIT_V(6); WAIT_L(0); BAR; MMA2(1, 0, 1, 1); BAR; SCHED;
	s_setprio 1
	s_waitcnt lgkmcnt(0)
	v_mfma_f32_16x16x32_bf16 v[124:127], v[202:205], v[170:173], v[124:127]
	v_mfma_f32_16x16x32_bf16 v[120:123], v[202:205], v[178:181], v[120:123]
	v_mfma_f32_16x16x32_bf16 v[116:119], v[210:213], v[170:173], v[116:119]
	v_mfma_f32_16x16x32_bf16 v[112:115], v[210:213], v[178:181], v[112:115]
	v_mfma_f32_16x16x32_bf16 v[108:111], v[218:221], v[170:173], v[108:111]
	v_mfma_f32_16x16x32_bf16 v[104:107], v[218:221], v[178:181], v[104:107]
	v_mfma_f32_16x16x32_bf16 v[100:103], v[226:229], v[170:173], v[100:103]
	v_mfma_f32_16x16x32_bf16 v[96:99], v[226:229], v[178:181], v[96:99]
	v_mfma_f32_16x16x32_bf16 v[92:95], v[202:205], v[186:189], v[92:95]
	v_mfma_f32_16x16x32_bf16 v[88:91], v[202:205], v[194:197], v[88:91]
	v_mfma_f32_16x16x32_bf16 v[84:87], v[210:213], v[186:189], v[84:87]
	v_mfma_f32_16x16x32_bf16 v[80:83], v[210:213], v[194:197], v[80:83]
	v_mfma_f32_16x16x32_bf16 v[76:79], v[218:221], v[186:189], v[76:79]
	v_mfma_f32_16x16x32_bf16 v[72:75], v[218:221], v[194:197], v[72:75]
	v_mfma_f32_16x16x32_bf16 v[68:71], v[226:229], v[186:189], v[68:71]
	v_mfma_f32_16x16x32_bf16 v[64:67], v[226:229], v[194:197], v[64:67]
	v_mfma_f32_16x16x32_bf16 v[124:127], v[206:209], v[174:177], v[124:127]
	v_mfma_f32_16x16x32_bf16 v[120:123], v[206:209], v[182:185], v[120:123]
	v_mfma_f32_16x16x32_bf16 v[116:119], v[214:217], v[174:177], v[116:119]
	v_mfma_f32_16x16x32_bf16 v[112:115], v[214:217], v[182:185], v[112:115]
	v_mfma_f32_16x16x32_bf16 v[108:111], v[222:225], v[174:177], v[108:111]
	v_mfma_f32_16x16x32_bf16 v[104:107], v[222:225], v[182:185], v[104:107]
	v_mfma_f32_16x16x32_bf16 v[100:103], v[230:233], v[174:177], v[100:103]
	v_mfma_f32_16x16x32_bf16 v[96:99], v[230:233], v[182:185], v[96:99]
	v_mfma_f32_16x16x32_bf16 v[92:95], v[206:209], v[190:193], v[92:95]
	v_mfma_f32_16x16x32_bf16 v[88:91], v[206:209], v[198:201], v[88:91]
	v_mfma_f32_16x16x32_bf16 v[84:87], v[214:217], v[190:193], v[84:87]
	v_mfma_f32_16x16x32_bf16 v[80:83], v[214:217], v[198:201], v[80:83]
	v_mfma_f32_16x16x32_bf16 v[76:79], v[222:225], v[190:193], v[76:79]
	v_mfma_f32_16x16x32_bf16 v[72:75], v[222:225], v[198:201], v[72:75]
	v_mfma_f32_16x16x32_bf16 v[68:71], v[230:233], v[190:193], v[68:71]
	v_mfma_f32_16x16x32_bf16 v[64:67], v[230:233], v[198:201], v[64:67]
	s_setprio 0
	s_barrier
	s_add_u32 s64, s32, 0x18000
	s_mov_b32 m0, s64
	s_add_u32 s64, s32, 0x1a000
	ds_read_b128 v[202:205], v150 offset:49152
	ds_read_b128 v[206:209], v150 offset:50176
	ds_read_b128 v[210:213], v150 offset:51200
	ds_read_b128 v[214:217], v150 offset:52224
	ds_read_b128 v[218:221], v150 offset:53248
	ds_read_b128 v[222:225], v150 offset:54272
	ds_read_b128 v[226:229], v150 offset:55296
	ds_read_b128 v[230:233], v150 offset:56320
	s_add_u32 s92, s62, s38
	s_addc_u32 s93, s63, s39
	global_load_lds_dwordx4 v138, s[92:93]
	s_mov_b32 m0, s64
	s_add_u32 s64, s32, 0x1c000
	s_add_u32 s96, s62, s38
	s_addc_u32 s97, s63, s39
	global_load_lds_dwordx4 v140, s[96:97]
	s_mov_b32 m0, s64
	s_add_u32 s64, s32, 0x1e000
	s_add_u32 s88, s62, s40
	s_addc_u32 s89, s63, s41
	global_load_lds_dwordx4 v142, s[88:89]
	s_mov_b32 m0, s64
	s_add_u32 s64, s32, 0x8000
	s_add_u32 s90, s62, s40
	s_addc_u32 s91, s63, s41
	global_load_lds_dwordx4 v144, s[90:91]
	s_mov_b32 m0, s64
	s_add_u32 s64, s32, 0xa000
	s_add_u32 s92, s62, s42
	s_addc_u32 s93, s63, s43
	global_load_lds_dwordx4 v146, s[92:93]
	s_mov_b32 m0, s64
	s_nop 0
	s_add_u32 s96, s62, s42
	s_addc_u32 s97, s63, s43
	global_load_lds_dwordx4 v148, s[96:97]
	s_waitcnt vmcnt(6)
	s_waitcnt lgkmcnt(0)
	s_barrier
	s_setprio 1
	s_waitcnt lgkmcnt(0)
	v_mfma_f32_16x16x32_bf16 v[60:63], v[202:205], v[170:173], v[60:63]
	v_mfma_f32_16x16x32_bf16 v[56:59], v[202:205], v[178:181], v[56:59]
	v_mfma_f32_16x16x32_bf16 v[52:55], v[210:213], v[170:173], v[52:55]
	v_mfma_f32_16x16x32_bf16 v[48:51], v[210:213], v[178:181], v[48:51]
	v_mfma_f32_16x16x32_bf16 v[44:47], v[218:221], v[170:173], v[44:47]
	v_mfma_f32_16x16x32_bf16 v[40:43], v[218:221], v[178:181], v[40:43]
	v_mfma_f32_16x16x32_bf16 v[36:39], v[226:229], v[170:173], v[36:39]
	v_mfma_f32_16x16x32_bf16 v[32:35], v[226:229], v[178:181], v[32:35]
	v_mfma_f32_16x16x32_bf16 v[28:31], v[202:205], v[186:189], v[28:31]
	v_mfma_f32_16x16x32_bf16 v[24:27], v[202:205], v[194:197], v[24:27]
	v_mfma_f32_16x16x32_bf16 v[20:23], v[210:213], v[186:189], v[20:23]
	v_mfma_f32_16x16x32_bf16 v[16:19], v[210:213], v[194:197], v[16:19]
	v_mfma_f32_16x16x32_bf16 v[12:15], v[218:221], v[186:189], v[12:15]
	v_mfma_f32_16x16x32_bf16 v[8:11], v[218:221], v[194:197], v[8:11]
	v_mfma_f32_16x16x32_bf16 v[4:7], v[226:229], v[186:189], v[4:7]
	v_mfma_f32_16x16x32_bf16 v[0:3], v[226:229], v[194:197], v[0:3]
	v_mfma_f32_16x16x32_bf16 v[60:63], v[206:209], v[174:177], v[60:63]
	v_mfma_f32_16x16x32_bf16 v[56:59], v[206:209], v[182:185], v[56:59]
	v_mfma_f32_16x16x32_bf16 v[52:55], v[214:217], v[174:177], v[52:55]
	v_mfma_f32_16x16x32_bf16 v[48:51], v[214:217], v[182:185], v[48:51]
	v_mfma_f32_16x16x32_bf16 v[44:47], v[222:225], v[174:177], v[44:47]
	v_mfma_f32_16x16x32_bf16 v[40:43], v[222:225], v[182:185], v[40:43]
	v_mfma_f32_16x16x32_bf16 v[36:39], v[230:233], v[174:177], v[36:39]
	v_mfma_f32_16x16x32_bf16 v[32:35], v[230:233], v[182:185], v[32:35]
	v_mfma_f32_16x16x32_bf16 v[28:31], v[206:209], v[190:193], v[28:31]
	v_mfma_f32_16x16x32_bf16 v[24:27], v[206:209], v[198:201], v[24:27]
	v_mfma_f32_16x16x32_bf16 v[20:23], v[214:217], v[190:193], v[20:23]
	v_mfma_f32_16x16x32_bf16 v[16:19], v[214:217], v[198:201], v[16:19]
	v_mfma_f32_16x16x32_bf16 v[12:15], v[222:225], v[190:193], v[12:15]
	v_mfma_f32_16x16x32_bf16 v[8:11], v[222:225], v[198:201], v[8:11]
	v_mfma_f32_16x16x32_bf16 v[4:7], v[230:233], v[190:193], v[4:7]
	v_mfma_f32_16x16x32_bf16 v[0:3], v[230:233], v[198:201], v[0:3]
	s_setprio 0
	s_barrier
; #define STAGE(Pp, BASE, br, kt) do { const u16* _g = (BASE) + ((long)(br) * K + (long)(kt) * BK); \
;     __builtin_amdgcn_global_load_lds((const unsigned*)(_g + voff0), (unsigned*)((char*)(Pp) + tb16), 16, 0, 0); \
;     __builtin_amdgcn_global_load_lds((const unsigned*)(_g + voff1), (unsigned*)((char*)(Pp) + tb16 + 8192), 16, 0, 0); } while (0)
; #define LDA(dst, b, h) _Pragma("unroll") for (int m = 0; m < 4; ++m) _Pragma("unroll") for (int k = 0; k < 2; ++k) \
;     dst[m][k] = *reinterpret_cast<const bf16x8*>((const char*)shm + aB + (((b) * 2 + (h)) * 16384 + (m * 2 + k) * 1024))
; #define LDB(dst, b, h) _Pragma("unroll") for (int n = 0; n < 2; ++n) _Pragma("unroll") for (int k = 0; k < 2; ++k) \
;     dst[n][k] = *reinterpret_cast<const bf16x8*>((const char*)shm + bB + (((b) * 2 + (h)) * 16384 + (n * 2 + k) * 1024))
; #define WAIT_V(n) asm volatile("s_waitcnt vmcnt(" #n ")" ::: "memory")
; #define WAIT_L(n) asm volatile("s_waitcnt lgkmcnt(" #n ")" ::: "memory")
; #define BAR __builtin_amdgcn_s_barrier()
; #define SCHED __builtin_amdgcn_sched_barrier(0)
; template <int MODE> ...
;     ...
;     }
;     {
;       LDB(B0, 0, 0); LDB(B1, 0, 1); LDA(At, 0, 0); STAGE(SA(1, 1), A, brow + HALF, nt - 1);
;       WAIT_L(0); BAR; MMA2(0, 0, 0, 1); BAR; SCHED;
;       LDA(At, 0, 1); WAIT_V(0); WAIT_L(0); BAR; MMA2(1, 0, 1, 1); BAR; SCHED;
	s_add_i32 s45, s45, 2
	s_add_u32 s62, s62, 0x100
	s_addc_u32 s63, s63, 0
	s_cmpk_lt_u32 s45, 0xa8
	s_cbranch_scc1 .LBB0_848
	s_add_u32 s60, s60, 0x5580
	v_readfirstlane_b32 s45, v167
	s_addc_u32 s61, s61, 0
	s_mov_b32 m0, s45
	v_readfirstlane_b32 s45, v168
	ds_read_b128 v[138:141], v151
	ds_read_b128 v[142:145], v151 offset:1024
	ds_read_b128 v[146:149], v151 offset:2048
	ds_read_b128 v[170:173], v151 offset:3072
	ds_read_b128 v[174:177], v151 offset:16384
	ds_read_b128 v[178:181], v151 offset:17408
	ds_read_b128 v[182:185], v151 offset:18432
	ds_read_b128 v[186:189], v151 offset:19456
	ds_read_b128 v[190:193], v150
	ds_read_b128 v[194:197], v150 offset:1024
	ds_read_b128 v[198:201], v150 offset:2048
	ds_read_b128 v[202:205], v150 offset:3072
	ds_read_b128 v[206:209], v150 offset:4096
	ds_read_b128 v[210:213], v150 offset:5120
	ds_read_b128 v[214:217], v150 offset:6144
	ds_read_b128 v[218:221], v150 offset:7168
	global_load_lds_dwordx4 v134, s[60:61]
	s_mov_b32 m0, s45
	s_nop 0
	global_load_lds_dwordx4 v136, s[60:61]
	s_waitcnt lgkmcnt(0)
	s_barrier
	s_setprio 1
	s_waitcnt lgkmcnt(0)
	v_mfma_f32_16x16x32_bf16 v[124:127], v[190:193], v[138:141], v[124:127]
	v_mfma_f32_16x16x32_bf16 v[116:119], v[198:201], v[138:141], v[116:119]
	v_mfma_f32_16x16x32_bf16 v[108:111], v[206:209], v[138:141], v[108:111]
	v_mfma_f32_16x16x32_bf16 v[100:103], v[214:217], v[138:141], v[100:103]
	v_mfma_f32_16x16x32_bf16 v[96:99], v[214:217], v[146:149], v[96:99]
	v_mfma_f32_16x16x32_bf16 v[92:95], v[190:193], v[174:177], v[92:95]
	v_mfma_f32_16x16x32_bf16 v[88:91], v[190:193], v[182:185], v[88:91]
	v_mfma_f32_16x16x32_bf16 v[80:83], v[198:201], v[182:185], v[80:83]
	v_mfma_f32_16x16x32_bf16 v[76:79], v[206:209], v[174:177], v[76:79]
	v_mfma_f32_16x16x32_bf16 v[124:127], v[194:197], v[142:145], v[124:127]
	v_mfma_f32_16x16x32_bf16 v[120:123], v[190:193], v[146:149], v[120:123]
	v_mfma_f32_16x16x32_bf16 v[116:119], v[202:205], v[142:145], v[116:119]
	v_mfma_f32_16x16x32_bf16 v[112:115], v[198:201], v[146:149], v[112:115]
	v_mfma_f32_16x16x32_bf16 v[108:111], v[210:213], v[142:145], v[108:111]
	v_mfma_f32_16x16x32_bf16 v[104:107], v[206:209], v[146:149], v[104:107]
	v_mfma_f32_16x16x32_bf16 v[100:103], v[218:221], v[142:145], v[100:103]
	v_mfma_f32_16x16x32_bf16 v[96:99], v[218:221], v[170:173], v[96:99]
	v_mfma_f32_16x16x32_bf16 v[92:95], v[194:197], v[178:181], v[92:95]
	v_mfma_f32_16x16x32_bf16 v[88:91], v[194:197], v[186:189], v[88:91]
	v_mfma_f32_16x16x32_bf16 v[84:87], v[198:201], v[174:177], v[84:87]
	v_mfma_f32_16x16x32_bf16 v[80:83], v[202:205], v[186:189], v[80:83]
	v_mfma_f32_16x16x32_bf16 v[76:79], v[210:213], v[178:181], v[76:79]
	v_mfma_f32_16x16x32_bf16 v[72:75], v[206:209], v[182:185], v[72:75]
	v_mfma_f32_16x16x32_bf16 v[68:71], v[214:217], v[174:177], v[68:71]
	v_mfma_f32_16x16x32_bf16 v[64:67], v[214:217], v[182:185], v[64:67]
	v_mfma_f32_16x16x32_bf16 v[222:225], v[194:197], v[170:173], v[120:123]
	v_mfma_f32_16x16x32_bf16 v[226:229], v[202:205], v[170:173], v[112:115]
	v_mfma_f32_16x16x32_bf16 v[230:233], v[210:213], v[170:173], v[104:107]
	v_mfma_f32_16x16x32_bf16 v[190:193], v[202:205], v[178:181], v[84:87]
	v_mfma_f32_16x16x32_bf16 v[194:197], v[210:213], v[186:189], v[72:75]
	v_mfma_f32_16x16x32_bf16 v[198:201], v[218:221], v[178:181], v[68:71]
	v_mfma_f32_16x16x32_bf16 v[202:205], v[218:221], v[186:189], v[64:67]
	s_setprio 0
	s_barrier
	s_nop 0
	ds_read_b128 v[64:67], v150 offset:16384
	ds_read_b128 v[68:71], v150 offset:17408
	ds_read_b128 v[72:75], v150 offset:18432
	ds_read_b128 v[84:87], v150 offset:19456
	ds_read_b128 v[104:107], v150 offset:20480
	ds_read_b128 v[112:115], v150 offset:21504
	ds_read_b128 v[120:123], v150 offset:22528
	ds_read_b128 v[206:209], v150 offset:23552
	s_waitcnt vmcnt(0)
	s_waitcnt lgkmcnt(0)
	s_barrier
	s_setprio 1
	s_waitcnt lgkmcnt(0)
	v_mfma_f32_16x16x32_bf16 v[60:63], v[64:67], v[138:141], v[60:63]
	v_mfma_f32_16x16x32_bf16 v[56:59], v[64:67], v[146:149], v[56:59]
	v_mfma_f32_16x16x32_bf16 v[52:55], v[72:75], v[138:141], v[52:55]
	v_mfma_f32_16x16x32_bf16 v[48:51], v[72:75], v[146:149], v[48:51]
	v_mfma_f32_16x16x32_bf16 v[44:47], v[104:107], v[138:141], v[44:47]
	v_mfma_f32_16x16x32_bf16 v[40:43], v[104:107], v[146:149], v[40:43]
	v_mfma_f32_16x16x32_bf16 v[28:31], v[64:67], v[174:177], v[28:31]
	v_mfma_f32_16x16x32_bf16 v[24:27], v[64:67], v[182:185], v[24:27]
	v_mfma_f32_16x16x32_bf16 v[20:23], v[72:75], v[174:177], v[20:23]
	v_mfma_f32_16x16x32_bf16 v[60:63], v[68:71], v[142:145], v[60:63]
	v_mfma_f32_16x16x32_bf16 v[56:59], v[68:71], v[170:173], v[56:59]
	v_mfma_f32_16x16x32_bf16 v[52:55], v[84:87], v[142:145], v[52:55]
	v_mfma_f32_16x16x32_bf16 v[48:51], v[84:87], v[170:173], v[48:51]
	v_mfma_f32_16x16x32_bf16 v[44:47], v[112:115], v[142:145], v[44:47]
	v_mfma_f32_16x16x32_bf16 v[40:43], v[112:115], v[170:173], v[40:43]
	v_mfma_f32_16x16x32_bf16 v[36:39], v[120:123], v[138:141], v[36:39]
	v_mfma_f32_16x16x32_bf16 v[32:35], v[120:123], v[146:149], v[32:35]
	v_mfma_f32_16x16x32_bf16 v[28:31], v[68:71], v[178:181], v[28:31]
	v_mfma_f32_16x16x32_bf16 v[24:27], v[68:71], v[186:189], v[24:27]
	v_mfma_f32_16x16x32_bf16 v[20:23], v[84:87], v[178:181], v[20:23]
	v_mfma_f32_16x16x32_bf16 v[16:19], v[72:75], v[182:185], v[16:19]
	v_mfma_f32_16x16x32_bf16 v[12:15], v[104:107], v[174:177], v[12:15]
	v_mfma_f32_16x16x32_bf16 v[8:11], v[104:107], v[182:185], v[8:11]
	v_mfma_f32_16x16x32_bf16 v[4:7], v[120:123], v[174:177], v[4:7]
	v_mfma_f32_16x16x32_bf16 v[0:3], v[120:123], v[182:185], v[0:3]
	v_mfma_f32_16x16x32_bf16 v[138:141], v[206:209], v[142:145], v[36:39]
	v_mfma_f32_16x16x32_bf16 v[142:145], v[206:209], v[170:173], v[32:35]
	v_mfma_f32_16x16x32_bf16 v[146:149], v[84:87], v[186:189], v[16:19]
	v_mfma_f32_16x16x32_bf16 v[170:173], v[112:115], v[178:181], v[12:15]
	v_mfma_f32_16x16x32_bf16 v[210:213], v[112:115], v[186:189], v[8:11]
	v_mfma_f32_16x16x32_bf16 v[174:177], v[206:209], v[178:181], v[4:7]
	v_mfma_f32_16x16x32_bf16 v[178:181], v[206:209], v[186:189], v[0:3]
	s_setprio 0
	s_barrier
; #define LDA(dst, b, h) _Pragma("unroll") for (int m = 0; m < 4; ++m) _Pragma("unroll") for (int k = 0; k < 2; ++k) \
;     dst[m][k] = *reinterpret_cast<const bf16x8*>((const char*)shm + aB + (((b) * 2 + (h)) * 16384 + (m * 2 + k) * 1024))
; #define LDB(dst, b, h) _Pragma("unroll") for (int n = 0; n < 2; ++n) _Pragma("unroll") for (int k = 0; k < 2; ++k) \
;     dst[n][k] = *reinterpret_cast<const bf16x8*>((const char*)shm + bB + (((b) * 2 + (h)) * 16384 + (n * 2 + k) * 1024))
; #define WAIT_L(n) asm volatile("s_waitcnt lgkmcnt(" #n ")" ::: "memory")
; #define BAR __builtin_amdgcn_s_barrier()
; #define SCHED __builtin_amdgcn_sched_barrier(0)
; template <int MODE> ...
;     ...
;       LDB(B0, 1, 0); LDB(B1, 1, 1); LDA(At, 1, 0); WAIT_L(0); BAR; MMA2(0, 0, 0, 1); BAR; SCHED;
;       LDA(At, 1, 1); WAIT_L(0); BAR; MMA2(1, 0, 1, 1); BAR; SCHED;
;     }
;     ...
;     if (wr == 0) BAR;
	ds_read_b128 v[12:15], v151 offset:32768
	ds_read_b128 v[16:19], v151 offset:33792
	ds_read_b128 v[182:185], v151 offset:34816
	ds_read_b128 v[186:189], v151 offset:35840
	ds_read_b128 v[206:209], v151 offset:49152
	ds_read_b128 v[214:217], v151 offset:50176
	ds_read_b128 v[218:221], v151 offset:51200
	ds_read_b128 v[234:237], v151 offset:52224
	ds_read_b128 v[0:3], v150 offset:32768
	ds_read_b128 v[4:7], v150 offset:33792
	ds_read_b128 v[8:11], v150 offset:34816
	ds_read_b128 v[32:35], v150 offset:35840
	ds_read_b128 v[36:39], v150 offset:36864
	ds_read_b128 v[238:241], v150 offset:37888
	ds_read_b128 v[242:245], v150 offset:38912
	ds_read_b128 v[246:249], v150 offset:39936
	s_waitcnt lgkmcnt(0)
	s_barrier
	s_setprio 1
	s_waitcnt lgkmcnt(0)
	v_mfma_f32_16x16x32_bf16 v[64:67], v[0:3], v[12:15], v[124:127]
	v_mfma_f32_16x16x32_bf16 v[68:71], v[242:245], v[182:185], v[96:99]
	v_mfma_f32_16x16x32_bf16 v[120:123], v[4:7], v[16:19], v[64:67]
	v_mfma_f32_16x16x32_bf16 v[64:67], v[0:3], v[182:185], v[222:225]
	v_mfma_f32_16x16x32_bf16 v[84:87], v[246:249], v[186:189], v[68:71]
	v_mfma_f32_16x16x32_bf16 v[68:71], v[0:3], v[206:209], v[92:95]
	v_mfma_f32_16x16x32_bf16 v[0:3], v[0:3], v[218:221], v[88:91]
	v_mfma_f32_16x16x32_bf16 v[88:91], v[4:7], v[234:237], v[0:3]
	v_mfma_f32_16x16x32_bf16 v[0:3], v[8:11], v[206:209], v[190:193]
	v_mfma_f32_16x16x32_bf16 v[124:127], v[4:7], v[186:189], v[64:67]
	v_mfma_f32_16x16x32_bf16 v[64:67], v[8:11], v[12:15], v[116:119]
	v_mfma_f32_16x16x32_bf16 v[72:75], v[32:35], v[214:217], v[0:3]
	v_mfma_f32_16x16x32_bf16 v[0:3], v[8:11], v[218:221], v[80:83]
	v_mfma_f32_16x16x32_bf16 v[112:115], v[32:35], v[16:19], v[64:67]
	v_mfma_f32_16x16x32_bf16 v[64:67], v[8:11], v[182:185], v[226:229]
	v_mfma_f32_16x16x32_bf16 v[92:95], v[32:35], v[234:237], v[0:3]
	v_mfma_f32_16x16x32_bf16 v[0:3], v[36:39], v[206:209], v[76:79]
	v_mfma_f32_16x16x32_bf16 v[116:119], v[32:35], v[186:189], v[64:67]
	v_mfma_f32_16x16x32_bf16 v[64:67], v[36:39], v[12:15], v[108:111]
	v_mfma_f32_16x16x32_bf16 v[76:79], v[238:241], v[214:217], v[0:3]
	v_mfma_f32_16x16x32_bf16 v[0:3], v[36:39], v[218:221], v[194:197]
	v_mfma_f32_16x16x32_bf16 v[104:107], v[238:241], v[16:19], v[64:67]
	v_mfma_f32_16x16x32_bf16 v[64:67], v[36:39], v[182:185], v[230:233]
	v_mfma_f32_16x16x32_bf16 v[96:99], v[238:241], v[234:237], v[0:3]
	v_mfma_f32_16x16x32_bf16 v[0:3], v[242:245], v[206:209], v[198:201]
	v_mfma_f32_16x16x32_bf16 v[108:111], v[238:241], v[186:189], v[64:67]
	v_mfma_f32_16x16x32_bf16 v[64:67], v[242:245], v[12:15], v[100:103]
	v_mfma_f32_16x16x32_bf16 v[80:83], v[246:249], v[214:217], v[0:3]
	v_mfma_f32_16x16x32_bf16 v[0:3], v[242:245], v[218:221], v[202:205]
	v_mfma_f32_16x16x32_bf16 v[64:67], v[246:249], v[16:19], v[64:67]
	v_mfma_f32_16x16x32_bf16 v[68:71], v[4:7], v[214:217], v[68:71]
	v_mfma_f32_16x16x32_bf16 v[100:103], v[246:249], v[234:237], v[0:3]
	s_setprio 0
	s_barrier
	ds_read_b128 v[190:193], v150 offset:49152
	ds_read_b128 v[194:197], v150 offset:50176
	ds_read_b128 v[198:201], v150 offset:51200
	ds_read_b128 v[202:205], v150 offset:52224
	ds_read_b128 v[222:225], v150 offset:53248
	ds_read_b128 v[226:229], v150 offset:54272
	ds_read_b128 v[230:233], v150 offset:55296
	ds_read_b128 v[238:241], v150 offset:56320
	s_waitcnt lgkmcnt(0)
	s_barrier
	s_setprio 1
	s_waitcnt lgkmcnt(0)
	v_mfma_f32_16x16x32_bf16 v[4:7], v[190:193], v[182:185], v[56:59]
	v_mfma_f32_16x16x32_bf16 v[8:11], v[198:201], v[182:185], v[48:51]
	v_mfma_f32_16x16x32_bf16 v[0:3], v[190:193], v[12:15], v[60:63]
	v_mfma_f32_16x16x32_bf16 v[32:35], v[194:197], v[186:189], v[4:7]
	v_mfma_f32_16x16x32_bf16 v[4:7], v[198:201], v[12:15], v[52:55]
	v_mfma_f32_16x16x32_bf16 v[36:39], v[202:205], v[186:189], v[8:11]
	v_mfma_f32_16x16x32_bf16 v[8:11], v[222:225], v[12:15], v[44:47]
	v_mfma_f32_16x16x32_bf16 v[12:15], v[230:233], v[12:15], v[138:141]
	v_mfma_f32_16x16x32_bf16 v[0:3], v[194:197], v[16:19], v[0:3]
	v_mfma_f32_16x16x32_bf16 v[4:7], v[202:205], v[16:19], v[4:7]
	v_mfma_f32_16x16x32_bf16 v[8:11], v[226:229], v[16:19], v[8:11]
	v_mfma_f32_16x16x32_bf16 v[12:15], v[238:241], v[16:19], v[12:15]
	v_mfma_f32_16x16x32_bf16 v[16:19], v[230:233], v[182:185], v[142:145]
	v_mfma_f32_16x16x32_bf16 v[24:27], v[190:193], v[218:221], v[24:27]
	v_mfma_f32_16x16x32_bf16 v[44:47], v[238:241], v[186:189], v[16:19]
	v_mfma_f32_16x16x32_bf16 v[16:19], v[190:193], v[206:209], v[28:31]
	v_mfma_f32_16x16x32_bf16 v[48:51], v[194:197], v[234:237], v[24:27]
	v_mfma_f32_16x16x32_bf16 v[24:27], v[198:201], v[218:221], v[146:149]
	v_mfma_f32_16x16x32_bf16 v[28:31], v[222:225], v[218:221], v[210:213]
	v_mfma_f32_16x16x32_bf16 v[40:43], v[222:225], v[182:185], v[40:43]
	v_mfma_f32_16x16x32_bf16 v[20:23], v[198:201], v[206:209], v[20:23]
	v_mfma_f32_16x16x32_bf16 v[52:55], v[202:205], v[234:237], v[24:27]
	v_mfma_f32_16x16x32_bf16 v[24:27], v[222:225], v[206:209], v[170:173]
	v_mfma_f32_16x16x32_bf16 v[56:59], v[226:229], v[234:237], v[28:31]
	v_mfma_f32_16x16x32_bf16 v[28:31], v[230:233], v[206:209], v[174:177]
	v_mfma_f32_16x16x32_bf16 v[60:63], v[230:233], v[218:221], v[178:181]
	v_mfma_f32_16x16x32_bf16 v[40:43], v[226:229], v[186:189], v[40:43]
	v_mfma_f32_16x16x32_bf16 v[16:19], v[194:197], v[214:217], v[16:19]
	v_mfma_f32_16x16x32_bf16 v[20:23], v[202:205], v[214:217], v[20:23]
	v_mfma_f32_16x16x32_bf16 v[24:27], v[226:229], v[214:217], v[24:27]
	v_mfma_f32_16x16x32_bf16 v[28:31], v[238:241], v[214:217], v[28:31]
	v_mfma_f32_16x16x32_bf16 v[60:63], v[238:241], v[234:237], v[60:63]
	s_setprio 0
	s_barrier
	s_and_saveexec_b64 s[60:61], s[6:7]
	s_cbranch_execz .LBB0_851
	s_barrier
